# LN second-batch params preloaded (no mid-phase drain); mlp2/out-proj epilogue stores plain, mlp1 nt
# speedup vs baseline: 1.1392x; 1.0119x over previous
; DI f32x16 zero16() { f32x16 z; for (int i = 0; i < 16; ++i) z[i] = 0.f; return z; }
; DI int opqv(int x) { asm volatile("" : "+v"(x)); return x; }
; DI char* opq(char* p) { asm volatile("" : "+s"(p)); return p; }
;   const int tid = opqv(threadIdx.x), lane = tid & 63, w = tid >> 6, wm = w >> 2, wn = w & 3, l32 = lane & 31, hf = lane >> 5;
;   f32x16 acc[2][2][2];
; #pragma unroll
;   for (int h = 0; h < 2; ++h)
; #pragma unroll
;     for (int i = 0; i < 2; ++i)
; #pragma unroll
;       for (int j = 0; j < 2; ++j) acc[h][i][j] = zero16();
;   const int nk = nk1 + nk2;
;   const int drow = lane >> 3, dslot = lane & 7, x7 = (l32 >> 1) & 7;
;     ...
;   if (V != 1) GLDS(0, 0);
; DI void glu_phase(const Params& p, int j, char* smem) {
;   const int tid = opqv(threadIdx.x), lane = tid & 63, w = tid >> 6, wm = w >> 2, wn = w & 3, l32 = lane & 31, hf = lane >> 5;
;   char* ws = opq(p.ws);
;   const u16* yt = (const u16*)(ws + OFF_YT);
;   const u16* Wt = (const u16*)(ws + OFF_W_GLU) + (size_t)j * 512 * LDGLU;
;   u16* o = (u16*)(ws + OFF_UO);
;   const float* gb = p.s5_glu_b + j * 512;
;   const int nN = 2;
;   for (int lt = blockIdx.x >> 3; lt < 16 * nN; lt += gridDim.x >> 3) {
;     int mt, nt; tile_map(lt, 16, nN, 16, 2, mt, nt);
;     const int m0 = mt * 256, n0 = nt * 256;
;     gemm_tile(yt + (size_t)m0 * LDYT, LDYT, 8, nullptr, 0, 0, Wt + (size_t)n0 * LDGLU, LDGLU, smem, [&](f32x16(&acc)[2][2], int moff) {
.LBB0_710:
	s_and_b64 vcc, exec, s[0:1]
	s_cbranch_vccz .LBB0_846
	v_readlane_b32 s0, v254, 24
	s_cmp_lt_i32 s0, 10
	s_mov_b64 s[0:1], -1
	s_cbranch_scc1 .LBB0_762
	v_readlane_b32 s0, v254, 24
	s_cmp_lt_i32 s0, 11
	s_mov_b64 s[0:1], -1
	s_cbranch_scc1 .LBB0_740
	v_readlane_b32 s0, v254, 24
	s_cmp_lg_u32 s0, 11
	s_mov_b64 s[0:1], -1
	s_cbranch_scc0 .LBB0_722
	v_readlane_b32 s4, v252, 7
	v_readlane_b32 s0, v251, 13
	v_readlane_b32 s5, v252, 8
	v_mov_b32_e32 v0, v182
	v_readlane_b32 s1, v251, 14
	s_andn2_b64 vcc, exec, s[4:5]
	s_cbranch_vccnz .LBB0_721
	v_readlane_b32 s68, v253, 62
	v_readlane_b32 s82, v254, 12
	v_readlane_b32 s83, v254, 13
	v_readlane_b32 s69, v253, 63
	v_readlane_b32 s70, v254, 0
	v_readlane_b32 s71, v254, 1
	v_readlane_b32 s72, v254, 2
	v_readlane_b32 s73, v254, 3
	v_readlane_b32 s74, v254, 4
	v_readlane_b32 s75, v254, 5
	v_readlane_b32 s76, v254, 6
	v_readlane_b32 s77, v254, 7
	v_readlane_b32 s78, v254, 8
	v_readlane_b32 s79, v254, 9
	v_readlane_b32 s80, v254, 10
	v_readlane_b32 s81, v254, 11
	v_readlane_b32 s28, v253, 48
	v_readlane_b32 s30, v253, 50
	s_cmp_ge_u32 s28, 0x20
	s_cbranch_scc1 .LBB0_721
	s_add_u32 s6, s0, 0x8c04100
	s_addc_u32 s7, s1, 0
	v_readlane_b32 s10, v254, 25
	v_readlane_b32 s5, v251, 0
	s_mul_i32 s8, s10, 0x90000
	s_add_u32 s8, s0, s8
	s_addc_u32 s9, s1, 0
	s_add_u32 s8, s8, 0x2824100
	s_addc_u32 s9, s9, 0
	s_lshl_b32 s10, s10, 11
	s_add_u32 s10, s82, s10
	s_addc_u32 s11, s83, 0
	s_and_b32 s5, s5, 7
	s_lshl_b32 s5, s5, 4
	v_lshrrev_b32_e32 v228, 6, v182
	v_and_b32_e32 v229, 63, v182
	v_readfirstlane_b32 s15, v228
	v_and_b32_e32 v230, 31, v229
	v_lshrrev_b32_e32 v231, 5, v229
	v_lshrrev_b32_e32 v232, 3, v229
	v_and_b32_e32 v233, 7, v229
	s_lshl_b32 s14, s15, 12
	s_add_u32 s14, s14, 32
	v_lshrrev_b32_e32 v234, 1, v232
	v_xor_b32_e32 v234, v233, v234
	v_lshlrev_b32_e32 v234, 4, v234
	s_lshl_b32 s12, s15, 2
	s_add_u32 s12, s12, 0
	s_lshl_b32 s12, s12, 3
	v_add_u32_e32 v235, s12, v232
	s_movk_i32 s13, 0x480
	v_mad_u32_u24 v220, v235, s13, v234
	v_lshrrev_b32_e32 v234, 1, v232
	v_add_u32_e32 v234, 4, v234
	v_xor_b32_e32 v234, v233, v234
	v_lshlrev_b32_e32 v234, 4, v234
	s_lshl_b32 s12, s15, 2
	s_add_u32 s12, s12, 1
	s_lshl_b32 s12, s12, 3
	v_add_u32_e32 v235, s12, v232
	s_movk_i32 s13, 0x480
	v_mad_u32_u24 v221, v235, s13, v234
	v_lshrrev_b32_e32 v234, 1, v232
	v_xor_b32_e32 v234, v233, v234
	v_lshlrev_b32_e32 v234, 4, v234
	s_lshl_b32 s12, s15, 2
	s_add_u32 s12, s12, 2
	s_lshl_b32 s12, s12, 3
	v_add_u32_e32 v235, s12, v232
	s_movk_i32 s13, 0x480
	v_mad_u32_u24 v222, v235, s13, v234
	v_lshrrev_b32_e32 v234, 1, v232
	v_add_u32_e32 v234, 4, v234
	v_xor_b32_e32 v234, v233, v234
	v_lshlrev_b32_e32 v234, 4, v234
	s_lshl_b32 s12, s15, 2
	s_add_u32 s12, s12, 3
	s_lshl_b32 s12, s12, 3
	v_add_u32_e32 v235, s12, v232
	s_movk_i32 s13, 0x480
	v_mad_u32_u24 v223, v235, s13, v234
	v_lshrrev_b32_e32 v236, 1, v230
	v_and_b32_e32 v236, 7, v236
	s_lshr_b32 s12, s15, 2
	s_and_b32 s13, s15, 3
	s_lshl_b32 s20, s12, 14
	s_add_u32 s20, s20, 32
	s_lshl_b32 s29, s13, 13
	s_add_u32 s29, s29, 0x8020
	v_lshlrev_b32_e32 v237, 7, v230
	v_add_u32_e32 v238, s29, v237
	v_add_u32_e32 v237, s20, v237
	v_add_u32_e32 v239, 0, v231
	v_xor_b32_e32 v239, v239, v236
	v_lshlrev_b32_e32 v239, 4, v239
	v_add_u32_e32 v204, v237, v239
	v_add_u32_e32 v212, v238, v239
	v_add_u32_e32 v208, 0x10000, v204
	v_add_u32_e32 v216, 0x10000, v212
	v_add_u32_e32 v239, 2, v231
	v_xor_b32_e32 v239, v239, v236
	v_lshlrev_b32_e32 v239, 4, v239
	v_add_u32_e32 v205, v237, v239
	v_add_u32_e32 v213, v238, v239
	v_add_u32_e32 v209, 0x10000, v205
	v_add_u32_e32 v217, 0x10000, v213
	v_add_u32_e32 v239, 4, v231
	v_xor_b32_e32 v239, v239, v236
	v_lshlrev_b32_e32 v239, 4, v239
	v_add_u32_e32 v206, v237, v239
	v_add_u32_e32 v214, v238, v239
	v_add_u32_e32 v210, 0x10000, v206
	v_add_u32_e32 v218, 0x10000, v214
	v_add_u32_e32 v239, 6, v231
	v_xor_b32_e32 v239, v239, v236
	v_lshlrev_b32_e32 v239, 4, v239
	v_add_u32_e32 v207, v237, v239
	v_add_u32_e32 v215, v238, v239
	v_add_u32_e32 v211, 0x10000, v207
	v_add_u32_e32 v219, 0x10000, v215
	s_add_u32 s20, s14, 0x18000
	v_lshlrev_b32_e32 v234, 7, v230
	v_lshlrev_b32_e32 v235, 3, v231
	v_add3_u32 v234, v234, v235, s20
	v_and_b32_e32 v235, 7, v230
	v_mov_b32_e32 v178, v235
	v_xor_b32_e32 v179, 1, v235
	v_xor_b32_e32 v180, 2, v235
	v_xor_b32_e32 v181, 3, v235
	v_xor_b32_e32 v188, 4, v235
	v_xor_b32_e32 v189, 5, v235
	v_xor_b32_e32 v190, 6, v235
	v_xor_b32_e32 v191, 7, v235
	v_lshl_add_u32 v178, v178, 4, v234
	v_lshl_add_u32 v179, v179, 4, v234
	v_lshl_add_u32 v180, v180, 4, v234
	v_lshl_add_u32 v181, v181, 4, v234
	v_lshl_add_u32 v188, v188, 4, v234
	v_lshl_add_u32 v189, v189, 4, v234
	v_lshl_add_u32 v190, v190, 4, v234
	v_lshl_add_u32 v191, v191, 4, v234
	v_xor_b32_e32 v194, v232, v233
	v_lshlrev_b32_e32 v194, 4, v194
	v_lshl_add_u32 v194, v232, 7, v194
	v_add_u32_e32 v194, s20, v194
	v_lshlrev_b32_e32 v195, 4, v233
	s_movk_i32 s20, 0x880
	v_mad_u32_u24 v195, v232, s20, v195
	v_lshlrev_b32_e32 v196, 4, v231
	v_lshlrev_b32_e32 v197, 3, v231
	s_movk_i32 s20, 0x480
	v_mad_u32_u24 v197, v230, s20, v197
	s_mov_b32 s27, s28
	s_mov_b32 s26, 0
	s_lshr_b32 s12, s27, 1
	s_add_u32 s12, s12, s5
	s_mul_i32 s12, s12, 0x48000
	s_add_u32 s22, s6, s12
	s_addc_u32 s23, s7, 0
	s_and_b32 s12, s27, 1
	s_mul_i32 s12, s12, 0x48000
	s_add_u32 s24, s8, s12
	s_addc_u32 s25, s9, 0
	s_add_u32 m0, s14, 0x0
	s_nop 0
	global_load_lds_dwordx4 v220, s[22:23]
	s_add_u32 m0, s14, 0x8000
	s_nop 0
	global_load_lds_dwordx4 v220, s[24:25]
	s_add_u32 m0, s14, 0x400
	s_nop 0
	global_load_lds_dwordx4 v221, s[22:23]
	s_add_u32 m0, s14, 0x8400
	s_nop 0
	global_load_lds_dwordx4 v221, s[24:25]
	s_add_u32 m0, s14, 0x800
	s_nop 0
	global_load_lds_dwordx4 v222, s[22:23]
	s_add_u32 m0, s14, 0x8800
	s_nop 0
	global_load_lds_dwordx4 v222, s[24:25]
	s_add_u32 m0, s14, 0xc00
	s_nop 0
	global_load_lds_dwordx4 v223, s[22:23]
	s_add_u32 m0, s14, 0x8c00
	s_nop 0
	global_load_lds_dwordx4 v223, s[24:25]
	s_add_u32 s22, s22, 0x80
	s_addc_u32 s23, s23, 0
	s_add_u32 s24, s24, 0x80
	s_addc_u32 s25, s25, 0
	s_add_u32 s26, s26, 1
	s_cmp_eq_u32 s26, 8
	s_cbranch_scc0 .Lgl1_cadv_done
	s_mov_b32 s26, 0
	s_add_u32 s27, s27, s30
	s_cmp_lt_u32 s27, 0x20
	s_cbranch_scc1 .Lgl1_cadv_new
	s_sub_u32 s22, s22, 0x400
	s_subb_u32 s23, s23, 0
	s_sub_u32 s24, s24, 0x400
	s_subb_u32 s25, s25, 0
	s_branch .Lgl1_cadv_done
;     ...
;   for (int kt = 0; kt < nk; kt += 2) {
;     if (V != 1) GLDS(kt + 1, 1);
.Lgl1_cadv_new:
	s_lshr_b32 s12, s27, 1
	s_add_u32 s12, s12, s5
	s_mul_i32 s12, s12, 0x48000
	s_add_u32 s22, s6, s12
	s_addc_u32 s23, s7, 0
	s_and_b32 s12, s27, 1
	s_mul_i32 s12, s12, 0x48000
	s_add_u32 s24, s8, s12
	s_addc_u32 s25, s9, 0
.Lgl1_cadv_done:
	s_add_u32 m0, s14, 0x10000
	s_nop 0
	global_load_lds_dwordx4 v220, s[22:23]
	s_add_u32 m0, s14, 0x18000
	s_nop 0
	global_load_lds_dwordx4 v220, s[24:25]
	s_add_u32 m0, s14, 0x10400
	s_nop 0
	global_load_lds_dwordx4 v221, s[22:23]
	s_add_u32 m0, s14, 0x18400
	s_nop 0
	global_load_lds_dwordx4 v221, s[24:25]
	s_add_u32 m0, s14, 0x10800
	s_nop 0
	global_load_lds_dwordx4 v222, s[22:23]
	s_add_u32 m0, s14, 0x18800
	s_nop 0
	global_load_lds_dwordx4 v222, s[24:25]
	s_add_u32 m0, s14, 0x10c00
	s_nop 0
	global_load_lds_dwordx4 v223, s[22:23]
	s_add_u32 m0, s14, 0x18c00
	s_nop 0
	global_load_lds_dwordx4 v223, s[24:25]
	s_add_u32 s22, s22, 0x80
	s_addc_u32 s23, s23, 0
	s_add_u32 s24, s24, 0x80
	s_addc_u32 s25, s25, 0
	s_add_u32 s26, s26, 1
	s_cmp_eq_u32 s26, 8
	s_cbranch_scc0 .Lgl2_cadv_done
	s_mov_b32 s26, 0
	s_add_u32 s27, s27, s30
	s_cmp_lt_u32 s27, 0x20
	s_cbranch_scc1 .Lgl2_cadv_new
	s_sub_u32 s22, s22, 0x400
	s_subb_u32 s23, s23, 0
	s_sub_u32 s24, s24, 0x400
	s_subb_u32 s25, s25, 0
	s_branch .Lgl2_cadv_done

; #define RAWBAR() { asm volatile("s_waitcnt vmcnt(0) lgkmcnt(0)" ::: "memory"); __builtin_amdgcn_s_barrier(); }
;     ...
;   if (V != 1) GLDS(0, 0);
;   RAWBAR();
;   for (int kt = 0; kt < nk; kt += 2) {
;     if (V != 1) GLDS(kt + 1, 1);
;     if (V != 2) COMPUTE(0);
;     RAWBAR();
;     if (V != 1) if (kt + 2 < nk) GLDS(kt + 2, 0);
;     if (V != 2) COMPUTE(1);
;     RAWBAR();
.Lgl_tile:
	s_waitcnt lgkmcnt(6)
	v_mfma_f32_32x32x16_bf16 v[0:15], v[162:165], v[128:131], 0
	v_mfma_f32_32x32x16_bf16 v[16:31], v[166:169], v[128:131], 0
	ds_read_b128 v[128:131], v206
	v_mfma_f32_32x32x16_bf16 v[32:47], v[162:165], v[132:135], 0
	v_mfma_f32_32x32x16_bf16 v[48:63], v[166:169], v[132:135], 0
	ds_read_b128 v[132:135], v206 offset:4096
	v_mfma_f32_32x32x16_bf16 v[64:79], v[162:165], v[136:139], 0
	v_mfma_f32_32x32x16_bf16 v[80:95], v[166:169], v[136:139], 0
	ds_read_b128 v[136:139], v206 offset:8192
	v_mfma_f32_32x32x16_bf16 v[96:111], v[162:165], v[140:143], 0
	v_mfma_f32_32x32x16_bf16 v[112:127], v[166:169], v[140:143], 0
	ds_read_b128 v[140:143], v206 offset:12288
	ds_read_b128 v[162:165], v214
	ds_read_b128 v[166:169], v214 offset:4096
	s_waitcnt lgkmcnt(6)
	v_mfma_f32_32x32x16_bf16 v[0:15], v[170:173], v[144:147], v[0:15]
	v_mfma_f32_32x32x16_bf16 v[16:31], v[174:177], v[144:147], v[16:31]
	ds_read_b128 v[144:147], v207
	v_mfma_f32_32x32x16_bf16 v[32:47], v[170:173], v[148:151], v[32:47]
	v_mfma_f32_32x32x16_bf16 v[48:63], v[174:177], v[148:151], v[48:63]
	ds_read_b128 v[148:151], v207 offset:4096
	v_mfma_f32_32x32x16_bf16 v[64:79], v[170:173], v[152:155], v[64:79]
	v_mfma_f32_32x32x16_bf16 v[80:95], v[174:177], v[152:155], v[80:95]
	ds_read_b128 v[152:155], v207 offset:8192
	v_mfma_f32_32x32x16_bf16 v[96:111], v[170:173], v[156:159], v[96:111]
	v_mfma_f32_32x32x16_bf16 v[112:127], v[174:177], v[156:159], v[112:127]
	ds_read_b128 v[156:159], v207 offset:12288
	ds_read_b128 v[170:173], v215
	ds_read_b128 v[174:177], v215 offset:4096
	s_waitcnt vmcnt(0) lgkmcnt(0)
	s_barrier
	s_add_u32 m0, s14, 0x0
	v_mfma_f32_32x32x16_bf16 v[0:15], v[162:165], v[128:131], v[0:15]
	global_load_lds_dwordx4 v220, s[22:23]
	s_add_u32 m0, s14, 0x8000
	v_mfma_f32_32x32x16_bf16 v[16:31], v[166:169], v[128:131], v[16:31]
	global_load_lds_dwordx4 v220, s[24:25]
	ds_read_b128 v[128:131], v208
	s_add_u32 m0, s14, 0x400
	v_mfma_f32_32x32x16_bf16 v[32:47], v[162:165], v[132:135], v[32:47]
	global_load_lds_dwordx4 v221, s[22:23]
	s_add_u32 m0, s14, 0x8400
	v_mfma_f32_32x32x16_bf16 v[48:63], v[166:169], v[132:135], v[48:63]
	global_load_lds_dwordx4 v221, s[24:25]
	ds_read_b128 v[132:135], v208 offset:4096
	s_add_u32 m0, s14, 0x800
	v_mfma_f32_32x32x16_bf16 v[64:79], v[162:165], v[136:139], v[64:79]
	global_load_lds_dwordx4 v222, s[22:23]
	s_add_u32 m0, s14, 0x8800
	v_mfma_f32_32x32x16_bf16 v[80:95], v[166:169], v[136:139], v[80:95]
	global_load_lds_dwordx4 v222, s[24:25]
	ds_read_b128 v[136:139], v208 offset:8192
	s_add_u32 m0, s14, 0xc00
	v_mfma_f32_32x32x16_bf16 v[96:111], v[162:165], v[140:143], v[96:111]
	global_load_lds_dwordx4 v223, s[22:23]
	s_add_u32 m0, s14, 0x8c00
	v_mfma_f32_32x32x16_bf16 v[112:127], v[166:169], v[140:143], v[112:127]
	global_load_lds_dwordx4 v223, s[24:25]
	ds_read_b128 v[140:143], v208 offset:12288
	ds_read_b128 v[162:165], v216
	ds_read_b128 v[166:169], v216 offset:4096
	v_mfma_f32_32x32x16_bf16 v[0:15], v[170:173], v[144:147], v[0:15]
	v_mfma_f32_32x32x16_bf16 v[16:31], v[174:177], v[144:147], v[16:31]
	ds_read_b128 v[144:147], v209
	v_mfma_f32_32x32x16_bf16 v[32:47], v[170:173], v[148:151], v[32:47]
	v_mfma_f32_32x32x16_bf16 v[48:63], v[174:177], v[148:151], v[48:63]
	ds_read_b128 v[148:151], v209 offset:4096
	v_mfma_f32_32x32x16_bf16 v[64:79], v[170:173], v[152:155], v[64:79]
	v_mfma_f32_32x32x16_bf16 v[80:95], v[174:177], v[152:155], v[80:95]
	ds_read_b128 v[152:155], v209 offset:8192
	v_mfma_f32_32x32x16_bf16 v[96:111], v[170:173], v[156:159], v[96:111]
	v_mfma_f32_32x32x16_bf16 v[112:127], v[174:177], v[156:159], v[112:127]
	ds_read_b128 v[156:159], v209 offset:12288
	ds_read_b128 v[170:173], v217
	ds_read_b128 v[174:177], v217 offset:4096
	s_add_u32 s22, s22, 0x80
	s_addc_u32 s23, s23, 0
	s_add_u32 s24, s24, 0x80
	s_addc_u32 s25, s25, 0
	s_add_u32 s26, s26, 1
	s_cmp_eq_u32 s26, 8
	s_cbranch_scc0 .Lgl3_cadv_done
	s_mov_b32 s26, 0
	s_add_u32 s27, s27, s30
	s_cmp_lt_u32 s27, 0x20
	s_cbranch_scc1 .Lgl3_cadv_new
	s_sub_u32 s22, s22, 0x400
	s_subb_u32 s23, s23, 0
	s_sub_u32 s24, s24, 0x400
	s_subb_u32 s25, s25, 0
	s_branch .Lgl3_cadv_done

; #define RAWBAR() { asm volatile("s_waitcnt vmcnt(0) lgkmcnt(0)" ::: "memory"); __builtin_amdgcn_s_barrier(); }
;     ...
;   if (V != 1) GLDS(0, 0);
;   RAWBAR();
;   for (int kt = 0; kt < nk; kt += 2) {
;     if (V != 1) GLDS(kt + 1, 1);
;     if (V != 2) COMPUTE(0);
;     RAWBAR();
;     if (V != 1) if (kt + 2 < nk) GLDS(kt + 2, 0);
;     if (V != 2) COMPUTE(1);
;     RAWBAR();
.Lgl3_cadv_done:
	s_waitcnt lgkmcnt(6)
	v_mfma_f32_32x32x16_bf16 v[0:15], v[162:165], v[128:131], v[0:15]
	v_mfma_f32_32x32x16_bf16 v[16:31], v[166:169], v[128:131], v[16:31]
	ds_read_b128 v[128:131], v210
	v_mfma_f32_32x32x16_bf16 v[32:47], v[162:165], v[132:135], v[32:47]
	v_mfma_f32_32x32x16_bf16 v[48:63], v[166:169], v[132:135], v[48:63]
	ds_read_b128 v[132:135], v210 offset:4096
	v_mfma_f32_32x32x16_bf16 v[64:79], v[162:165], v[136:139], v[64:79]
	v_mfma_f32_32x32x16_bf16 v[80:95], v[166:169], v[136:139], v[80:95]
	ds_read_b128 v[136:139], v210 offset:8192
	v_mfma_f32_32x32x16_bf16 v[96:111], v[162:165], v[140:143], v[96:111]
	v_mfma_f32_32x32x16_bf16 v[112:127], v[166:169], v[140:143], v[112:127]
	ds_read_b128 v[140:143], v210 offset:12288
	ds_read_b128 v[162:165], v218
	ds_read_b128 v[166:169], v218 offset:4096
	s_waitcnt lgkmcnt(6)
	v_mfma_f32_32x32x16_bf16 v[0:15], v[170:173], v[144:147], v[0:15]
	v_mfma_f32_32x32x16_bf16 v[16:31], v[174:177], v[144:147], v[16:31]
	ds_read_b128 v[144:147], v211
	v_mfma_f32_32x32x16_bf16 v[32:47], v[170:173], v[148:151], v[32:47]
	v_mfma_f32_32x32x16_bf16 v[48:63], v[174:177], v[148:151], v[48:63]
	ds_read_b128 v[148:151], v211 offset:4096
	v_mfma_f32_32x32x16_bf16 v[64:79], v[170:173], v[152:155], v[64:79]
	v_mfma_f32_32x32x16_bf16 v[80:95], v[174:177], v[152:155], v[80:95]
	ds_read_b128 v[152:155], v211 offset:8192
	v_mfma_f32_32x32x16_bf16 v[96:111], v[170:173], v[156:159], v[96:111]
	v_mfma_f32_32x32x16_bf16 v[112:127], v[174:177], v[156:159], v[112:127]
	ds_read_b128 v[156:159], v211 offset:12288
	ds_read_b128 v[170:173], v219
	ds_read_b128 v[174:177], v219 offset:4096
	s_waitcnt vmcnt(0) lgkmcnt(0)
	s_barrier
	s_add_u32 m0, s14, 0x10000
	v_mfma_f32_32x32x16_bf16 v[0:15], v[162:165], v[128:131], v[0:15]
	global_load_lds_dwordx4 v220, s[22:23]
	s_add_u32 m0, s14, 0x18000
	v_mfma_f32_32x32x16_bf16 v[16:31], v[166:169], v[128:131], v[16:31]
	global_load_lds_dwordx4 v220, s[24:25]
	ds_read_b128 v[128:131], v204
	s_add_u32 m0, s14, 0x10400
	v_mfma_f32_32x32x16_bf16 v[32:47], v[162:165], v[132:135], v[32:47]
	global_load_lds_dwordx4 v221, s[22:23]
	s_add_u32 m0, s14, 0x18400
	v_mfma_f32_32x32x16_bf16 v[48:63], v[166:169], v[132:135], v[48:63]
	global_load_lds_dwordx4 v221, s[24:25]
	ds_read_b128 v[132:135], v204 offset:4096
	s_add_u32 m0, s14, 0x10800
	v_mfma_f32_32x32x16_bf16 v[64:79], v[162:165], v[136:139], v[64:79]
	global_load_lds_dwordx4 v222, s[22:23]
	s_add_u32 m0, s14, 0x18800
	v_mfma_f32_32x32x16_bf16 v[80:95], v[166:169], v[136:139], v[80:95]
	global_load_lds_dwordx4 v222, s[24:25]
	ds_read_b128 v[136:139], v204 offset:8192
	s_add_u32 m0, s14, 0x10c00
	v_mfma_f32_32x32x16_bf16 v[96:111], v[162:165], v[140:143], v[96:111]
	global_load_lds_dwordx4 v223, s[22:23]
	s_add_u32 m0, s14, 0x18c00
	v_mfma_f32_32x32x16_bf16 v[112:127], v[166:169], v[140:143], v[112:127]
	global_load_lds_dwordx4 v223, s[24:25]
	ds_read_b128 v[140:143], v204 offset:12288
	ds_read_b128 v[162:165], v212
	ds_read_b128 v[166:169], v212 offset:4096
	v_mfma_f32_32x32x16_bf16 v[0:15], v[170:173], v[144:147], v[0:15]
	v_mfma_f32_32x32x16_bf16 v[16:31], v[174:177], v[144:147], v[16:31]
	ds_read_b128 v[144:147], v205
	v_mfma_f32_32x32x16_bf16 v[32:47], v[170:173], v[148:151], v[32:47]
	v_mfma_f32_32x32x16_bf16 v[48:63], v[174:177], v[148:151], v[48:63]
	ds_read_b128 v[148:151], v205 offset:4096
	v_mfma_f32_32x32x16_bf16 v[64:79], v[170:173], v[152:155], v[64:79]
	v_mfma_f32_32x32x16_bf16 v[80:95], v[174:177], v[152:155], v[80:95]
	ds_read_b128 v[152:155], v205 offset:8192
	v_mfma_f32_32x32x16_bf16 v[96:111], v[170:173], v[156:159], v[96:111]
	v_mfma_f32_32x32x16_bf16 v[112:127], v[174:177], v[156:159], v[112:127]
	ds_read_b128 v[156:159], v205 offset:12288
	ds_read_b128 v[170:173], v213
	ds_read_b128 v[174:177], v213 offset:4096
	s_add_u32 s22, s22, 0x80
	s_addc_u32 s23, s23, 0
	s_add_u32 s24, s24, 0x80
	s_addc_u32 s25, s25, 0
	s_add_u32 s26, s26, 1
	s_cmp_eq_u32 s26, 8
	s_cbranch_scc0 .Lgl4_cadv_done
	s_mov_b32 s26, 0
	s_add_u32 s27, s27, s30
	s_cmp_lt_u32 s27, 0x20
	s_cbranch_scc1 .Lgl4_cadv_new
	s_sub_u32 s22, s22, 0x400
	s_subb_u32 s23, s23, 0
	s_sub_u32 s24, s24, 0x400
	s_subb_u32 s25, s25, 0
	s_branch .Lgl4_cadv_done

; #define RAWBAR() { asm volatile("s_waitcnt vmcnt(0) lgkmcnt(0)" ::: "memory"); __builtin_amdgcn_s_barrier(); }
;     ...
;   if (V != 1) GLDS(0, 0);
;   RAWBAR();
;   for (int kt = 0; kt < nk; kt += 2) {
;     if (V != 1) GLDS(kt + 1, 1);
;     if (V != 2) COMPUTE(0);
;     RAWBAR();
;     if (V != 1) if (kt + 2 < nk) GLDS(kt + 2, 0);
;     if (V != 2) COMPUTE(1);
;     RAWBAR();
.Lgl4_cadv_done:
	s_mov_b32 s31, 2
	s_cmp_eq_u32 s31, 0
	s_cbranch_scc1 .Lgl_pairs_done
.Lgl_pair:
	s_waitcnt lgkmcnt(6)
	v_mfma_f32_32x32x16_bf16 v[0:15], v[162:165], v[128:131], v[0:15]
	v_mfma_f32_32x32x16_bf16 v[16:31], v[166:169], v[128:131], v[16:31]
	ds_read_b128 v[128:131], v206
	v_mfma_f32_32x32x16_bf16 v[32:47], v[162:165], v[132:135], v[32:47]
	v_mfma_f32_32x32x16_bf16 v[48:63], v[166:169], v[132:135], v[48:63]
	ds_read_b128 v[132:135], v206 offset:4096
	v_mfma_f32_32x32x16_bf16 v[64:79], v[162:165], v[136:139], v[64:79]
	v_mfma_f32_32x32x16_bf16 v[80:95], v[166:169], v[136:139], v[80:95]
	ds_read_b128 v[136:139], v206 offset:8192
	v_mfma_f32_32x32x16_bf16 v[96:111], v[162:165], v[140:143], v[96:111]
	v_mfma_f32_32x32x16_bf16 v[112:127], v[166:169], v[140:143], v[112:127]
	ds_read_b128 v[140:143], v206 offset:12288
	ds_read_b128 v[162:165], v214
	ds_read_b128 v[166:169], v214 offset:4096
	s_waitcnt lgkmcnt(6)
	v_mfma_f32_32x32x16_bf16 v[0:15], v[170:173], v[144:147], v[0:15]
	v_mfma_f32_32x32x16_bf16 v[16:31], v[174:177], v[144:147], v[16:31]
	ds_read_b128 v[144:147], v207
	v_mfma_f32_32x32x16_bf16 v[32:47], v[170:173], v[148:151], v[32:47]
	v_mfma_f32_32x32x16_bf16 v[48:63], v[174:177], v[148:151], v[48:63]
	ds_read_b128 v[148:151], v207 offset:4096
	v_mfma_f32_32x32x16_bf16 v[64:79], v[170:173], v[152:155], v[64:79]
	v_mfma_f32_32x32x16_bf16 v[80:95], v[174:177], v[152:155], v[80:95]
	ds_read_b128 v[152:155], v207 offset:8192
	v_mfma_f32_32x32x16_bf16 v[96:111], v[170:173], v[156:159], v[96:111]
	v_mfma_f32_32x32x16_bf16 v[112:127], v[174:177], v[156:159], v[112:127]
	ds_read_b128 v[156:159], v207 offset:12288
	ds_read_b128 v[170:173], v215
	ds_read_b128 v[174:177], v215 offset:4096
	s_waitcnt vmcnt(0) lgkmcnt(0)
	s_barrier
	s_add_u32 m0, s14, 0x0
	v_mfma_f32_32x32x16_bf16 v[0:15], v[162:165], v[128:131], v[0:15]
	global_load_lds_dwordx4 v220, s[22:23]
	s_add_u32 m0, s14, 0x8000
	v_mfma_f32_32x32x16_bf16 v[16:31], v[166:169], v[128:131], v[16:31]
	global_load_lds_dwordx4 v220, s[24:25]
	ds_read_b128 v[128:131], v208
	s_add_u32 m0, s14, 0x400
	v_mfma_f32_32x32x16_bf16 v[32:47], v[162:165], v[132:135], v[32:47]
	global_load_lds_dwordx4 v221, s[22:23]
	s_add_u32 m0, s14, 0x8400
	v_mfma_f32_32x32x16_bf16 v[48:63], v[166:169], v[132:135], v[48:63]
	global_load_lds_dwordx4 v221, s[24:25]
	ds_read_b128 v[132:135], v208 offset:4096
	s_add_u32 m0, s14, 0x800
	v_mfma_f32_32x32x16_bf16 v[64:79], v[162:165], v[136:139], v[64:79]
	global_load_lds_dwordx4 v222, s[22:23]
	s_add_u32 m0, s14, 0x8800
	v_mfma_f32_32x32x16_bf16 v[80:95], v[166:169], v[136:139], v[80:95]
	global_load_lds_dwordx4 v222, s[24:25]
	ds_read_b128 v[136:139], v208 offset:8192
	s_add_u32 m0, s14, 0xc00
	v_mfma_f32_32x32x16_bf16 v[96:111], v[162:165], v[140:143], v[96:111]
	global_load_lds_dwordx4 v223, s[22:23]
	s_add_u32 m0, s14, 0x8c00
	v_mfma_f32_32x32x16_bf16 v[112:127], v[166:169], v[140:143], v[112:127]
	global_load_lds_dwordx4 v223, s[24:25]
	ds_read_b128 v[140:143], v208 offset:12288
	ds_read_b128 v[162:165], v216
	ds_read_b128 v[166:169], v216 offset:4096
	v_mfma_f32_32x32x16_bf16 v[0:15], v[170:173], v[144:147], v[0:15]
	v_mfma_f32_32x32x16_bf16 v[16:31], v[174:177], v[144:147], v[16:31]
	ds_read_b128 v[144:147], v209
	v_mfma_f32_32x32x16_bf16 v[32:47], v[170:173], v[148:151], v[32:47]
	v_mfma_f32_32x32x16_bf16 v[48:63], v[174:177], v[148:151], v[48:63]
	ds_read_b128 v[148:151], v209 offset:4096
	v_mfma_f32_32x32x16_bf16 v[64:79], v[170:173], v[152:155], v[64:79]
	v_mfma_f32_32x32x16_bf16 v[80:95], v[174:177], v[152:155], v[80:95]
	ds_read_b128 v[152:155], v209 offset:8192
	v_mfma_f32_32x32x16_bf16 v[96:111], v[170:173], v[156:159], v[96:111]
	v_mfma_f32_32x32x16_bf16 v[112:127], v[174:177], v[156:159], v[112:127]
	ds_read_b128 v[156:159], v209 offset:12288
	ds_read_b128 v[170:173], v217
	ds_read_b128 v[174:177], v217 offset:4096
	s_add_u32 s22, s22, 0x80
	s_addc_u32 s23, s23, 0
	s_add_u32 s24, s24, 0x80
	s_addc_u32 s25, s25, 0
	s_add_u32 s26, s26, 1
	s_cmp_eq_u32 s26, 8
	s_cbranch_scc0 .Lgl5_cadv_done
	s_mov_b32 s26, 0
	s_add_u32 s27, s27, s30
	s_cmp_lt_u32 s27, 0x20
	s_cbranch_scc1 .Lgl5_cadv_new
	s_sub_u32 s22, s22, 0x400
	s_subb_u32 s23, s23, 0
	s_sub_u32 s24, s24, 0x400
	s_subb_u32 s25, s25, 0
	s_branch .Lgl5_cadv_done

; #define RAWBAR() { asm volatile("s_waitcnt vmcnt(0) lgkmcnt(0)" ::: "memory"); __builtin_amdgcn_s_barrier(); }
;     ...
;   for (int kt = 0; kt < nk; kt += 2) {
;     if (V != 1) GLDS(kt + 1, 1);
;     if (V != 2) COMPUTE(0);
;     RAWBAR();
;     if (V != 1) if (kt + 2 < nk) GLDS(kt + 2, 0);
;     if (V != 2) COMPUTE(1);
;     RAWBAR();
;   }
.Lgl6_cadv_done:
	s_sub_u32 s31, s31, 1
	s_cmp_lg_u32 s31, 0
	s_cbranch_scc1 .Lgl_pair

; DI float bf2f(unsigned h) { return __uint_as_float(h << 16); }
; DI int crow(int r, int hf) { return (r & 3) + 8 * (r >> 2) + 4 * hf; }
; #define RAWBAR() { asm volatile("s_waitcnt vmcnt(0) lgkmcnt(0)" ::: "memory"); __builtin_amdgcn_s_barrier(); }
;     ...
;   for (int kt = 0; kt < nk; kt += 2) {
;     if (V != 1) GLDS(kt + 1, 1);
;     if (V != 2) COMPUTE(0);
;     RAWBAR();
;     if (V != 1) if (kt + 2 < nk) GLDS(kt + 2, 0);
;     if (V != 2) COMPUTE(1);
;     RAWBAR();
;   }
; DI void glu_phase(const Params& p, int j, char* smem) {
;     ...
; #pragma unroll
;       for (int i = 0; i < 2; ++i)
; #pragma unroll
;         for (int jn = 0; jn < 2; ++jn)
; #pragma unroll
;           for (int r = 0; r < 16; ++r) {
;             const int row = m0_ + wm * 64 + i * 32 + crow(r, hf_), col = n0 + wn * 64 + jn * 32 + l32_;
;             const float gt = acc[i][jn][r] + gb[col];
;             const float y = bf2f(yt[(size_t)row * LDYT + col]);
;             o[(size_t)row * LDH + 512 + col] = f2bf(y / (1.f + __expf(-gt)));
.Lgl7_cadv_done:
	s_waitcnt lgkmcnt(6)
	v_mfma_f32_32x32x16_bf16 v[0:15], v[162:165], v[128:131], v[0:15]
	v_mfma_f32_32x32x16_bf16 v[16:31], v[166:169], v[128:131], v[16:31]
	ds_read_b128 v[128:131], v210
	v_mfma_f32_32x32x16_bf16 v[32:47], v[162:165], v[132:135], v[32:47]
	v_mfma_f32_32x32x16_bf16 v[48:63], v[166:169], v[132:135], v[48:63]
	ds_read_b128 v[132:135], v210 offset:4096
	v_mfma_f32_32x32x16_bf16 v[64:79], v[162:165], v[136:139], v[64:79]
	v_mfma_f32_32x32x16_bf16 v[80:95], v[166:169], v[136:139], v[80:95]
	ds_read_b128 v[136:139], v210 offset:8192
	v_mfma_f32_32x32x16_bf16 v[96:111], v[162:165], v[140:143], v[96:111]
	v_mfma_f32_32x32x16_bf16 v[112:127], v[166:169], v[140:143], v[112:127]
	ds_read_b128 v[140:143], v210 offset:12288
	ds_read_b128 v[162:165], v218
	ds_read_b128 v[166:169], v218 offset:4096
	s_waitcnt lgkmcnt(6)
	v_mfma_f32_32x32x16_bf16 v[0:15], v[170:173], v[144:147], v[0:15]
	v_mfma_f32_32x32x16_bf16 v[16:31], v[174:177], v[144:147], v[16:31]
	ds_read_b128 v[144:147], v211
	v_mfma_f32_32x32x16_bf16 v[32:47], v[170:173], v[148:151], v[32:47]
	v_mfma_f32_32x32x16_bf16 v[48:63], v[174:177], v[148:151], v[48:63]
	ds_read_b128 v[148:151], v211 offset:4096
	v_mfma_f32_32x32x16_bf16 v[64:79], v[170:173], v[152:155], v[64:79]
	v_mfma_f32_32x32x16_bf16 v[80:95], v[174:177], v[152:155], v[80:95]
	ds_read_b128 v[152:155], v211 offset:8192
	v_mfma_f32_32x32x16_bf16 v[96:111], v[170:173], v[156:159], v[96:111]
	v_mfma_f32_32x32x16_bf16 v[112:127], v[174:177], v[156:159], v[112:127]
	ds_read_b128 v[156:159], v211 offset:12288
	ds_read_b128 v[170:173], v219
	ds_read_b128 v[174:177], v219 offset:4096
	s_waitcnt vmcnt(0) lgkmcnt(0)
	s_barrier
	s_add_u32 m0, s14, 0x10000
	v_mfma_f32_32x32x16_bf16 v[0:15], v[162:165], v[128:131], v[0:15]
	global_load_lds_dwordx4 v220, s[22:23]
	s_add_u32 m0, s14, 0x10400
	v_mfma_f32_32x32x16_bf16 v[16:31], v[166:169], v[128:131], v[16:31]
	global_load_lds_dwordx4 v221, s[22:23]
	s_add_u32 m0, s14, 0x10800
	v_mfma_f32_32x32x16_bf16 v[32:47], v[162:165], v[132:135], v[32:47]
	global_load_lds_dwordx4 v222, s[22:23]
	s_add_u32 m0, s14, 0x10c00
	v_mfma_f32_32x32x16_bf16 v[48:63], v[166:169], v[132:135], v[48:63]
	global_load_lds_dwordx4 v223, s[22:23]
	v_mfma_f32_32x32x16_bf16 v[64:79], v[162:165], v[136:139], v[64:79]
	v_mfma_f32_32x32x16_bf16 v[80:95], v[166:169], v[136:139], v[80:95]
	v_mfma_f32_32x32x16_bf16 v[96:111], v[162:165], v[140:143], v[96:111]
	v_mfma_f32_32x32x16_bf16 v[112:127], v[166:169], v[140:143], v[112:127]
	v_mfma_f32_32x32x16_bf16 v[0:15], v[170:173], v[144:147], v[0:15]
	v_mfma_f32_32x32x16_bf16 v[16:31], v[174:177], v[144:147], v[16:31]
	v_mfma_f32_32x32x16_bf16 v[32:47], v[170:173], v[148:151], v[32:47]
	v_mfma_f32_32x32x16_bf16 v[48:63], v[174:177], v[148:151], v[48:63]
	v_mfma_f32_32x32x16_bf16 v[64:79], v[170:173], v[152:155], v[64:79]
	v_mfma_f32_32x32x16_bf16 v[80:95], v[174:177], v[152:155], v[80:95]
	v_mfma_f32_32x32x16_bf16 v[96:111], v[170:173], v[156:159], v[96:111]
	v_mfma_f32_32x32x16_bf16 v[112:127], v[174:177], v[156:159], v[112:127]
	s_lshr_b32 s12, s15, 2
	s_and_b32 s13, s15, 3
	s_lshr_b32 s20, s28, 1
	s_add_u32 s20, s20, s5
	s_lshl_b32 s20, s20, 8
	s_lshl_b32 s12, s12, 7
	s_add_u32 s20, s20, s12
	s_and_b32 s29, s28, 1
	s_lshl_b32 s29, s29, 8
	s_lshl_b32 s13, s13, 6
	s_add_u32 s29, s29, s13
	s_lshl_b32 s12, s29, 2
	s_add_u32 s12, s10, s12
	s_addc_u32 s13, s11, 0
	global_load_dwordx4 v[128:131], v196, s[12:13]
	global_load_dwordx4 v[132:135], v196, s[12:13] offset:32
	global_load_dwordx4 v[136:139], v196, s[12:13] offset:64
	global_load_dwordx4 v[140:143], v196, s[12:13] offset:96
	global_load_dwordx4 v[144:147], v196, s[12:13] offset:128
	global_load_dwordx4 v[148:151], v196, s[12:13] offset:160
	global_load_dwordx4 v[152:155], v196, s[12:13] offset:192
	global_load_dwordx4 v[156:159], v196, s[12:13] offset:224
	s_mul_i32 s12, s20, 0x480
	s_lshl_b32 s13, s29, 1
	s_add_u32 s12, s12, s13
	s_add_u32 s12, s6, s12
	s_addc_u32 s13, s7, 0
	s_mul_i32 s100, s20, 0x880
	s_lshl_b32 s101, s29, 1
	s_add_u32 s100, s100, s101
	s_add_u32 s100, s0, s100
	s_addc_u32 s101, s1, 0
	s_add_u32 s100, s100, 0x17404500
	s_addc_u32 s101, s101, 0
	global_load_dwordx2 v[162:163], v197, s[12:13]
	global_load_dwordx2 v[164:165], v197, s[12:13] offset:16
	global_load_dwordx2 v[166:167], v197, s[12:13] offset:32
	global_load_dwordx2 v[168:169], v197, s[12:13] offset:48
	global_load_dwordx2 v[170:171], v197, s[12:13] offset:64
	global_load_dwordx2 v[172:173], v197, s[12:13] offset:80
	global_load_dwordx2 v[174:175], v197, s[12:13] offset:96
	global_load_dwordx2 v[176:177], v197, s[12:13] offset:112
	s_add_u32 s12, s12, 0x9000
	s_addc_u32 s13, s13, 0
	global_load_dwordx2 v[224:225], v197, s[12:13]
	global_load_dwordx2 v[226:227], v197, s[12:13] offset:16
	global_load_dwordx2 v[228:229], v197, s[12:13] offset:32
	global_load_dwordx2 v[230:231], v197, s[12:13] offset:48
	global_load_dwordx2 v[232:233], v197, s[12:13] offset:64
	global_load_dwordx2 v[234:235], v197, s[12:13] offset:80
	global_load_dwordx2 v[236:237], v197, s[12:13] offset:96
	global_load_dwordx2 v[238:239], v197, s[12:13] offset:112
	s_add_u32 s12, s12, 0x9000
	s_addc_u32 s13, s13, 0
	s_waitcnt vmcnt(8)
; DI float bf2f(unsigned h) { return __uint_as_float(h << 16); }
; DI int crow(int r, int hf) { return (r & 3) + 8 * (r >> 2) + 4 * hf; }
; DI void glu_phase(const Params& p, int j, char* smem) {
;     ...
; #pragma unroll
;       for (int i = 0; i < 2; ++i)
; #pragma unroll
;         for (int jn = 0; jn < 2; ++jn)
; #pragma unroll
;           for (int r = 0; r < 16; ++r) {
;             const int row = m0_ + wm * 64 + i * 32 + crow(r, hf_), col = n0 + wn * 64 + jn * 32 + l32_;
;             const float gt = acc[i][jn][r] + gb[col];
;             const float y = bf2f(yt[(size_t)row * LDYT + col]);
;             o[(size_t)row * LDH + 512 + col] = f2bf(y / (1.f + __expf(-gt)));
	v_add_f32_e32 v0, v0, v128
	v_mul_f32_e32 v0, 0xbfb8aa3b, v0
	v_exp_f32_e32 v0, v0
	s_nop 0
	v_add_f32_e32 v0, 1.0, v0
	v_rcp_f32_e32 v0, v0
	v_lshlrev_b32_e32 v246, 16, v162
	v_mul_f32_e32 v0, v246, v0
	v_add_f32_e32 v1, v1, v129
	v_mul_f32_e32 v1, 0xbfb8aa3b, v1
	v_exp_f32_e32 v1, v1
	s_nop 0
	v_add_f32_e32 v1, 1.0, v1
	v_rcp_f32_e32 v1, v1
	v_and_b32_e32 v246, 0xffff0000, v162
	v_mul_f32_e32 v1, v246, v1
	v_add_f32_e32 v2, v2, v130
	v_mul_f32_e32 v2, 0xbfb8aa3b, v2
	v_exp_f32_e32 v2, v2
	s_nop 0
	v_add_f32_e32 v2, 1.0, v2
	v_rcp_f32_e32 v2, v2
	v_lshlrev_b32_e32 v246, 16, v163
	v_mul_f32_e32 v2, v246, v2
	v_add_f32_e32 v3, v3, v131
	v_mul_f32_e32 v3, 0xbfb8aa3b, v3
	v_exp_f32_e32 v3, v3
	s_nop 0
	v_add_f32_e32 v3, 1.0, v3
	v_rcp_f32_e32 v3, v3
	v_and_b32_e32 v246, 0xffff0000, v163
	v_mul_f32_e32 v3, v246, v3
	v_add_f32_e32 v4, v4, v132
	v_mul_f32_e32 v4, 0xbfb8aa3b, v4
	v_exp_f32_e32 v4, v4
	s_nop 0
	v_add_f32_e32 v4, 1.0, v4
	v_rcp_f32_e32 v4, v4
	v_lshlrev_b32_e32 v246, 16, v164
	v_mul_f32_e32 v4, v246, v4
	v_add_f32_e32 v5, v5, v133
	v_mul_f32_e32 v5, 0xbfb8aa3b, v5
	v_exp_f32_e32 v5, v5
	s_nop 0
	v_add_f32_e32 v5, 1.0, v5
	v_rcp_f32_e32 v5, v5
	v_and_b32_e32 v246, 0xffff0000, v164
	v_mul_f32_e32 v5, v246, v5
	v_add_f32_e32 v6, v6, v134
	v_mul_f32_e32 v6, 0xbfb8aa3b, v6
	v_exp_f32_e32 v6, v6
	s_nop 0
	v_add_f32_e32 v6, 1.0, v6
	v_rcp_f32_e32 v6, v6
	v_lshlrev_b32_e32 v246, 16, v165
	v_mul_f32_e32 v6, v246, v6
	v_add_f32_e32 v7, v7, v135
	v_mul_f32_e32 v7, 0xbfb8aa3b, v7
	v_exp_f32_e32 v7, v7
	s_nop 0
	v_add_f32_e32 v7, 1.0, v7
	v_rcp_f32_e32 v7, v7
	v_and_b32_e32 v246, 0xffff0000, v165
	v_mul_f32_e32 v7, v246, v7
	v_add_f32_e32 v8, v8, v136
	v_mul_f32_e32 v8, 0xbfb8aa3b, v8
	v_exp_f32_e32 v8, v8
	s_nop 0
	v_add_f32_e32 v8, 1.0, v8
	v_rcp_f32_e32 v8, v8
	v_lshlrev_b32_e32 v246, 16, v166
	v_mul_f32_e32 v8, v246, v8
	v_add_f32_e32 v9, v9, v137
	v_mul_f32_e32 v9, 0xbfb8aa3b, v9
	v_exp_f32_e32 v9, v9
	s_nop 0
	v_add_f32_e32 v9, 1.0, v9
	v_rcp_f32_e32 v9, v9
	v_and_b32_e32 v246, 0xffff0000, v166
	v_mul_f32_e32 v9, v246, v9
	v_add_f32_e32 v10, v10, v138
	v_mul_f32_e32 v10, 0xbfb8aa3b, v10
	v_exp_f32_e32 v10, v10
	s_nop 0
	v_add_f32_e32 v10, 1.0, v10
	v_rcp_f32_e32 v10, v10
	v_lshlrev_b32_e32 v246, 16, v167
	v_mul_f32_e32 v10, v246, v10
	v_add_f32_e32 v11, v11, v139
	v_mul_f32_e32 v11, 0xbfb8aa3b, v11
	v_exp_f32_e32 v11, v11
	s_nop 0
	v_add_f32_e32 v11, 1.0, v11
	v_rcp_f32_e32 v11, v11
	v_and_b32_e32 v246, 0xffff0000, v167
	v_mul_f32_e32 v11, v246, v11
	v_add_f32_e32 v12, v12, v140
	v_mul_f32_e32 v12, 0xbfb8aa3b, v12
	v_exp_f32_e32 v12, v12
	s_nop 0
	v_add_f32_e32 v12, 1.0, v12
	v_rcp_f32_e32 v12, v12
	v_lshlrev_b32_e32 v246, 16, v168
	v_mul_f32_e32 v12, v246, v12
	v_add_f32_e32 v13, v13, v141
	v_mul_f32_e32 v13, 0xbfb8aa3b, v13
	v_exp_f32_e32 v13, v13
	s_nop 0
	v_add_f32_e32 v13, 1.0, v13
	v_rcp_f32_e32 v13, v13
	v_and_b32_e32 v246, 0xffff0000, v168
	v_mul_f32_e32 v13, v246, v13
	v_add_f32_e32 v14, v14, v142
	v_mul_f32_e32 v14, 0xbfb8aa3b, v14
	v_exp_f32_e32 v14, v14
	s_nop 0
	v_add_f32_e32 v14, 1.0, v14
	v_rcp_f32_e32 v14, v14
	v_lshlrev_b32_e32 v246, 16, v169
	v_mul_f32_e32 v14, v246, v14
	v_add_f32_e32 v15, v15, v143
	v_mul_f32_e32 v15, 0xbfb8aa3b, v15
	v_exp_f32_e32 v15, v15
	s_nop 0
	v_add_f32_e32 v15, 1.0, v15
	v_rcp_f32_e32 v15, v15
	v_and_b32_e32 v246, 0xffff0000, v169
	v_mul_f32_e32 v15, v246, v15
	v_add_f32_e32 v16, v16, v144
	v_mul_f32_e32 v16, 0xbfb8aa3b, v16
	v_exp_f32_e32 v16, v16
	s_nop 0
	v_add_f32_e32 v16, 1.0, v16
	v_rcp_f32_e32 v16, v16
	v_lshlrev_b32_e32 v246, 16, v170
	v_mul_f32_e32 v16, v246, v16
	v_add_f32_e32 v17, v17, v145
	v_mul_f32_e32 v17, 0xbfb8aa3b, v17
	v_exp_f32_e32 v17, v17
	s_nop 0
	v_add_f32_e32 v17, 1.0, v17
	v_rcp_f32_e32 v17, v17
	v_and_b32_e32 v246, 0xffff0000, v170
	v_mul_f32_e32 v17, v246, v17
	v_add_f32_e32 v18, v18, v146
	v_mul_f32_e32 v18, 0xbfb8aa3b, v18
	v_exp_f32_e32 v18, v18
	s_nop 0
	v_add_f32_e32 v18, 1.0, v18
	v_rcp_f32_e32 v18, v18
	v_lshlrev_b32_e32 v246, 16, v171
	v_mul_f32_e32 v18, v246, v18
	v_add_f32_e32 v19, v19, v147
	v_mul_f32_e32 v19, 0xbfb8aa3b, v19
	v_exp_f32_e32 v19, v19
	s_nop 0
	v_add_f32_e32 v19, 1.0, v19
	v_rcp_f32_e32 v19, v19
	v_and_b32_e32 v246, 0xffff0000, v171
	v_mul_f32_e32 v19, v246, v19
	v_add_f32_e32 v20, v20, v148
	v_mul_f32_e32 v20, 0xbfb8aa3b, v20
	v_exp_f32_e32 v20, v20
	s_nop 0
	v_add_f32_e32 v20, 1.0, v20
	v_rcp_f32_e32 v20, v20
	v_lshlrev_b32_e32 v246, 16, v172
	v_mul_f32_e32 v20, v246, v20
	v_add_f32_e32 v21, v21, v149
	v_mul_f32_e32 v21, 0xbfb8aa3b, v21
	v_exp_f32_e32 v21, v21
	s_nop 0
	v_add_f32_e32 v21, 1.0, v21
	v_rcp_f32_e32 v21, v21
	v_and_b32_e32 v246, 0xffff0000, v172
	v_mul_f32_e32 v21, v246, v21
	v_add_f32_e32 v22, v22, v150
	v_mul_f32_e32 v22, 0xbfb8aa3b, v22
	v_exp_f32_e32 v22, v22
	s_nop 0
	v_add_f32_e32 v22, 1.0, v22
	v_rcp_f32_e32 v22, v22
	v_lshlrev_b32_e32 v246, 16, v173
	v_mul_f32_e32 v22, v246, v22
	v_add_f32_e32 v23, v23, v151
	v_mul_f32_e32 v23, 0xbfb8aa3b, v23
	v_exp_f32_e32 v23, v23
	s_nop 0
	v_add_f32_e32 v23, 1.0, v23
	v_rcp_f32_e32 v23, v23
	v_and_b32_e32 v246, 0xffff0000, v173
	v_mul_f32_e32 v23, v246, v23
	v_add_f32_e32 v24, v24, v152
	v_mul_f32_e32 v24, 0xbfb8aa3b, v24
	v_exp_f32_e32 v24, v24
	s_nop 0
	v_add_f32_e32 v24, 1.0, v24
	v_rcp_f32_e32 v24, v24
	v_lshlrev_b32_e32 v246, 16, v174
	v_mul_f32_e32 v24, v246, v24
	v_add_f32_e32 v25, v25, v153
	v_mul_f32_e32 v25, 0xbfb8aa3b, v25
	v_exp_f32_e32 v25, v25
	s_nop 0
	v_add_f32_e32 v25, 1.0, v25
	v_rcp_f32_e32 v25, v25
	v_and_b32_e32 v246, 0xffff0000, v174
	v_mul_f32_e32 v25, v246, v25
	v_add_f32_e32 v26, v26, v154
	v_mul_f32_e32 v26, 0xbfb8aa3b, v26
	v_exp_f32_e32 v26, v26
; DI float bf2f(unsigned h) { return __uint_as_float(h << 16); }
; DI int crow(int r, int hf) { return (r & 3) + 8 * (r >> 2) + 4 * hf; }
; DI void glu_phase(const Params& p, int j, char* smem) {
;     ...
; #pragma unroll
;       for (int i = 0; i < 2; ++i)
; #pragma unroll
;         for (int jn = 0; jn < 2; ++jn)
; #pragma unroll
;           for (int r = 0; r < 16; ++r) {
;             const int row = m0_ + wm * 64 + i * 32 + crow(r, hf_), col = n0 + wn * 64 + jn * 32 + l32_;
;             const float gt = acc[i][jn][r] + gb[col];
;             const float y = bf2f(yt[(size_t)row * LDYT + col]);
;             o[(size_t)row * LDH + 512 + col] = f2bf(y / (1.f + __expf(-gt)));
	s_nop 0
	v_add_f32_e32 v26, 1.0, v26
	v_rcp_f32_e32 v26, v26
	v_lshlrev_b32_e32 v246, 16, v175
	v_mul_f32_e32 v26, v246, v26
	v_add_f32_e32 v27, v27, v155
	v_mul_f32_e32 v27, 0xbfb8aa3b, v27
	v_exp_f32_e32 v27, v27
	s_nop 0
	v_add_f32_e32 v27, 1.0, v27
	v_rcp_f32_e32 v27, v27
	v_and_b32_e32 v246, 0xffff0000, v175
	v_mul_f32_e32 v27, v246, v27
	v_add_f32_e32 v28, v28, v156
	v_mul_f32_e32 v28, 0xbfb8aa3b, v28
	v_exp_f32_e32 v28, v28
	s_nop 0
	v_add_f32_e32 v28, 1.0, v28
	v_rcp_f32_e32 v28, v28
	v_lshlrev_b32_e32 v246, 16, v176
	v_mul_f32_e32 v28, v246, v28
	v_add_f32_e32 v29, v29, v157
	v_mul_f32_e32 v29, 0xbfb8aa3b, v29
	v_exp_f32_e32 v29, v29
	s_nop 0
	v_add_f32_e32 v29, 1.0, v29
	v_rcp_f32_e32 v29, v29
	v_and_b32_e32 v246, 0xffff0000, v176
	v_mul_f32_e32 v29, v246, v29
	v_add_f32_e32 v30, v30, v158
	v_mul_f32_e32 v30, 0xbfb8aa3b, v30
	v_exp_f32_e32 v30, v30
	s_nop 0
	v_add_f32_e32 v30, 1.0, v30
	v_rcp_f32_e32 v30, v30
	v_lshlrev_b32_e32 v246, 16, v177
	v_mul_f32_e32 v30, v246, v30
	v_add_f32_e32 v31, v31, v159
	v_mul_f32_e32 v31, 0xbfb8aa3b, v31
	v_exp_f32_e32 v31, v31
	s_nop 0
	v_add_f32_e32 v31, 1.0, v31
	v_rcp_f32_e32 v31, v31
	v_and_b32_e32 v246, 0xffff0000, v177
	v_mul_f32_e32 v31, v246, v31
	global_load_dwordx2 v[162:163], v197, s[12:13]
	global_load_dwordx2 v[164:165], v197, s[12:13] offset:16
	global_load_dwordx2 v[166:167], v197, s[12:13] offset:32
	global_load_dwordx2 v[168:169], v197, s[12:13] offset:48
	global_load_dwordx2 v[170:171], v197, s[12:13] offset:64
	global_load_dwordx2 v[172:173], v197, s[12:13] offset:80
	global_load_dwordx2 v[174:175], v197, s[12:13] offset:96
	global_load_dwordx2 v[176:177], v197, s[12:13] offset:112
	s_add_u32 s12, s12, 0x9000
	s_addc_u32 s13, s13, 0
	v_cvt_pk_bf16_f32 v240, v0, v1
	v_cvt_pk_bf16_f32 v241, v2, v3
	ds_write_b64 v178, v[240:241]
	v_cvt_pk_bf16_f32 v242, v4, v5
	v_cvt_pk_bf16_f32 v243, v6, v7
	ds_write_b64 v179, v[242:243]
	v_cvt_pk_bf16_f32 v244, v8, v9
	v_cvt_pk_bf16_f32 v245, v10, v11
	ds_write_b64 v180, v[244:245]
	v_cvt_pk_bf16_f32 v240, v12, v13
	v_cvt_pk_bf16_f32 v241, v14, v15
	ds_write_b64 v181, v[240:241]
	v_cvt_pk_bf16_f32 v242, v16, v17
	v_cvt_pk_bf16_f32 v243, v18, v19
	ds_write_b64 v188, v[242:243]
	v_cvt_pk_bf16_f32 v244, v20, v21
	v_cvt_pk_bf16_f32 v245, v22, v23
	ds_write_b64 v189, v[244:245]
	v_cvt_pk_bf16_f32 v240, v24, v25
	v_cvt_pk_bf16_f32 v241, v26, v27
	ds_write_b64 v190, v[240:241]
	v_cvt_pk_bf16_f32 v242, v28, v29
	v_cvt_pk_bf16_f32 v243, v30, v31
	ds_write_b64 v191, v[242:243]
	ds_read_b128 v[0:3], v194
	ds_read_b128 v[4:7], v194 offset:1024
	ds_read_b128 v[8:11], v194 offset:2048
	ds_read_b128 v[12:15], v194 offset:3072
	s_waitcnt vmcnt(8)
	v_add_f32_e32 v32, v32, v128
	v_mul_f32_e32 v32, 0xbfb8aa3b, v32
	v_exp_f32_e32 v32, v32
	s_nop 0
	v_add_f32_e32 v32, 1.0, v32
	v_rcp_f32_e32 v32, v32
	v_lshlrev_b32_e32 v246, 16, v224
	v_mul_f32_e32 v32, v246, v32
	v_add_f32_e32 v33, v33, v129
	v_mul_f32_e32 v33, 0xbfb8aa3b, v33
	v_exp_f32_e32 v33, v33
	s_nop 0
	v_add_f32_e32 v33, 1.0, v33
	v_rcp_f32_e32 v33, v33
	v_and_b32_e32 v246, 0xffff0000, v224
	v_mul_f32_e32 v33, v246, v33
	v_add_f32_e32 v34, v34, v130
	v_mul_f32_e32 v34, 0xbfb8aa3b, v34
	v_exp_f32_e32 v34, v34
	s_nop 0
	v_add_f32_e32 v34, 1.0, v34
	v_rcp_f32_e32 v34, v34
	v_lshlrev_b32_e32 v246, 16, v225
	v_mul_f32_e32 v34, v246, v34
	v_add_f32_e32 v35, v35, v131
	v_mul_f32_e32 v35, 0xbfb8aa3b, v35
	v_exp_f32_e32 v35, v35
	s_nop 0
	v_add_f32_e32 v35, 1.0, v35
	v_rcp_f32_e32 v35, v35
	v_and_b32_e32 v246, 0xffff0000, v225
	v_mul_f32_e32 v35, v246, v35
	v_add_f32_e32 v36, v36, v132
	v_mul_f32_e32 v36, 0xbfb8aa3b, v36
	v_exp_f32_e32 v36, v36
	s_nop 0
	v_add_f32_e32 v36, 1.0, v36
	v_rcp_f32_e32 v36, v36
	v_lshlrev_b32_e32 v246, 16, v226
	v_mul_f32_e32 v36, v246, v36
	v_add_f32_e32 v37, v37, v133
	v_mul_f32_e32 v37, 0xbfb8aa3b, v37
	v_exp_f32_e32 v37, v37
	s_nop 0
	v_add_f32_e32 v37, 1.0, v37
	v_rcp_f32_e32 v37, v37
	v_and_b32_e32 v246, 0xffff0000, v226
	v_mul_f32_e32 v37, v246, v37
	v_add_f32_e32 v38, v38, v134
	v_mul_f32_e32 v38, 0xbfb8aa3b, v38
	v_exp_f32_e32 v38, v38
	s_nop 0
	v_add_f32_e32 v38, 1.0, v38
	v_rcp_f32_e32 v38, v38
	v_lshlrev_b32_e32 v246, 16, v227
	v_mul_f32_e32 v38, v246, v38
	v_add_f32_e32 v39, v39, v135
	v_mul_f32_e32 v39, 0xbfb8aa3b, v39
	v_exp_f32_e32 v39, v39
	s_nop 0
	v_add_f32_e32 v39, 1.0, v39
	v_rcp_f32_e32 v39, v39
	v_and_b32_e32 v246, 0xffff0000, v227
	v_mul_f32_e32 v39, v246, v39
	v_add_f32_e32 v40, v40, v136
	v_mul_f32_e32 v40, 0xbfb8aa3b, v40
	v_exp_f32_e32 v40, v40
	s_nop 0
	v_add_f32_e32 v40, 1.0, v40
	v_rcp_f32_e32 v40, v40
	v_lshlrev_b32_e32 v246, 16, v228
	v_mul_f32_e32 v40, v246, v40
	v_add_f32_e32 v41, v41, v137
	v_mul_f32_e32 v41, 0xbfb8aa3b, v41
	v_exp_f32_e32 v41, v41
	s_nop 0
	v_add_f32_e32 v41, 1.0, v41
	v_rcp_f32_e32 v41, v41
	v_and_b32_e32 v246, 0xffff0000, v228
	v_mul_f32_e32 v41, v246, v41
	v_add_f32_e32 v42, v42, v138
	v_mul_f32_e32 v42, 0xbfb8aa3b, v42
	v_exp_f32_e32 v42, v42
	s_nop 0
	v_add_f32_e32 v42, 1.0, v42
	v_rcp_f32_e32 v42, v42
	v_lshlrev_b32_e32 v246, 16, v229
	v_mul_f32_e32 v42, v246, v42
	v_add_f32_e32 v43, v43, v139
	v_mul_f32_e32 v43, 0xbfb8aa3b, v43
	v_exp_f32_e32 v43, v43
	s_nop 0
	v_add_f32_e32 v43, 1.0, v43
	v_rcp_f32_e32 v43, v43
	v_and_b32_e32 v246, 0xffff0000, v229
	v_mul_f32_e32 v43, v246, v43
	v_add_f32_e32 v44, v44, v140
	v_mul_f32_e32 v44, 0xbfb8aa3b, v44
	v_exp_f32_e32 v44, v44
	s_nop 0
	v_add_f32_e32 v44, 1.0, v44
	v_rcp_f32_e32 v44, v44
	v_lshlrev_b32_e32 v246, 16, v230
	v_mul_f32_e32 v44, v246, v44
	v_add_f32_e32 v45, v45, v141
	v_mul_f32_e32 v45, 0xbfb8aa3b, v45
	v_exp_f32_e32 v45, v45
	s_nop 0
	v_add_f32_e32 v45, 1.0, v45
; DI float bf2f(unsigned h) { return __uint_as_float(h << 16); }
; DI int crow(int r, int hf) { return (r & 3) + 8 * (r >> 2) + 4 * hf; }
; DI void glu_phase(const Params& p, int j, char* smem) {
;     ...
; #pragma unroll
;       for (int i = 0; i < 2; ++i)
; #pragma unroll
;         for (int jn = 0; jn < 2; ++jn)
; #pragma unroll
;           for (int r = 0; r < 16; ++r) {
;             const int row = m0_ + wm * 64 + i * 32 + crow(r, hf_), col = n0 + wn * 64 + jn * 32 + l32_;
;             const float gt = acc[i][jn][r] + gb[col];
;             const float y = bf2f(yt[(size_t)row * LDYT + col]);
;             o[(size_t)row * LDH + 512 + col] = f2bf(y / (1.f + __expf(-gt)));
	v_rcp_f32_e32 v45, v45
	v_and_b32_e32 v246, 0xffff0000, v230
	v_mul_f32_e32 v45, v246, v45
	v_add_f32_e32 v46, v46, v142
	v_mul_f32_e32 v46, 0xbfb8aa3b, v46
	v_exp_f32_e32 v46, v46
	s_nop 0
	v_add_f32_e32 v46, 1.0, v46
	v_rcp_f32_e32 v46, v46
	v_lshlrev_b32_e32 v246, 16, v231
	v_mul_f32_e32 v46, v246, v46
	v_add_f32_e32 v47, v47, v143
	v_mul_f32_e32 v47, 0xbfb8aa3b, v47
	v_exp_f32_e32 v47, v47
	s_nop 0
	v_add_f32_e32 v47, 1.0, v47
	v_rcp_f32_e32 v47, v47
	v_and_b32_e32 v246, 0xffff0000, v231
	v_mul_f32_e32 v47, v246, v47
	v_add_f32_e32 v48, v48, v144
	v_mul_f32_e32 v48, 0xbfb8aa3b, v48
	v_exp_f32_e32 v48, v48
	s_nop 0
	v_add_f32_e32 v48, 1.0, v48
	v_rcp_f32_e32 v48, v48
	v_lshlrev_b32_e32 v246, 16, v232
	v_mul_f32_e32 v48, v246, v48
	v_add_f32_e32 v49, v49, v145
	v_mul_f32_e32 v49, 0xbfb8aa3b, v49
	v_exp_f32_e32 v49, v49
	s_nop 0
	v_add_f32_e32 v49, 1.0, v49
	v_rcp_f32_e32 v49, v49
	v_and_b32_e32 v246, 0xffff0000, v232
	v_mul_f32_e32 v49, v246, v49
	v_add_f32_e32 v50, v50, v146
	v_mul_f32_e32 v50, 0xbfb8aa3b, v50
	v_exp_f32_e32 v50, v50
	s_nop 0
	v_add_f32_e32 v50, 1.0, v50
	v_rcp_f32_e32 v50, v50
	v_lshlrev_b32_e32 v246, 16, v233
	v_mul_f32_e32 v50, v246, v50
	v_add_f32_e32 v51, v51, v147
	v_mul_f32_e32 v51, 0xbfb8aa3b, v51
	v_exp_f32_e32 v51, v51
	s_nop 0
	v_add_f32_e32 v51, 1.0, v51
	v_rcp_f32_e32 v51, v51
	v_and_b32_e32 v246, 0xffff0000, v233
	v_mul_f32_e32 v51, v246, v51
	v_add_f32_e32 v52, v52, v148
	v_mul_f32_e32 v52, 0xbfb8aa3b, v52
	v_exp_f32_e32 v52, v52
	s_nop 0
	v_add_f32_e32 v52, 1.0, v52
	v_rcp_f32_e32 v52, v52
	v_lshlrev_b32_e32 v246, 16, v234
	v_mul_f32_e32 v52, v246, v52
	v_add_f32_e32 v53, v53, v149
	v_mul_f32_e32 v53, 0xbfb8aa3b, v53
	v_exp_f32_e32 v53, v53
	s_nop 0
	v_add_f32_e32 v53, 1.0, v53
	v_rcp_f32_e32 v53, v53
	v_and_b32_e32 v246, 0xffff0000, v234
	v_mul_f32_e32 v53, v246, v53
	v_add_f32_e32 v54, v54, v150
	v_mul_f32_e32 v54, 0xbfb8aa3b, v54
	v_exp_f32_e32 v54, v54
	s_nop 0
	v_add_f32_e32 v54, 1.0, v54
	v_rcp_f32_e32 v54, v54
	v_lshlrev_b32_e32 v246, 16, v235
	v_mul_f32_e32 v54, v246, v54
	v_add_f32_e32 v55, v55, v151
	v_mul_f32_e32 v55, 0xbfb8aa3b, v55
	v_exp_f32_e32 v55, v55
	s_nop 0
	v_add_f32_e32 v55, 1.0, v55
	v_rcp_f32_e32 v55, v55
	v_and_b32_e32 v246, 0xffff0000, v235
	v_mul_f32_e32 v55, v246, v55
	v_add_f32_e32 v56, v56, v152
	v_mul_f32_e32 v56, 0xbfb8aa3b, v56
	v_exp_f32_e32 v56, v56
	s_nop 0
	v_add_f32_e32 v56, 1.0, v56
	v_rcp_f32_e32 v56, v56
	v_lshlrev_b32_e32 v246, 16, v236
	v_mul_f32_e32 v56, v246, v56
	v_add_f32_e32 v57, v57, v153
	v_mul_f32_e32 v57, 0xbfb8aa3b, v57
	v_exp_f32_e32 v57, v57
	s_nop 0
	v_add_f32_e32 v57, 1.0, v57
	v_rcp_f32_e32 v57, v57
	v_and_b32_e32 v246, 0xffff0000, v236
	v_mul_f32_e32 v57, v246, v57
	v_add_f32_e32 v58, v58, v154
	v_mul_f32_e32 v58, 0xbfb8aa3b, v58
	v_exp_f32_e32 v58, v58
	s_nop 0
	v_add_f32_e32 v58, 1.0, v58
	v_rcp_f32_e32 v58, v58
	v_lshlrev_b32_e32 v246, 16, v237
	v_mul_f32_e32 v58, v246, v58
	v_add_f32_e32 v59, v59, v155
	v_mul_f32_e32 v59, 0xbfb8aa3b, v59
	v_exp_f32_e32 v59, v59
	s_nop 0
	v_add_f32_e32 v59, 1.0, v59
	v_rcp_f32_e32 v59, v59
	v_and_b32_e32 v246, 0xffff0000, v237
	v_mul_f32_e32 v59, v246, v59
	v_add_f32_e32 v60, v60, v156
	v_mul_f32_e32 v60, 0xbfb8aa3b, v60
	v_exp_f32_e32 v60, v60
	s_nop 0
	v_add_f32_e32 v60, 1.0, v60
	v_rcp_f32_e32 v60, v60
	v_lshlrev_b32_e32 v246, 16, v238
	v_mul_f32_e32 v60, v246, v60
	v_add_f32_e32 v61, v61, v157
	v_mul_f32_e32 v61, 0xbfb8aa3b, v61
	v_exp_f32_e32 v61, v61
	s_nop 0
	v_add_f32_e32 v61, 1.0, v61
	v_rcp_f32_e32 v61, v61
	v_and_b32_e32 v246, 0xffff0000, v238
	v_mul_f32_e32 v61, v246, v61
	v_add_f32_e32 v62, v62, v158
	v_mul_f32_e32 v62, 0xbfb8aa3b, v62
	v_exp_f32_e32 v62, v62
	s_nop 0
	v_add_f32_e32 v62, 1.0, v62
	v_rcp_f32_e32 v62, v62
	v_lshlrev_b32_e32 v246, 16, v239
	v_mul_f32_e32 v62, v246, v62
	v_add_f32_e32 v63, v63, v159
	v_mul_f32_e32 v63, 0xbfb8aa3b, v63
	v_exp_f32_e32 v63, v63
	s_nop 0
	v_add_f32_e32 v63, 1.0, v63
	v_rcp_f32_e32 v63, v63
	v_and_b32_e32 v246, 0xffff0000, v239
	v_mul_f32_e32 v63, v246, v63
	global_load_dwordx2 v[224:225], v197, s[12:13]
	global_load_dwordx2 v[226:227], v197, s[12:13] offset:16
	global_load_dwordx2 v[228:229], v197, s[12:13] offset:32
	global_load_dwordx2 v[230:231], v197, s[12:13] offset:48
	global_load_dwordx2 v[232:233], v197, s[12:13] offset:64
	global_load_dwordx2 v[234:235], v197, s[12:13] offset:80
	global_load_dwordx2 v[236:237], v197, s[12:13] offset:96
	global_load_dwordx2 v[238:239], v197, s[12:13] offset:112
	s_add_u32 s12, s12, 0x9000
	s_addc_u32 s13, s13, 0
	v_cvt_pk_bf16_f32 v244, v32, v33
	v_cvt_pk_bf16_f32 v245, v34, v35
	ds_write_b64 v178, v[244:245]
	v_cvt_pk_bf16_f32 v240, v36, v37
	v_cvt_pk_bf16_f32 v241, v38, v39
	ds_write_b64 v179, v[240:241]
	v_cvt_pk_bf16_f32 v242, v40, v41
	v_cvt_pk_bf16_f32 v243, v42, v43
	ds_write_b64 v180, v[242:243]
	v_cvt_pk_bf16_f32 v244, v44, v45
	v_cvt_pk_bf16_f32 v245, v46, v47
	ds_write_b64 v181, v[244:245]
	v_cvt_pk_bf16_f32 v240, v48, v49
	v_cvt_pk_bf16_f32 v241, v50, v51
	ds_write_b64 v188, v[240:241]
	v_cvt_pk_bf16_f32 v242, v52, v53
	v_cvt_pk_bf16_f32 v243, v54, v55
	ds_write_b64 v189, v[242:243]
	v_cvt_pk_bf16_f32 v244, v56, v57
	v_cvt_pk_bf16_f32 v245, v58, v59
	ds_write_b64 v190, v[244:245]
	v_cvt_pk_bf16_f32 v240, v60, v61
	v_cvt_pk_bf16_f32 v241, v62, v63
	ds_write_b64 v191, v[240:241]
	ds_read_b128 v[32:35], v194
	ds_read_b128 v[36:39], v194 offset:1024
	ds_read_b128 v[40:43], v194 offset:2048
	ds_read_b128 v[44:47], v194 offset:3072
	s_waitcnt lgkmcnt(12)
; DI float bf2f(unsigned h) { return __uint_as_float(h << 16); }
; DI int crow(int r, int hf) { return (r & 3) + 8 * (r >> 2) + 4 * hf; }
; DI void glu_phase(const Params& p, int j, char* smem) {
;     ...
;       int l32_ = l32, hf_ = hf; asm volatile("" : "+v"(l32_), "+v"(hf_));
; #pragma unroll
;       for (int i = 0; i < 2; ++i)
; #pragma unroll
;         for (int jn = 0; jn < 2; ++jn)
; #pragma unroll
;           for (int r = 0; r < 16; ++r) {
;             const int row = m0_ + wm * 64 + i * 32 + crow(r, hf_), col = n0 + wn * 64 + jn * 32 + l32_;
;             const float gt = acc[i][jn][r] + gb[col];
;             const float y = bf2f(yt[(size_t)row * LDYT + col]);
;             o[(size_t)row * LDH + 512 + col] = f2bf(y / (1.f + __expf(-gt)));
;           }
	global_store_dwordx4 v195, v[0:3], s[100:101] nt
	s_add_u32 s100, s100, 0x4400
	s_addc_u32 s101, s101, 0
	global_store_dwordx4 v195, v[4:7], s[100:101] nt
	s_add_u32 s100, s100, 0x4400
	s_addc_u32 s101, s101, 0
	global_store_dwordx4 v195, v[8:11], s[100:101] nt
	s_add_u32 s100, s100, 0x4400
	s_addc_u32 s101, s101, 0
	global_store_dwordx4 v195, v[12:15], s[100:101] nt
	s_add_u32 s100, s100, 0x4400
	s_addc_u32 s101, s101, 0
	s_waitcnt vmcnt(12)
	v_add_f32_e32 v64, v64, v128
	v_mul_f32_e32 v64, 0xbfb8aa3b, v64
	v_exp_f32_e32 v64, v64
	s_nop 0
	v_add_f32_e32 v64, 1.0, v64
	v_rcp_f32_e32 v64, v64
	v_lshlrev_b32_e32 v246, 16, v162
	v_mul_f32_e32 v64, v246, v64
	v_add_f32_e32 v65, v65, v129
	v_mul_f32_e32 v65, 0xbfb8aa3b, v65
	v_exp_f32_e32 v65, v65
	s_nop 0
	v_add_f32_e32 v65, 1.0, v65
	v_rcp_f32_e32 v65, v65
	v_and_b32_e32 v246, 0xffff0000, v162
	v_mul_f32_e32 v65, v246, v65
	v_add_f32_e32 v66, v66, v130
	v_mul_f32_e32 v66, 0xbfb8aa3b, v66
	v_exp_f32_e32 v66, v66
	s_nop 0
	v_add_f32_e32 v66, 1.0, v66
	v_rcp_f32_e32 v66, v66
	v_lshlrev_b32_e32 v246, 16, v163
	v_mul_f32_e32 v66, v246, v66
	v_add_f32_e32 v67, v67, v131
	v_mul_f32_e32 v67, 0xbfb8aa3b, v67
	v_exp_f32_e32 v67, v67
	s_nop 0
	v_add_f32_e32 v67, 1.0, v67
	v_rcp_f32_e32 v67, v67
	v_and_b32_e32 v246, 0xffff0000, v163
	v_mul_f32_e32 v67, v246, v67
	v_add_f32_e32 v68, v68, v132
	v_mul_f32_e32 v68, 0xbfb8aa3b, v68
	v_exp_f32_e32 v68, v68
	s_nop 0
	v_add_f32_e32 v68, 1.0, v68
	v_rcp_f32_e32 v68, v68
	v_lshlrev_b32_e32 v246, 16, v164
	v_mul_f32_e32 v68, v246, v68
	v_add_f32_e32 v69, v69, v133
	v_mul_f32_e32 v69, 0xbfb8aa3b, v69
	v_exp_f32_e32 v69, v69
	s_nop 0
	v_add_f32_e32 v69, 1.0, v69
	v_rcp_f32_e32 v69, v69
	v_and_b32_e32 v246, 0xffff0000, v164
	v_mul_f32_e32 v69, v246, v69
	v_add_f32_e32 v70, v70, v134
	v_mul_f32_e32 v70, 0xbfb8aa3b, v70
	v_exp_f32_e32 v70, v70
	s_nop 0
	v_add_f32_e32 v70, 1.0, v70
	v_rcp_f32_e32 v70, v70
	v_lshlrev_b32_e32 v246, 16, v165
	v_mul_f32_e32 v70, v246, v70
	v_add_f32_e32 v71, v71, v135
	v_mul_f32_e32 v71, 0xbfb8aa3b, v71
	v_exp_f32_e32 v71, v71
	s_nop 0
	v_add_f32_e32 v71, 1.0, v71
	v_rcp_f32_e32 v71, v71
	v_and_b32_e32 v246, 0xffff0000, v165
	v_mul_f32_e32 v71, v246, v71
	v_add_f32_e32 v72, v72, v136
	v_mul_f32_e32 v72, 0xbfb8aa3b, v72
	v_exp_f32_e32 v72, v72
	s_nop 0
	v_add_f32_e32 v72, 1.0, v72
	v_rcp_f32_e32 v72, v72
	v_lshlrev_b32_e32 v246, 16, v166
	v_mul_f32_e32 v72, v246, v72
	v_add_f32_e32 v73, v73, v137
	v_mul_f32_e32 v73, 0xbfb8aa3b, v73
	v_exp_f32_e32 v73, v73
	s_nop 0
	v_add_f32_e32 v73, 1.0, v73
	v_rcp_f32_e32 v73, v73
	v_and_b32_e32 v246, 0xffff0000, v166
	v_mul_f32_e32 v73, v246, v73
	v_add_f32_e32 v74, v74, v138
	v_mul_f32_e32 v74, 0xbfb8aa3b, v74
	v_exp_f32_e32 v74, v74
	s_nop 0
	v_add_f32_e32 v74, 1.0, v74
	v_rcp_f32_e32 v74, v74
	v_lshlrev_b32_e32 v246, 16, v167
	v_mul_f32_e32 v74, v246, v74
	v_add_f32_e32 v75, v75, v139
	v_mul_f32_e32 v75, 0xbfb8aa3b, v75
	v_exp_f32_e32 v75, v75
	s_nop 0
	v_add_f32_e32 v75, 1.0, v75
	v_rcp_f32_e32 v75, v75
	v_and_b32_e32 v246, 0xffff0000, v167
	v_mul_f32_e32 v75, v246, v75
	v_add_f32_e32 v76, v76, v140
	v_mul_f32_e32 v76, 0xbfb8aa3b, v76
	v_exp_f32_e32 v76, v76
	s_nop 0
	v_add_f32_e32 v76, 1.0, v76
	v_rcp_f32_e32 v76, v76
	v_lshlrev_b32_e32 v246, 16, v168
	v_mul_f32_e32 v76, v246, v76
	v_add_f32_e32 v77, v77, v141
	v_mul_f32_e32 v77, 0xbfb8aa3b, v77
	v_exp_f32_e32 v77, v77
	s_nop 0
	v_add_f32_e32 v77, 1.0, v77
	v_rcp_f32_e32 v77, v77
	v_and_b32_e32 v246, 0xffff0000, v168
	v_mul_f32_e32 v77, v246, v77
	v_add_f32_e32 v78, v78, v142
	v_mul_f32_e32 v78, 0xbfb8aa3b, v78
	v_exp_f32_e32 v78, v78
	s_nop 0
	v_add_f32_e32 v78, 1.0, v78
	v_rcp_f32_e32 v78, v78
	v_lshlrev_b32_e32 v246, 16, v169
	v_mul_f32_e32 v78, v246, v78
	v_add_f32_e32 v79, v79, v143
	v_mul_f32_e32 v79, 0xbfb8aa3b, v79
	v_exp_f32_e32 v79, v79
	s_nop 0
	v_add_f32_e32 v79, 1.0, v79
	v_rcp_f32_e32 v79, v79
	v_and_b32_e32 v246, 0xffff0000, v169
	v_mul_f32_e32 v79, v246, v79
	v_add_f32_e32 v80, v80, v144
	v_mul_f32_e32 v80, 0xbfb8aa3b, v80
	v_exp_f32_e32 v80, v80
	s_nop 0
	v_add_f32_e32 v80, 1.0, v80
	v_rcp_f32_e32 v80, v80
	v_lshlrev_b32_e32 v246, 16, v170
	v_mul_f32_e32 v80, v246, v80
	v_add_f32_e32 v81, v81, v145
	v_mul_f32_e32 v81, 0xbfb8aa3b, v81
	v_exp_f32_e32 v81, v81
	s_nop 0
	v_add_f32_e32 v81, 1.0, v81
	v_rcp_f32_e32 v81, v81
	v_and_b32_e32 v246, 0xffff0000, v170
	v_mul_f32_e32 v81, v246, v81
	v_add_f32_e32 v82, v82, v146
	v_mul_f32_e32 v82, 0xbfb8aa3b, v82
	v_exp_f32_e32 v82, v82
	s_nop 0
	v_add_f32_e32 v82, 1.0, v82
	v_rcp_f32_e32 v82, v82
	v_lshlrev_b32_e32 v246, 16, v171
	v_mul_f32_e32 v82, v246, v82
	v_add_f32_e32 v83, v83, v147
	v_mul_f32_e32 v83, 0xbfb8aa3b, v83
	v_exp_f32_e32 v83, v83
	s_nop 0
	v_add_f32_e32 v83, 1.0, v83
	v_rcp_f32_e32 v83, v83
	v_and_b32_e32 v246, 0xffff0000, v171
	v_mul_f32_e32 v83, v246, v83
	v_add_f32_e32 v84, v84, v148
	v_mul_f32_e32 v84, 0xbfb8aa3b, v84
	v_exp_f32_e32 v84, v84
	s_nop 0
	v_add_f32_e32 v84, 1.0, v84
	v_rcp_f32_e32 v84, v84
	v_lshlrev_b32_e32 v246, 16, v172
	v_mul_f32_e32 v84, v246, v84
	v_add_f32_e32 v85, v85, v149
	v_mul_f32_e32 v85, 0xbfb8aa3b, v85
	v_exp_f32_e32 v85, v85
	s_nop 0
	v_add_f32_e32 v85, 1.0, v85
	v_rcp_f32_e32 v85, v85
	v_and_b32_e32 v246, 0xffff0000, v172
	v_mul_f32_e32 v85, v246, v85
	v_add_f32_e32 v86, v86, v150
	v_mul_f32_e32 v86, 0xbfb8aa3b, v86
	v_exp_f32_e32 v86, v86
	s_nop 0
	v_add_f32_e32 v86, 1.0, v86
	v_rcp_f32_e32 v86, v86
	v_lshlrev_b32_e32 v246, 16, v173
	v_mul_f32_e32 v86, v246, v86
	v_add_f32_e32 v87, v87, v151
	v_mul_f32_e32 v87, 0xbfb8aa3b, v87
	v_exp_f32_e32 v87, v87
	s_nop 0
	v_add_f32_e32 v87, 1.0, v87
	v_rcp_f32_e32 v87, v87
	v_and_b32_e32 v246, 0xffff0000, v173
; DI float bf2f(unsigned h) { return __uint_as_float(h << 16); }
; DI int crow(int r, int hf) { return (r & 3) + 8 * (r >> 2) + 4 * hf; }
; DI void glu_phase(const Params& p, int j, char* smem) {
;     ...
;       int l32_ = l32, hf_ = hf; asm volatile("" : "+v"(l32_), "+v"(hf_));
; #pragma unroll
;       for (int i = 0; i < 2; ++i)
; #pragma unroll
;         for (int jn = 0; jn < 2; ++jn)
; #pragma unroll
;           for (int r = 0; r < 16; ++r) {
;             const int row = m0_ + wm * 64 + i * 32 + crow(r, hf_), col = n0 + wn * 64 + jn * 32 + l32_;
;             const float gt = acc[i][jn][r] + gb[col];
;             const float y = bf2f(yt[(size_t)row * LDYT + col]);
;             o[(size_t)row * LDH + 512 + col] = f2bf(y / (1.f + __expf(-gt)));
;           }
	v_mul_f32_e32 v87, v246, v87
	v_add_f32_e32 v88, v88, v152
	v_mul_f32_e32 v88, 0xbfb8aa3b, v88
	v_exp_f32_e32 v88, v88
	s_nop 0
	v_add_f32_e32 v88, 1.0, v88
	v_rcp_f32_e32 v88, v88
	v_lshlrev_b32_e32 v246, 16, v174
	v_mul_f32_e32 v88, v246, v88
	v_add_f32_e32 v89, v89, v153
	v_mul_f32_e32 v89, 0xbfb8aa3b, v89
	v_exp_f32_e32 v89, v89
	s_nop 0
	v_add_f32_e32 v89, 1.0, v89
	v_rcp_f32_e32 v89, v89
	v_and_b32_e32 v246, 0xffff0000, v174
	v_mul_f32_e32 v89, v246, v89
	v_add_f32_e32 v90, v90, v154
	v_mul_f32_e32 v90, 0xbfb8aa3b, v90
	v_exp_f32_e32 v90, v90
	s_nop 0
	v_add_f32_e32 v90, 1.0, v90
	v_rcp_f32_e32 v90, v90
	v_lshlrev_b32_e32 v246, 16, v175
	v_mul_f32_e32 v90, v246, v90
	v_add_f32_e32 v91, v91, v155
	v_mul_f32_e32 v91, 0xbfb8aa3b, v91
	v_exp_f32_e32 v91, v91
	s_nop 0
	v_add_f32_e32 v91, 1.0, v91
	v_rcp_f32_e32 v91, v91
	v_and_b32_e32 v246, 0xffff0000, v175
	v_mul_f32_e32 v91, v246, v91
	v_add_f32_e32 v92, v92, v156
	v_mul_f32_e32 v92, 0xbfb8aa3b, v92
	v_exp_f32_e32 v92, v92
	s_nop 0
	v_add_f32_e32 v92, 1.0, v92
	v_rcp_f32_e32 v92, v92
	v_lshlrev_b32_e32 v246, 16, v176
	v_mul_f32_e32 v92, v246, v92
	v_add_f32_e32 v93, v93, v157
	v_mul_f32_e32 v93, 0xbfb8aa3b, v93
	v_exp_f32_e32 v93, v93
	s_nop 0
	v_add_f32_e32 v93, 1.0, v93
	v_rcp_f32_e32 v93, v93
	v_and_b32_e32 v246, 0xffff0000, v176
	v_mul_f32_e32 v93, v246, v93
	v_add_f32_e32 v94, v94, v158
	v_mul_f32_e32 v94, 0xbfb8aa3b, v94
	v_exp_f32_e32 v94, v94
	s_nop 0
	v_add_f32_e32 v94, 1.0, v94
	v_rcp_f32_e32 v94, v94
	v_lshlrev_b32_e32 v246, 16, v177
	v_mul_f32_e32 v94, v246, v94
	v_add_f32_e32 v95, v95, v159
	v_mul_f32_e32 v95, 0xbfb8aa3b, v95
	v_exp_f32_e32 v95, v95
	s_nop 0
	v_add_f32_e32 v95, 1.0, v95
	v_rcp_f32_e32 v95, v95
	v_and_b32_e32 v246, 0xffff0000, v177
	v_mul_f32_e32 v95, v246, v95
	v_cvt_pk_bf16_f32 v242, v64, v65
	v_cvt_pk_bf16_f32 v243, v66, v67
	ds_write_b64 v178, v[242:243]
	v_cvt_pk_bf16_f32 v244, v68, v69
	v_cvt_pk_bf16_f32 v245, v70, v71
	ds_write_b64 v179, v[244:245]
	v_cvt_pk_bf16_f32 v240, v72, v73
	v_cvt_pk_bf16_f32 v241, v74, v75
	ds_write_b64 v180, v[240:241]
	v_cvt_pk_bf16_f32 v242, v76, v77
	v_cvt_pk_bf16_f32 v243, v78, v79
	ds_write_b64 v181, v[242:243]
	v_cvt_pk_bf16_f32 v244, v80, v81
	v_cvt_pk_bf16_f32 v245, v82, v83
	ds_write_b64 v188, v[244:245]
	v_cvt_pk_bf16_f32 v240, v84, v85
	v_cvt_pk_bf16_f32 v241, v86, v87
	ds_write_b64 v189, v[240:241]
	v_cvt_pk_bf16_f32 v242, v88, v89
	v_cvt_pk_bf16_f32 v243, v90, v91
	ds_write_b64 v190, v[242:243]
	v_cvt_pk_bf16_f32 v244, v92, v93
	v_cvt_pk_bf16_f32 v245, v94, v95
	ds_write_b64 v191, v[244:245]
	ds_read_b128 v[64:67], v194
	ds_read_b128 v[68:71], v194 offset:1024
	ds_read_b128 v[72:75], v194 offset:2048
	ds_read_b128 v[76:79], v194 offset:3072
	s_waitcnt lgkmcnt(12)
	global_store_dwordx4 v195, v[32:35], s[100:101] nt
	s_add_u32 s100, s100, 0x4400
	s_addc_u32 s101, s101, 0
	global_store_dwordx4 v195, v[36:39], s[100:101] nt
	s_add_u32 s100, s100, 0x4400
	s_addc_u32 s101, s101, 0
	global_store_dwordx4 v195, v[40:43], s[100:101] nt
	s_add_u32 s100, s100, 0x4400
	s_addc_u32 s101, s101, 0
	global_store_dwordx4 v195, v[44:47], s[100:101] nt
	s_add_u32 s100, s100, 0x4400
	s_addc_u32 s101, s101, 0
	s_waitcnt vmcnt(8)
	v_add_f32_e32 v96, v96, v128
	v_mul_f32_e32 v96, 0xbfb8aa3b, v96
	v_exp_f32_e32 v96, v96
	s_nop 0
	v_add_f32_e32 v96, 1.0, v96
	v_rcp_f32_e32 v96, v96
	v_lshlrev_b32_e32 v246, 16, v224
	v_mul_f32_e32 v96, v246, v96
	v_add_f32_e32 v97, v97, v129
	v_mul_f32_e32 v97, 0xbfb8aa3b, v97
	v_exp_f32_e32 v97, v97
	s_nop 0
	v_add_f32_e32 v97, 1.0, v97
	v_rcp_f32_e32 v97, v97
	v_and_b32_e32 v246, 0xffff0000, v224
	v_mul_f32_e32 v97, v246, v97
	v_add_f32_e32 v98, v98, v130
	v_mul_f32_e32 v98, 0xbfb8aa3b, v98
	v_exp_f32_e32 v98, v98
	s_nop 0
	v_add_f32_e32 v98, 1.0, v98
	v_rcp_f32_e32 v98, v98
	v_lshlrev_b32_e32 v246, 16, v225
	v_mul_f32_e32 v98, v246, v98
	v_add_f32_e32 v99, v99, v131
	v_mul_f32_e32 v99, 0xbfb8aa3b, v99
	v_exp_f32_e32 v99, v99
	s_nop 0
	v_add_f32_e32 v99, 1.0, v99
	v_rcp_f32_e32 v99, v99
	v_and_b32_e32 v246, 0xffff0000, v225
	v_mul_f32_e32 v99, v246, v99
	v_add_f32_e32 v100, v100, v132
	v_mul_f32_e32 v100, 0xbfb8aa3b, v100
	v_exp_f32_e32 v100, v100
	s_nop 0
	v_add_f32_e32 v100, 1.0, v100
	v_rcp_f32_e32 v100, v100
	v_lshlrev_b32_e32 v246, 16, v226
	v_mul_f32_e32 v100, v246, v100
	v_add_f32_e32 v101, v101, v133
	v_mul_f32_e32 v101, 0xbfb8aa3b, v101
	v_exp_f32_e32 v101, v101
	s_nop 0
	v_add_f32_e32 v101, 1.0, v101
	v_rcp_f32_e32 v101, v101
	v_and_b32_e32 v246, 0xffff0000, v226
	v_mul_f32_e32 v101, v246, v101
	v_add_f32_e32 v102, v102, v134
	v_mul_f32_e32 v102, 0xbfb8aa3b, v102
	v_exp_f32_e32 v102, v102
	s_nop 0
	v_add_f32_e32 v102, 1.0, v102
	v_rcp_f32_e32 v102, v102
	v_lshlrev_b32_e32 v246, 16, v227
	v_mul_f32_e32 v102, v246, v102
	v_add_f32_e32 v103, v103, v135
	v_mul_f32_e32 v103, 0xbfb8aa3b, v103
	v_exp_f32_e32 v103, v103
	s_nop 0
	v_add_f32_e32 v103, 1.0, v103
	v_rcp_f32_e32 v103, v103
	v_and_b32_e32 v246, 0xffff0000, v227
	v_mul_f32_e32 v103, v246, v103
	v_add_f32_e32 v104, v104, v136
	v_mul_f32_e32 v104, 0xbfb8aa3b, v104
	v_exp_f32_e32 v104, v104
	s_nop 0
	v_add_f32_e32 v104, 1.0, v104
	v_rcp_f32_e32 v104, v104
	v_lshlrev_b32_e32 v246, 16, v228
	v_mul_f32_e32 v104, v246, v104
	v_add_f32_e32 v105, v105, v137
	v_mul_f32_e32 v105, 0xbfb8aa3b, v105
	v_exp_f32_e32 v105, v105
	s_nop 0
	v_add_f32_e32 v105, 1.0, v105
	v_rcp_f32_e32 v105, v105
	v_and_b32_e32 v246, 0xffff0000, v228
	v_mul_f32_e32 v105, v246, v105
	v_add_f32_e32 v106, v106, v138
	v_mul_f32_e32 v106, 0xbfb8aa3b, v106
	v_exp_f32_e32 v106, v106
	s_nop 0
	v_add_f32_e32 v106, 1.0, v106
	v_rcp_f32_e32 v106, v106
	v_lshlrev_b32_e32 v246, 16, v229
; DI float bf2f(unsigned h) { return __uint_as_float(h << 16); }
; DI int crow(int r, int hf) { return (r & 3) + 8 * (r >> 2) + 4 * hf; }
; DI void glu_phase(const Params& p, int j, char* smem) {
;     ...
;       int l32_ = l32, hf_ = hf; asm volatile("" : "+v"(l32_), "+v"(hf_));
; #pragma unroll
;       for (int i = 0; i < 2; ++i)
; #pragma unroll
;         for (int jn = 0; jn < 2; ++jn)
; #pragma unroll
;           for (int r = 0; r < 16; ++r) {
;             const int row = m0_ + wm * 64 + i * 32 + crow(r, hf_), col = n0 + wn * 64 + jn * 32 + l32_;
;             const float gt = acc[i][jn][r] + gb[col];
;             const float y = bf2f(yt[(size_t)row * LDYT + col]);
;             o[(size_t)row * LDH + 512 + col] = f2bf(y / (1.f + __expf(-gt)));
;           }
	v_mul_f32_e32 v106, v246, v106
	v_add_f32_e32 v107, v107, v139
	v_mul_f32_e32 v107, 0xbfb8aa3b, v107
	v_exp_f32_e32 v107, v107
	s_nop 0
	v_add_f32_e32 v107, 1.0, v107
	v_rcp_f32_e32 v107, v107
	v_and_b32_e32 v246, 0xffff0000, v229
	v_mul_f32_e32 v107, v246, v107
	v_add_f32_e32 v108, v108, v140
	v_mul_f32_e32 v108, 0xbfb8aa3b, v108
	v_exp_f32_e32 v108, v108
	s_nop 0
	v_add_f32_e32 v108, 1.0, v108
	v_rcp_f32_e32 v108, v108
	v_lshlrev_b32_e32 v246, 16, v230
	v_mul_f32_e32 v108, v246, v108
	v_add_f32_e32 v109, v109, v141
	v_mul_f32_e32 v109, 0xbfb8aa3b, v109
	v_exp_f32_e32 v109, v109
	s_nop 0
	v_add_f32_e32 v109, 1.0, v109
	v_rcp_f32_e32 v109, v109
	v_and_b32_e32 v246, 0xffff0000, v230
	v_mul_f32_e32 v109, v246, v109
	v_add_f32_e32 v110, v110, v142
	v_mul_f32_e32 v110, 0xbfb8aa3b, v110
	v_exp_f32_e32 v110, v110
	s_nop 0
	v_add_f32_e32 v110, 1.0, v110
	v_rcp_f32_e32 v110, v110
	v_lshlrev_b32_e32 v246, 16, v231
	v_mul_f32_e32 v110, v246, v110
	v_add_f32_e32 v111, v111, v143
	v_mul_f32_e32 v111, 0xbfb8aa3b, v111
	v_exp_f32_e32 v111, v111
	s_nop 0
	v_add_f32_e32 v111, 1.0, v111
	v_rcp_f32_e32 v111, v111
	v_and_b32_e32 v246, 0xffff0000, v231
	v_mul_f32_e32 v111, v246, v111
	v_add_f32_e32 v112, v112, v144
	v_mul_f32_e32 v112, 0xbfb8aa3b, v112
	v_exp_f32_e32 v112, v112
	s_nop 0
	v_add_f32_e32 v112, 1.0, v112
	v_rcp_f32_e32 v112, v112
	v_lshlrev_b32_e32 v246, 16, v232
	v_mul_f32_e32 v112, v246, v112
	v_add_f32_e32 v113, v113, v145
	v_mul_f32_e32 v113, 0xbfb8aa3b, v113
	v_exp_f32_e32 v113, v113
	s_nop 0
	v_add_f32_e32 v113, 1.0, v113
	v_rcp_f32_e32 v113, v113
	v_and_b32_e32 v246, 0xffff0000, v232
	v_mul_f32_e32 v113, v246, v113
	v_add_f32_e32 v114, v114, v146
	v_mul_f32_e32 v114, 0xbfb8aa3b, v114
	v_exp_f32_e32 v114, v114
	s_nop 0
	v_add_f32_e32 v114, 1.0, v114
	v_rcp_f32_e32 v114, v114
	v_lshlrev_b32_e32 v246, 16, v233
	v_mul_f32_e32 v114, v246, v114
	v_add_f32_e32 v115, v115, v147
	v_mul_f32_e32 v115, 0xbfb8aa3b, v115
	v_exp_f32_e32 v115, v115
	s_nop 0
	v_add_f32_e32 v115, 1.0, v115
	v_rcp_f32_e32 v115, v115
	v_and_b32_e32 v246, 0xffff0000, v233
	v_mul_f32_e32 v115, v246, v115
	v_add_f32_e32 v116, v116, v148
	v_mul_f32_e32 v116, 0xbfb8aa3b, v116
	v_exp_f32_e32 v116, v116
	s_nop 0
	v_add_f32_e32 v116, 1.0, v116
	v_rcp_f32_e32 v116, v116
	v_lshlrev_b32_e32 v246, 16, v234
	v_mul_f32_e32 v116, v246, v116
	v_add_f32_e32 v117, v117, v149
	v_mul_f32_e32 v117, 0xbfb8aa3b, v117
	v_exp_f32_e32 v117, v117
	s_nop 0
	v_add_f32_e32 v117, 1.0, v117
	v_rcp_f32_e32 v117, v117
	v_and_b32_e32 v246, 0xffff0000, v234
	v_mul_f32_e32 v117, v246, v117
	v_add_f32_e32 v118, v118, v150
	v_mul_f32_e32 v118, 0xbfb8aa3b, v118
	v_exp_f32_e32 v118, v118
	s_nop 0
	v_add_f32_e32 v118, 1.0, v118
	v_rcp_f32_e32 v118, v118
	v_lshlrev_b32_e32 v246, 16, v235
	v_mul_f32_e32 v118, v246, v118
	v_add_f32_e32 v119, v119, v151
	v_mul_f32_e32 v119, 0xbfb8aa3b, v119
	v_exp_f32_e32 v119, v119
	s_nop 0
	v_add_f32_e32 v119, 1.0, v119
	v_rcp_f32_e32 v119, v119
	v_and_b32_e32 v246, 0xffff0000, v235
	v_mul_f32_e32 v119, v246, v119
	v_add_f32_e32 v120, v120, v152
	v_mul_f32_e32 v120, 0xbfb8aa3b, v120
	v_exp_f32_e32 v120, v120
	s_nop 0
	v_add_f32_e32 v120, 1.0, v120
	v_rcp_f32_e32 v120, v120
	v_lshlrev_b32_e32 v246, 16, v236
	v_mul_f32_e32 v120, v246, v120
	v_add_f32_e32 v121, v121, v153
	v_mul_f32_e32 v121, 0xbfb8aa3b, v121
	v_exp_f32_e32 v121, v121
	s_nop 0
	v_add_f32_e32 v121, 1.0, v121
	v_rcp_f32_e32 v121, v121
	v_and_b32_e32 v246, 0xffff0000, v236
	v_mul_f32_e32 v121, v246, v121
	v_add_f32_e32 v122, v122, v154
	v_mul_f32_e32 v122, 0xbfb8aa3b, v122
	v_exp_f32_e32 v122, v122
	s_nop 0
	v_add_f32_e32 v122, 1.0, v122
	v_rcp_f32_e32 v122, v122
	v_lshlrev_b32_e32 v246, 16, v237
	v_mul_f32_e32 v122, v246, v122
	v_add_f32_e32 v123, v123, v155
	v_mul_f32_e32 v123, 0xbfb8aa3b, v123
	v_exp_f32_e32 v123, v123
	s_nop 0
	v_add_f32_e32 v123, 1.0, v123
	v_rcp_f32_e32 v123, v123
	v_and_b32_e32 v246, 0xffff0000, v237
	v_mul_f32_e32 v123, v246, v123
	v_add_f32_e32 v124, v124, v156
	v_mul_f32_e32 v124, 0xbfb8aa3b, v124
	v_exp_f32_e32 v124, v124
	s_nop 0
	v_add_f32_e32 v124, 1.0, v124
	v_rcp_f32_e32 v124, v124
	v_lshlrev_b32_e32 v246, 16, v238
	v_mul_f32_e32 v124, v246, v124
	v_add_f32_e32 v125, v125, v157
	v_mul_f32_e32 v125, 0xbfb8aa3b, v125
	v_exp_f32_e32 v125, v125
	s_nop 0
	v_add_f32_e32 v125, 1.0, v125
	v_rcp_f32_e32 v125, v125
	v_and_b32_e32 v246, 0xffff0000, v238
	v_mul_f32_e32 v125, v246, v125
	v_add_f32_e32 v126, v126, v158
	v_mul_f32_e32 v126, 0xbfb8aa3b, v126
	v_exp_f32_e32 v126, v126
	s_nop 0
	v_add_f32_e32 v126, 1.0, v126
	v_rcp_f32_e32 v126, v126
	v_lshlrev_b32_e32 v246, 16, v239
	v_mul_f32_e32 v126, v246, v126
	v_add_f32_e32 v127, v127, v159
	v_mul_f32_e32 v127, 0xbfb8aa3b, v127
	v_exp_f32_e32 v127, v127
	s_nop 0
	v_add_f32_e32 v127, 1.0, v127
	v_rcp_f32_e32 v127, v127
	v_and_b32_e32 v246, 0xffff0000, v239
	v_mul_f32_e32 v127, v246, v127
	v_cvt_pk_bf16_f32 v240, v96, v97
	v_cvt_pk_bf16_f32 v241, v98, v99
	ds_write_b64 v178, v[240:241]
	v_cvt_pk_bf16_f32 v242, v100, v101
	v_cvt_pk_bf16_f32 v243, v102, v103
	ds_write_b64 v179, v[242:243]
	v_cvt_pk_bf16_f32 v244, v104, v105
	v_cvt_pk_bf16_f32 v245, v106, v107
	ds_write_b64 v180, v[244:245]
	v_cvt_pk_bf16_f32 v240, v108, v109
	v_cvt_pk_bf16_f32 v241, v110, v111
	ds_write_b64 v181, v[240:241]
	v_cvt_pk_bf16_f32 v242, v112, v113
	v_cvt_pk_bf16_f32 v243, v114, v115
	ds_write_b64 v188, v[242:243]
	v_cvt_pk_bf16_f32 v244, v116, v117
	v_cvt_pk_bf16_f32 v245, v118, v119
	ds_write_b64 v189, v[244:245]
	v_cvt_pk_bf16_f32 v240, v120, v121
	v_cvt_pk_bf16_f32 v241, v122, v123
	ds_write_b64 v190, v[240:241]
	v_cvt_pk_bf16_f32 v242, v124, v125
	v_cvt_pk_bf16_f32 v243, v126, v127
	ds_write_b64 v191, v[242:243]
	ds_read_b128 v[96:99], v194
	ds_read_b128 v[100:103], v194 offset:1024
	ds_read_b128 v[104:107], v194 offset:2048
	ds_read_b128 v[108:111], v194 offset:3072
	s_waitcnt lgkmcnt(12)
; DI float bf2f(unsigned h) { return __uint_as_float(h << 16); }
; DI int crow(int r, int hf) { return (r & 3) + 8 * (r >> 2) + 4 * hf; }
; DI void glu_phase(const Params& p, int j, char* smem) {
;     ...
; #pragma unroll
;       for (int i = 0; i < 2; ++i)
; #pragma unroll
;         for (int jn = 0; jn < 2; ++jn)
; #pragma unroll
;           for (int r = 0; r < 16; ++r) {
;             const int row = m0_ + wm * 64 + i * 32 + crow(r, hf_), col = n0 + wn * 64 + jn * 32 + l32_;
;             const float gt = acc[i][jn][r] + gb[col];
;             const float y = bf2f(yt[(size_t)row * LDYT + col]);
;             o[(size_t)row * LDH + 512 + col] = f2bf(y / (1.f + __expf(-gt)));
;           }
	global_store_dwordx4 v195, v[64:67], s[100:101] nt
	s_add_u32 s100, s100, 0x4400
	s_addc_u32 s101, s101, 0
	global_store_dwordx4 v195, v[68:71], s[100:101] nt
	s_add_u32 s100, s100, 0x4400
	s_addc_u32 s101, s101, 0
	global_store_dwordx4 v195, v[72:75], s[100:101] nt
	s_add_u32 s100, s100, 0x4400
	s_addc_u32 s101, s101, 0
	global_store_dwordx4 v195, v[76:79], s[100:101] nt
	s_add_u32 s100, s100, 0x4400
	s_addc_u32 s101, s101, 0
	s_waitcnt lgkmcnt(0)
	global_store_dwordx4 v195, v[96:99], s[100:101] nt
	s_add_u32 s100, s100, 0x4400
	s_addc_u32 s101, s101, 0
	global_store_dwordx4 v195, v[100:103], s[100:101] nt
	s_add_u32 s100, s100, 0x4400
	s_addc_u32 s101, s101, 0
	global_store_dwordx4 v195, v[104:107], s[100:101] nt
	s_add_u32 s100, s100, 0x4400
	s_addc_u32 s101, s101, 0
	global_store_dwordx4 v195, v[108:111], s[100:101] nt
	s_waitcnt lgkmcnt(0)
	s_add_u32 m0, s14, 0x18000
	s_nop 0
	global_load_lds_dwordx4 v220, s[24:25]
	s_add_u32 m0, s14, 0x18400
	s_nop 0
	global_load_lds_dwordx4 v221, s[24:25]
	s_add_u32 m0, s14, 0x18800
	s_nop 0
	global_load_lds_dwordx4 v222, s[24:25]
	s_add_u32 m0, s14, 0x18c00
	s_nop 0
	global_load_lds_dwordx4 v223, s[24:25]
	s_add_u32 s22, s22, 0x80
	s_addc_u32 s23, s23, 0
	s_add_u32 s24, s24, 0x80
	s_addc_u32 s25, s25, 0
	s_add_u32 s26, s26, 1
	s_cmp_eq_u32 s26, 8
	s_cbranch_scc0 .Lgl8_cadv_done
	s_mov_b32 s26, 0
	s_add_u32 s27, s27, s30
	s_cmp_lt_u32 s27, 0x20
	s_cbranch_scc1 .Lgl8_cadv_new
	s_sub_u32 s22, s22, 0x400
	s_subb_u32 s23, s23, 0
	s_sub_u32 s24, s24, 0x400
	s_subb_u32 s25, s25, 0
	s_branch .Lgl8_cadv_done

; #define RAWBAR() { asm volatile("s_waitcnt vmcnt(0) lgkmcnt(0)" ::: "memory"); __builtin_amdgcn_s_barrier(); }
;     ...
;   if (V != 1) GLDS(0, 0);
;   RAWBAR();
;   for (int kt = 0; kt < nk; kt += 2) {
; DI void glu_phase(const Params& p, int j, char* smem) {
;     ...
;   for (int lt = blockIdx.x >> 3; lt < 16 * nN; lt += gridDim.x >> 3) {
;     int mt, nt; tile_map(lt, 16, nN, 16, 2, mt, nt);
;     const int m0 = mt * 256, n0 = nt * 256;
;     gemm_tile(yt + (size_t)m0 * LDYT, LDYT, 8, nullptr, 0, 0, Wt + (size_t)n0 * LDGLU, LDGLU, smem, [&](f32x16(&acc)[2][2], int moff) {
.Lgl8_cadv_done:
	ds_read_b128 v[128:131], v204
	ds_read_b128 v[132:135], v204 offset:4096
	ds_read_b128 v[136:139], v204 offset:8192
	ds_read_b128 v[140:143], v204 offset:12288
	ds_read_b128 v[162:165], v212
	ds_read_b128 v[166:169], v212 offset:4096
	ds_read_b128 v[144:147], v205
	ds_read_b128 v[148:151], v205 offset:4096
	ds_read_b128 v[152:155], v205 offset:8192
	ds_read_b128 v[156:159], v205 offset:12288
	ds_read_b128 v[170:173], v213
	ds_read_b128 v[174:177], v213 offset:4096
	s_add_u32 s28, s28, s30
	s_cmp_lt_u32 s28, 0x20
	s_cbranch_scc1 .Lgl_tile
	s_waitcnt vmcnt(0) lgkmcnt(0)

; DI int opqv(int x) { asm volatile("" : "+v"(x)); return x; }
; DI char* opq(char* p) { asm volatile("" : "+s"(p)); return p; }
; DI void ln_phase(const Params& p, int ls) {
;   const int tid = opqv(threadIdx.x), lane = tid & 63, w = tid >> 6;
;   char* ws = opq(p.ws);
;   const float* mod = (const float*)(ws + OFF_MOD);
;   u16* hy = (u16*)(ws + OFF_HY);
;   const float* xin = (ls == 0) ? p.x : p.out;
;   const float* lg = p.ln_g + ls * 1024; const float* lb = p.ln_b + ls * 1024;
;   const int stride = gridDim.x * 8;
;   f32x4 xc[4], xn[4]; uint2 yc[4], yn[4];
;   {
;     const int row = blockIdx.x * 8 + w;
; #pragma unroll
;     for (int i = 0; i < 4; ++i) {
;       const int col = lane * 4 + 256 * i;
;       xc[i] = __builtin_nontemporal_load((const f32x4*)(xin + (size_t)row * 1024 + col));
;       yc[i] = *(const uint2*)(hy + (size_t)row * LDH + col);
;     }
;   }
;   for (int row = blockIdx.x * 8 + w; row < T_; row += stride) {
;     const int b = row >> 14;
;     const float* gate = mod + (ls * 2 + b) * 3072 + 2048;
;     const int rn = row + stride;
;     if (rn < T_) {
; #pragma unroll
;       for (int i = 0; i < 4; ++i) {
;         const int col = lane * 4 + 256 * i;
;         xn[i] = __builtin_nontemporal_load((const f32x4*)(xin + (size_t)rn * 1024 + col));
;         yn[i] = *(const uint2*)(hy + (size_t)rn * LDH + col);
;       }
;     }
.LBB0_847:
	s_andn2_b64 vcc, exec, s[4:5]
	v_readlane_b32 s27, v254, 34
	s_cbranch_vccnz .LBB0_862
	s_waitcnt lgkmcnt(0)
	v_mov_b32_e32 v1, v182
	v_readlane_b32 s0, v253, 52
	v_ashrrev_i32_e32 v0, 6, v1
	v_readlane_b32 s6, v251, 13
	v_add_u32_e32 v62, s0, v0
	s_mov_b32 s0, 0x8000
	v_readlane_b32 s7, v251, 14
	v_cmp_gt_i32_e32 vcc, s0, v62
	s_and_saveexec_b64 s[8:9], vcc
	s_cbranch_execz .LBB0_861
	v_readlane_b32 s22, v254, 33
	v_readlane_b32 s24, v251, 1
	s_mov_b64 s[10:11], s[62:63]
	v_readlane_b32 s52, v251, 19
	v_readlane_b32 s0, v253, 58
	s_cmp_eq_u32 s22, 0
	v_readlane_b32 s30, v251, 7
	v_readlane_b32 s31, v251, 8
	v_readlane_b32 s53, v251, 20
	v_readlane_b32 s1, v253, 59
	s_mov_b32 s20, s0
	s_cselect_b32 s1, s53, s31
	s_cselect_b32 s0, s52, s30
	s_mov_b64 s[4:5], 0x8c04100
	s_mov_b32 s4, 0x8c04000
	s_lshl_b32 s4, s22, 10
	s_ashr_i32 s5, s4, 31
	v_readlane_b32 s62, v251, 29
	s_lshl_b64 s[4:5], s[4:5], 2
	v_readlane_b32 s63, v251, 30
	s_add_u32 s12, s62, s4
	v_readlane_b32 s60, v251, 27
	s_addc_u32 s13, s63, s5
	v_readlane_b32 s61, v251, 28
	s_add_u32 s4, s60, s4
	s_addc_u32 s5, s61, s5
	v_readlane_b32 s4, v253, 53
	v_readlane_b32 s25, v251, 2
	v_readlane_b32 s28, v251, 5
	v_readlane_b32 s29, v251, 6
	s_lshl_b32 s14, s22, 1
	v_readlane_b32 s26, v251, 3
	v_readlane_b32 s27, v251, 4
	v_readlane_b32 s64, v251, 31
	v_readlane_b32 s65, v251, 32
	v_readlane_b32 s66, v251, 33
	v_readlane_b32 s67, v251, 34
	v_readlane_b32 s28, v253, 60
	v_readlane_b32 s24, v253, 41
	s_cmp_lt_i32 s22, 7
	v_readlane_b32 s27, v254, 34
	s_mov_b32 s34, 0x3fd744fd
	s_mov_b64 s[64:65], 0x80
	v_readlane_b32 s29, v253, 61
	s_movk_i32 s67, 0x1ff
	s_movk_i32 s66, 0x60
	s_mov_b32 s26, 0x8000
	s_mov_b32 s15, 0x800000
	v_readlane_b32 s25, v253, 42
	s_mov_b64 s[62:63], s[10:11]
	s_cselect_b64 s[10:11], -1, 0
	s_mov_b64 s[12:13], 0
	v_readlane_b32 s54, v251, 21
	v_readlane_b32 s55, v251, 22
	v_readlane_b32 s56, v251, 23
	v_readlane_b32 s57, v251, 24
	v_readlane_b32 s58, v251, 25
	v_readlane_b32 s59, v251, 26
	s_nop 4
	s_mov_b64 s[12:13], s[0:1]
	v_and_b32_e32 v1, 63, v182
	v_lshlrev_b32_e32 v160, 4, v1
	v_lshlrev_b32_e32 v236, 3, v1
	v_readfirstlane_b32 s100, v62
	s_mov_b32 s101, 0
	s_nop 0
	s_lshl_b32 s0, s100, 12
	s_add_u32 s0, s12, s0
	s_addc_u32 s1, s13, 0
	global_load_dwordx4 v[0:3], v160, s[0:1] nt
	global_load_dwordx4 v[4:7], v160, s[0:1] offset:1024 nt
	global_load_dwordx4 v[8:11], v160, s[0:1] offset:2048 nt
	global_load_dwordx4 v[12:15], v160, s[0:1] offset:3072 nt
	s_mul_i32 s0, s100, 0x880
	s_add_u32 s0, s6, s0
	s_addc_u32 s1, s7, 0
	s_add_u32 s0, s0, 0x8c04100
	s_addc_u32 s1, s1, 0
	global_load_dwordx2 v[48:49], v236, s[0:1]
	global_load_dwordx2 v[50:51], v236, s[0:1] offset:512
	global_load_dwordx2 v[52:53], v236, s[0:1] offset:1024
	global_load_dwordx2 v[54:55], v236, s[0:1] offset:1536
	s_mov_b32 s4, s100
	s_add_i32 s4, s4, s20
	s_cmp_lt_u32 s4, 0x8000
	s_cbranch_scc0 .Lln_no1
	s_lshl_b32 s0, s4, 12
	s_add_u32 s0, s12, s0
	s_addc_u32 s1, s13, 0
	global_load_dwordx4 v[16:19], v160, s[0:1] nt
	global_load_dwordx4 v[20:23], v160, s[0:1] offset:1024 nt
	global_load_dwordx4 v[24:27], v160, s[0:1] offset:2048 nt
	global_load_dwordx4 v[28:31], v160, s[0:1] offset:3072 nt
	s_mul_i32 s0, s4, 0x880
	s_add_u32 s0, s6, s0
	s_addc_u32 s1, s7, 0
	s_add_u32 s0, s0, 0x8c04100
	s_addc_u32 s1, s1, 0
	global_load_dwordx2 v[56:57], v236, s[0:1]
	global_load_dwordx2 v[58:59], v236, s[0:1] offset:512
	global_load_dwordx2 v[60:61], v236, s[0:1] offset:1024
	global_load_dwordx2 v[62:63], v236, s[0:1] offset:1536

; DI float bf2f(unsigned h) { return __uint_as_float(h << 16); }
; DI void ln_phase(const Params& p, int ls) {
;     ...
;   for (int row = blockIdx.x * 8 + w; row < T_; row += stride) {
;     const int b = row >> 14;
;     const float* gate = mod + (ls * 2 + b) * 3072 + 2048;
;     const int rn = row + stride;
;     if (rn < T_) {
; #pragma unroll
;       for (int i = 0; i < 4; ++i) {
;         const int col = lane * 4 + 256 * i;
;         xn[i] = __builtin_nontemporal_load((const f32x4*)(xin + (size_t)rn * 1024 + col));
;         yn[i] = *(const uint2*)(hy + (size_t)rn * LDH + col);
;       }
;     }
;     float v[16];
;     float sum = 0.f;
; #pragma unroll
;     for (int i = 0; i < 4; ++i) {
;       const int col = lane * 4 + 256 * i;
;       const f32x4 xv = xc[i];
;       const uint2 yv = yc[i];
;       const float4 g = *(const float4*)(gate + col);
;       v[4 * i + 0] = DN_ALPHA * xv.x + (1.f + g.x) * bf2f(yv.x & 0xffffu);
;       v[4 * i + 1] = DN_ALPHA * xv.y + (1.f + g.y) * bf2f(yv.x >> 16);
;       v[4 * i + 2] = DN_ALPHA * xv.z + (1.f + g.z) * bf2f(yv.y & 0xffffu);
;       v[4 * i + 3] = DN_ALPHA * xv.w + (1.f + g.w) * bf2f(yv.y >> 16);
;       sum += v[4 * i] + v[4 * i + 1] + v[4 * i + 2] + v[4 * i + 3];
;     }
; #pragma unroll
;     for (int m = 32; m >= 1; m >>= 1) sum += __shfl_xor(sum, m);
;     const float mean = sum * (1.f / 1024.f);
;     float vs = 0.f;
; #pragma unroll
;     for (int i = 0; i < 16; ++i) { const float d = v[i] - mean; vs += d * d; }
; #pragma unroll
;     for (int m = 32; m >= 1; m >>= 1) vs += __shfl_xor(vs, m);
;     const float rstd = rsqrtf(vs * (1.f / 1024.f) + 1e-5f);
; #pragma unroll
;     for (int i = 0; i < 4; ++i) {
;       const int col = lane * 4 + 256 * i;
;       const float4 g = *(const float4*)(lg + col); const float4 bb = *(const float4*)(lb + col);
;       float4 o;
;       o.x = (v[4 * i + 0] - mean) * rstd * g.x + bb.x; o.y = (v[4 * i + 1] - mean) * rstd * g.y + bb.y;
;       o.z = (v[4 * i + 2] - mean) * rstd * g.z + bb.z; o.w = (v[4 * i + 3] - mean) * rstd * g.w + bb.w;
;       { f32x4 ov = {o.x, o.y, o.z, o.w}; __builtin_nontemporal_store(ov, (f32x4*)(p.out + (size_t)row * 1024 + col)); }
;       if (ls < 7) {
;         const float* m2 = mod + ((ls + 1) * 2 + b) * 3072;
;         const float4 sh = *(const float4*)(m2 + col); const float4 sc = *(const float4*)(m2 + 1024 + col);
.Lln_pskip_init:
	v_readlane_b32 s0, v251, 27
	v_readlane_b32 s1, v251, 28
	s_lshl_b32 s4, s22, 12
	s_add_u32 s0, s0, s4
	s_addc_u32 s1, s1, 0
	global_load_dwordx4 v[116:119], v160, s[0:1]
	global_load_dwordx4 v[120:123], v160, s[0:1] offset:1024
	global_load_dwordx4 v[124:127], v160, s[0:1] offset:2048
	global_load_dwordx4 v[128:131], v160, s[0:1] offset:3072
	v_readlane_b32 s0, v251, 29
	v_readlane_b32 s1, v251, 30
	s_add_u32 s0, s0, s4
	s_addc_u32 s1, s1, 0
	global_load_dwordx4 v[132:135], v160, s[0:1]
	global_load_dwordx4 v[136:139], v160, s[0:1] offset:1024
	global_load_dwordx4 v[140:143], v160, s[0:1] offset:2048
	global_load_dwordx4 v[144:147], v160, s[0:1] offset:3072
	s_lshr_b32 s0, s100, 14
	s_cmp_eq_u32 s0, 0
	s_cbranch_scc0 .Lln_noalt
	s_add_i32 s0, s14, 1
	s_mul_i32 s0, s0, 0x3000
	s_add_u32 s0, s6, s0
	s_addc_u32 s1, s7, 0
	s_add_u32 s4, s0, 0x2000
	s_addc_u32 s5, s1, 0
	global_load_dwordx4 v[72:75], v160, s[4:5]
	global_load_dwordx4 v[76:79], v160, s[4:5] offset:1024
	global_load_dwordx4 v[80:83], v160, s[4:5] offset:2048
	global_load_dwordx4 v[84:87], v160, s[4:5] offset:3072
	s_cmp_lt_i32 s22, 7
	s_cbranch_scc0 .Lln_noalt
	s_add_u32 s0, s0, 0x6000
	s_addc_u32 s1, s1, 0
	s_add_u32 s4, s0, 0x1000
	s_addc_u32 s5, s1, 0
	global_load_dwordx4 v[88:91], v160, s[0:1]
	global_load_dwordx4 v[92:95], v160, s[0:1] offset:1024
	global_load_dwordx4 v[96:99], v160, s[0:1] offset:2048
	global_load_dwordx4 v[148:151], v160, s[0:1] offset:3072
	global_load_dwordx4 v[152:155], v160, s[4:5]
	global_load_dwordx4 v[156:159], v160, s[4:5] offset:1024
	global_load_dwordx4 v[194:197], v160, s[4:5] offset:2048
	global_load_dwordx2 v[162:163], v160, s[4:5] offset:3072
	global_load_dwordx2 v[190:191], v160, s[4:5] offset:3080
.Lln_noalt:
	s_waitcnt vmcnt(0)
	v_add_f32_e32 v72, 1.0, v72
	v_add_f32_e32 v73, 1.0, v73
	v_add_f32_e32 v74, 1.0, v74
	v_add_f32_e32 v75, 1.0, v75
	v_add_f32_e32 v76, 1.0, v76
	v_add_f32_e32 v77, 1.0, v77
	v_add_f32_e32 v78, 1.0, v78
	v_add_f32_e32 v79, 1.0, v79
	v_add_f32_e32 v80, 1.0, v80
	v_add_f32_e32 v81, 1.0, v81
	v_add_f32_e32 v82, 1.0, v82
	v_add_f32_e32 v83, 1.0, v83
	v_add_f32_e32 v84, 1.0, v84
	v_add_f32_e32 v85, 1.0, v85
	v_add_f32_e32 v86, 1.0, v86
	v_add_f32_e32 v87, 1.0, v87
	v_add_f32_e32 v152, 1.0, v152
	v_add_f32_e32 v153, 1.0, v153
	v_add_f32_e32 v154, 1.0, v154
	v_add_f32_e32 v155, 1.0, v155
	v_add_f32_e32 v156, 1.0, v156
	v_add_f32_e32 v157, 1.0, v157
	v_add_f32_e32 v158, 1.0, v158
	v_add_f32_e32 v159, 1.0, v159
	v_add_f32_e32 v194, 1.0, v194
	v_add_f32_e32 v195, 1.0, v195
	v_add_f32_e32 v196, 1.0, v196
	v_add_f32_e32 v197, 1.0, v197
	v_add_f32_e32 v162, 1.0, v162
	v_add_f32_e32 v163, 1.0, v163
	v_add_f32_e32 v190, 1.0, v190
	v_add_f32_e32 v191, 1.0, v191
	v_add_f32_e32 v100, 1.0, v100
	v_add_f32_e32 v101, 1.0, v101
	v_add_f32_e32 v102, 1.0, v102
	v_add_f32_e32 v103, 1.0, v103
	v_add_f32_e32 v104, 1.0, v104
	v_add_f32_e32 v105, 1.0, v105
	v_add_f32_e32 v106, 1.0, v106
	v_add_f32_e32 v107, 1.0, v107
	v_add_f32_e32 v108, 1.0, v108
	v_add_f32_e32 v109, 1.0, v109
	v_add_f32_e32 v110, 1.0, v110
	v_add_f32_e32 v111, 1.0, v111
	v_add_f32_e32 v112, 1.0, v112
	v_add_f32_e32 v113, 1.0, v113
	v_add_f32_e32 v114, 1.0, v114
	v_add_f32_e32 v115, 1.0, v115
	s_cmp_lt_i32 s22, 7
	s_cbranch_scc0 .Lln_pskip2_init
	v_add_f32_e32 v204, 1.0, v204
	v_add_f32_e32 v205, 1.0, v205
	v_add_f32_e32 v206, 1.0, v206
	v_add_f32_e32 v207, 1.0, v207
	v_add_f32_e32 v208, 1.0, v208
	v_add_f32_e32 v209, 1.0, v209
	v_add_f32_e32 v210, 1.0, v210
	v_add_f32_e32 v211, 1.0, v211
	v_add_f32_e32 v212, 1.0, v212
	v_add_f32_e32 v213, 1.0, v213
	v_add_f32_e32 v214, 1.0, v214
	v_add_f32_e32 v215, 1.0, v215
	v_add_f32_e32 v216, 1.0, v216
	v_add_f32_e32 v217, 1.0, v217
	v_add_f32_e32 v218, 1.0, v218
	v_add_f32_e32 v219, 1.0, v219
.Lln_pskip2_init:
.Lln_it0:
	s_mul_i32 s4, s20, 2
	s_add_i32 s4, s100, s4
	s_cmp_lt_u32 s4, 0x8000
	s_cbranch_scc0 .Lln_nopf0
	s_lshl_b32 s0, s4, 12
	s_add_u32 s0, s12, s0
	s_addc_u32 s1, s13, 0
	global_load_dwordx4 v[32:35], v160, s[0:1] nt
	global_load_dwordx4 v[36:39], v160, s[0:1] offset:1024 nt
	global_load_dwordx4 v[40:43], v160, s[0:1] offset:2048 nt
	global_load_dwordx4 v[44:47], v160, s[0:1] offset:3072 nt
	s_mul_i32 s0, s4, 0x880
	s_add_u32 s0, s6, s0
	s_addc_u32 s1, s7, 0
	s_add_u32 s0, s0, 0x8c04100
	s_addc_u32 s1, s1, 0
	global_load_dwordx2 v[64:65], v236, s[0:1]
	global_load_dwordx2 v[66:67], v236, s[0:1] offset:512
	global_load_dwordx2 v[68:69], v236, s[0:1] offset:1024
	global_load_dwordx2 v[70:71], v236, s[0:1] offset:1536
.Lln_nopf0:
	s_mov_b32 s5, 0
	s_mov_b32 s4, s100
	s_add_i32 s4, s4, s20
	s_cmp_lt_u32 s4, 0x8000
	s_cselect_b32 s0, 1, 0
	s_add_i32 s5, s5, s0
	s_add_i32 s4, s4, s20
	s_cmp_lt_u32 s4, 0x8000
	s_cselect_b32 s0, 1, 0
	s_add_i32 s5, s5, s0
	s_lshr_b32 s1, s101, 1
	s_cmp_lt_i32 s22, 7
	s_cselect_b32 s0, s101, s1
	s_add_i32 s5, s5, s0
	s_cmp_eq_u32 s5, 4
	s_cbranch_scc1 .Lln_w32_0
	s_cmp_eq_u32 s5, 3
	s_cbranch_scc1 .Lln_w24_0
	s_cmp_eq_u32 s5, 2
	s_cbranch_scc1 .Lln_w16_0
	s_cmp_eq_u32 s5, 1
	s_cbranch_scc1 .Lln_w8_0
	s_waitcnt vmcnt(0)
	s_branch .Lln_j0

; DI float bf2f(unsigned h) { return __uint_as_float(h << 16); }
; DI void ln_phase(const Params& p, int ls) {
;     ...
;     float v[16];
;     float sum = 0.f;
; #pragma unroll
;     for (int i = 0; i < 4; ++i) {
;       const int col = lane * 4 + 256 * i;
;       const f32x4 xv = xc[i];
;       const uint2 yv = yc[i];
;       const float4 g = *(const float4*)(gate + col);
;       v[4 * i + 0] = DN_ALPHA * xv.x + (1.f + g.x) * bf2f(yv.x & 0xffffu);
;       v[4 * i + 1] = DN_ALPHA * xv.y + (1.f + g.y) * bf2f(yv.x >> 16);
;       v[4 * i + 2] = DN_ALPHA * xv.z + (1.f + g.z) * bf2f(yv.y & 0xffffu);
;       v[4 * i + 3] = DN_ALPHA * xv.w + (1.f + g.w) * bf2f(yv.y >> 16);
;       sum += v[4 * i] + v[4 * i + 1] + v[4 * i + 2] + v[4 * i + 3];
;     }
; #pragma unroll
;     for (int m = 32; m >= 1; m >>= 1) sum += __shfl_xor(sum, m);
;     const float mean = sum * (1.f / 1024.f);
;     float vs = 0.f;
; #pragma unroll
;     for (int i = 0; i < 16; ++i) { const float d = v[i] - mean; vs += d * d; }
; #pragma unroll
;     for (int m = 32; m >= 1; m >>= 1) vs += __shfl_xor(vs, m);
;     const float rstd = rsqrtf(vs * (1.f / 1024.f) + 1e-5f);
; #pragma unroll
;     for (int i = 0; i < 4; ++i) {
;       const int col = lane * 4 + 256 * i;
;       const float4 g = *(const float4*)(lg + col); const float4 bb = *(const float4*)(lb + col);
;       float4 o;
;       o.x = (v[4 * i + 0] - mean) * rstd * g.x + bb.x; o.y = (v[4 * i + 1] - mean) * rstd * g.y + bb.y;
;       o.z = (v[4 * i + 2] - mean) * rstd * g.z + bb.z; o.w = (v[4 * i + 3] - mean) * rstd * g.w + bb.w;
;       { f32x4 ov = {o.x, o.y, o.z, o.w}; __builtin_nontemporal_store(ov, (f32x4*)(p.out + (size_t)row * 1024 + col)); }
.Lln_j0:
	v_lshlrev_b32_e32 v180, 16, v48
	v_and_b32_e32 v181, 0xffff0000, v48
	v_mul_f32_e32 v164, v100, v180
	v_mul_f32_e32 v165, v101, v181
	v_fmamk_f32 v164, v0, 0x3fd744fd, v164
	v_fmamk_f32 v165, v1, 0x3fd744fd, v165
	v_lshlrev_b32_e32 v180, 16, v49
	v_and_b32_e32 v181, 0xffff0000, v49
	v_mul_f32_e32 v166, v102, v180
	v_mul_f32_e32 v167, v103, v181
	v_fmamk_f32 v166, v2, 0x3fd744fd, v166
	v_fmamk_f32 v167, v3, 0x3fd744fd, v167
	v_lshlrev_b32_e32 v180, 16, v50
	v_and_b32_e32 v181, 0xffff0000, v50
	v_mul_f32_e32 v168, v104, v180
	v_mul_f32_e32 v169, v105, v181
	v_fmamk_f32 v168, v4, 0x3fd744fd, v168
	v_fmamk_f32 v169, v5, 0x3fd744fd, v169
	v_lshlrev_b32_e32 v180, 16, v51
	v_and_b32_e32 v181, 0xffff0000, v51
	v_mul_f32_e32 v170, v106, v180
	v_mul_f32_e32 v171, v107, v181
	v_fmamk_f32 v170, v6, 0x3fd744fd, v170
	v_fmamk_f32 v171, v7, 0x3fd744fd, v171
	v_lshlrev_b32_e32 v180, 16, v52
	v_and_b32_e32 v181, 0xffff0000, v52
	v_mul_f32_e32 v172, v108, v180
	v_mul_f32_e32 v173, v109, v181
	v_fmamk_f32 v172, v8, 0x3fd744fd, v172
	v_fmamk_f32 v173, v9, 0x3fd744fd, v173
	v_lshlrev_b32_e32 v180, 16, v53
	v_and_b32_e32 v181, 0xffff0000, v53
	v_mul_f32_e32 v174, v110, v180
	v_mul_f32_e32 v175, v111, v181
	v_fmamk_f32 v174, v10, 0x3fd744fd, v174
	v_fmamk_f32 v175, v11, 0x3fd744fd, v175
	v_lshlrev_b32_e32 v180, 16, v54
	v_and_b32_e32 v181, 0xffff0000, v54
	v_mul_f32_e32 v176, v112, v180
	v_mul_f32_e32 v177, v113, v181
	v_fmamk_f32 v176, v12, 0x3fd744fd, v176
	v_fmamk_f32 v177, v13, 0x3fd744fd, v177
	v_lshlrev_b32_e32 v180, 16, v55
	v_and_b32_e32 v181, 0xffff0000, v55
	v_mul_f32_e32 v178, v114, v180
	v_mul_f32_e32 v179, v115, v181
	v_fmamk_f32 v178, v14, 0x3fd744fd, v178
	v_fmamk_f32 v179, v15, 0x3fd744fd, v179
	v_add_f32_e32 v180, v164, v165
	v_add_f32_e32 v188, v166, v167
	v_add_f32_e32 v180, v180, v168
	v_add_f32_e32 v188, v188, v169
	v_add_f32_e32 v180, v180, v170
	v_add_f32_e32 v188, v188, v171
	v_add_f32_e32 v180, v180, v172
	v_add_f32_e32 v188, v188, v173
	v_add_f32_e32 v180, v180, v174
	v_add_f32_e32 v188, v188, v175
	v_add_f32_e32 v180, v180, v176
	v_add_f32_e32 v188, v188, v177
	v_add_f32_e32 v180, v180, v178
	v_add_f32_e32 v188, v188, v179
	v_add_f32_e32 v180, v180, v188
	s_nop 1
	v_add_f32_dpp v180, v180, v180 quad_perm:[1,0,3,2] row_mask:0xf bank_mask:0xf
	s_nop 1
	v_add_f32_dpp v180, v180, v180 quad_perm:[2,3,0,1] row_mask:0xf bank_mask:0xf
	s_nop 1
	v_add_f32_dpp v180, v180, v180 row_half_mirror row_mask:0xf bank_mask:0xf
	s_nop 1
	v_add_f32_dpp v180, v180, v180 row_mirror row_mask:0xf bank_mask:0xf
	s_nop 1
	v_add_f32_dpp v180, v180, v180 row_bcast:15 row_mask:0xa bank_mask:0xf
	s_nop 1
	v_add_f32_dpp v180, v180, v180 row_bcast:31 row_mask:0xc bank_mask:0xf
	s_nop 1
	v_readlane_b32 s0, v180, 63
	s_nop 3
	v_mov_b32_e32 v181, s0
	v_mul_f32_e32 v181, 0x3a800000, v181
	v_sub_f32_e32 v164, v164, v181
	v_sub_f32_e32 v165, v165, v181
	v_sub_f32_e32 v166, v166, v181
	v_sub_f32_e32 v167, v167, v181
	v_sub_f32_e32 v168, v168, v181
	v_sub_f32_e32 v169, v169, v181
	v_sub_f32_e32 v170, v170, v181
	v_sub_f32_e32 v171, v171, v181
	v_sub_f32_e32 v172, v172, v181
	v_sub_f32_e32 v173, v173, v181
	v_sub_f32_e32 v174, v174, v181
	v_sub_f32_e32 v175, v175, v181
	v_sub_f32_e32 v176, v176, v181
	v_sub_f32_e32 v177, v177, v181
	v_sub_f32_e32 v178, v178, v181
	v_sub_f32_e32 v179, v179, v181
	v_mul_f32_e32 v180, v164, v164
	v_mul_f32_e32 v188, v165, v165
	v_fmac_f32_e32 v180, v166, v166
	v_fmac_f32_e32 v188, v167, v167
	v_fmac_f32_e32 v180, v168, v168
	v_fmac_f32_e32 v188, v169, v169
	v_fmac_f32_e32 v180, v170, v170
	v_fmac_f32_e32 v188, v171, v171
	v_fmac_f32_e32 v180, v172, v172
	v_fmac_f32_e32 v188, v173, v173
	v_fmac_f32_e32 v180, v174, v174
	v_fmac_f32_e32 v188, v175, v175
	v_fmac_f32_e32 v180, v176, v176
	v_fmac_f32_e32 v188, v177, v177
	v_fmac_f32_e32 v180, v178, v178
	v_fmac_f32_e32 v188, v179, v179
	v_add_f32_e32 v180, v180, v188
	s_nop 1
	v_add_f32_dpp v180, v180, v180 quad_perm:[1,0,3,2] row_mask:0xf bank_mask:0xf
	s_nop 1
	v_add_f32_dpp v180, v180, v180 quad_perm:[2,3,0,1] row_mask:0xf bank_mask:0xf
	s_nop 1
	v_add_f32_dpp v180, v180, v180 row_half_mirror row_mask:0xf bank_mask:0xf
	s_nop 1
	v_add_f32_dpp v180, v180, v180 row_mirror row_mask:0xf bank_mask:0xf
	s_nop 1
	v_add_f32_dpp v180, v180, v180 row_bcast:15 row_mask:0xa bank_mask:0xf
	s_nop 1
	v_add_f32_dpp v180, v180, v180 row_bcast:31 row_mask:0xc bank_mask:0xf
	s_nop 1
	v_readlane_b32 s0, v180, 63
	s_nop 3
	v_mov_b32_e32 v181, s0
	v_fmamk_f32 v181, v181, 0x3a800000, v183
	v_rsq_f32_e32 v181, v181
	s_nop 0
	v_mul_f32_e32 v164, v164, v181
	v_mul_f32_e32 v165, v165, v181
	v_mul_f32_e32 v166, v166, v181
	v_mul_f32_e32 v167, v167, v181
	v_mul_f32_e32 v168, v168, v181
	v_mul_f32_e32 v169, v169, v181
	v_mul_f32_e32 v170, v170, v181
	v_mul_f32_e32 v171, v171, v181
	v_mul_f32_e32 v172, v172, v181
	v_mul_f32_e32 v173, v173, v181
	v_mul_f32_e32 v174, v174, v181
	v_mul_f32_e32 v175, v175, v181
	v_mul_f32_e32 v176, v176, v181
	v_mul_f32_e32 v177, v177, v181
	v_mul_f32_e32 v178, v178, v181
	v_mul_f32_e32 v179, v179, v181
	v_fma_f32 v164, v116, v164, v132
	v_fma_f32 v165, v117, v165, v133
	v_fma_f32 v166, v118, v166, v134
	v_fma_f32 v167, v119, v167, v135
	v_fma_f32 v168, v120, v168, v136
	v_fma_f32 v169, v121, v169, v137
	v_fma_f32 v170, v122, v170, v138
	v_fma_f32 v171, v123, v171, v139
	v_fma_f32 v172, v124, v172, v140
	v_fma_f32 v173, v125, v173, v141
	v_fma_f32 v174, v126, v174, v142
	v_fma_f32 v175, v127, v175, v143
	v_fma_f32 v176, v128, v176, v144
	v_fma_f32 v177, v129, v177, v145
	v_fma_f32 v178, v130, v178, v146
	v_fma_f32 v179, v131, v179, v147
	s_lshl_b32 s0, s100, 12
	s_add_u32 s0, s30, s0
	s_addc_u32 s1, s31, 0
	global_store_dwordx4 v160, v[164:167], s[0:1] nt
	global_store_dwordx4 v160, v[168:171], s[0:1] offset:1024 nt
	global_store_dwordx4 v160, v[172:175], s[0:1] offset:2048 nt
	global_store_dwordx4 v160, v[176:179], s[0:1] offset:3072 nt
	s_cmp_lt_i32 s22, 7
	s_cbranch_scc0 .Lln_noh0
; DI unsigned pack2(float a, float b) { f2_t v = {a, b}; bf2_t r = __builtin_convertvector(v, bf2_t); return __builtin_bit_cast(unsigned, r); }
; DI void ln_phase(const Params& p, int ls) {
;     ...
;   for (int row = blockIdx.x * 8 + w; row < T_; row += stride) {
;     const int b = row >> 14;
;     const float* gate = mod + (ls * 2 + b) * 3072 + 2048;
;     const int rn = row + stride;
;     if (rn < T_) {
; #pragma unroll
;       for (int i = 0; i < 4; ++i) {
;         const int col = lane * 4 + 256 * i;
;         xn[i] = __builtin_nontemporal_load((const f32x4*)(xin + (size_t)rn * 1024 + col));
;         yn[i] = *(const uint2*)(hy + (size_t)rn * LDH + col);
;       }
;     }
;     ...
;       if (ls < 7) {
;         const float* m2 = mod + ((ls + 1) * 2 + b) * 3072;
;         const float4 sh = *(const float4*)(m2 + col); const float4 sc = *(const float4*)(m2 + 1024 + col);
;         uint2 h;
;         h.x = pack2(o.x * (1.f + sc.x) + sh.x, o.y * (1.f + sc.y) + sh.y);
;         h.y = pack2(o.z * (1.f + sc.z) + sh.z, o.w * (1.f + sc.w) + sh.w);
;         *(uint2*)(hy + (size_t)row * LDH + col) = h;
;       }
;     }
; #pragma unroll
;     for (int i = 0; i < 4; ++i) { xc[i] = xn[i]; yc[i] = yn[i]; }
;   }
	v_fma_f32 v180, v164, v204, v220
	v_fma_f32 v181, v165, v205, v221
	v_cvt_pk_bf16_f32 v238, v180, v181
	v_fma_f32 v180, v166, v206, v222
	v_fma_f32 v181, v167, v207, v223
	v_cvt_pk_bf16_f32 v239, v180, v181
	v_fma_f32 v180, v168, v208, v224
	v_fma_f32 v181, v169, v209, v225
	v_cvt_pk_bf16_f32 v240, v180, v181
	v_fma_f32 v180, v170, v210, v226
	v_fma_f32 v181, v171, v211, v227
	v_cvt_pk_bf16_f32 v241, v180, v181
	v_fma_f32 v180, v172, v212, v228
	v_fma_f32 v181, v173, v213, v229
	v_cvt_pk_bf16_f32 v242, v180, v181
	v_fma_f32 v180, v174, v214, v230
	v_fma_f32 v181, v175, v215, v231
	v_cvt_pk_bf16_f32 v243, v180, v181
	v_fma_f32 v180, v176, v216, v232
	v_fma_f32 v181, v177, v217, v233
	v_cvt_pk_bf16_f32 v244, v180, v181
	v_fma_f32 v180, v178, v218, v234
	v_fma_f32 v181, v179, v219, v235
	v_cvt_pk_bf16_f32 v245, v180, v181
	s_mul_i32 s0, s100, 0x880
	s_add_u32 s0, s6, s0
	s_addc_u32 s1, s7, 0
	s_add_u32 s0, s0, 0x8c04100
	s_addc_u32 s1, s1, 0
	global_store_dwordx2 v236, v[238:239], s[0:1]
	global_store_dwordx2 v236, v[240:241], s[0:1] offset:512
	global_store_dwordx2 v236, v[242:243], s[0:1] offset:1024
	global_store_dwordx2 v236, v[244:245], s[0:1] offset:1536
.Lln_noh0:
	s_add_i32 s101, s101, 1
	s_min_u32 s101, s101, 2
	s_add_i32 s4, s100, s20
	s_cmp_lt_u32 s4, 0x8000
	s_cbranch_scc0 .Lln_done
	s_lshr_b32 s0, s100, 14
	s_lshr_b32 s1, s4, 14
	s_mov_b32 s100, s4
	s_cmp_lg_u32 s0, s1
	s_cbranch_scc0 .Lln_it1
	v_mov_b32_e32 v100, v72
	v_mov_b32_e32 v220, v88
	v_mov_b32_e32 v204, v152
	v_mov_b32_e32 v101, v73
	v_mov_b32_e32 v221, v89
	v_mov_b32_e32 v205, v153
	v_mov_b32_e32 v102, v74
	v_mov_b32_e32 v222, v90
	v_mov_b32_e32 v206, v154
	v_mov_b32_e32 v103, v75
	v_mov_b32_e32 v223, v91
	v_mov_b32_e32 v207, v155
	v_mov_b32_e32 v104, v76
	v_mov_b32_e32 v224, v92
	v_mov_b32_e32 v208, v156
	v_mov_b32_e32 v105, v77
	v_mov_b32_e32 v225, v93
	v_mov_b32_e32 v209, v157
	v_mov_b32_e32 v106, v78
	v_mov_b32_e32 v226, v94
	v_mov_b32_e32 v210, v158
	v_mov_b32_e32 v107, v79
	v_mov_b32_e32 v227, v95
	v_mov_b32_e32 v211, v159
	v_mov_b32_e32 v108, v80
	v_mov_b32_e32 v228, v96
	v_mov_b32_e32 v212, v194
	v_mov_b32_e32 v109, v81
	v_mov_b32_e32 v229, v97
	v_mov_b32_e32 v213, v195
	v_mov_b32_e32 v110, v82
	v_mov_b32_e32 v230, v98
	v_mov_b32_e32 v214, v196
	v_mov_b32_e32 v111, v83
	v_mov_b32_e32 v231, v99
	v_mov_b32_e32 v215, v197
	v_mov_b32_e32 v112, v84
	v_mov_b32_e32 v232, v148
	v_mov_b32_e32 v216, v162
	v_mov_b32_e32 v113, v85
	v_mov_b32_e32 v233, v149
	v_mov_b32_e32 v217, v163
	v_mov_b32_e32 v114, v86
	v_mov_b32_e32 v234, v150
	v_mov_b32_e32 v218, v190
	v_mov_b32_e32 v115, v87
	v_mov_b32_e32 v235, v151
	v_mov_b32_e32 v219, v191
	s_branch .Lln_it1
.Lln_it1:
	s_mul_i32 s4, s20, 2
	s_add_i32 s4, s100, s4
	s_cmp_lt_u32 s4, 0x8000
	s_cbranch_scc0 .Lln_nopf1
	s_lshl_b32 s0, s4, 12
	s_add_u32 s0, s12, s0
	s_addc_u32 s1, s13, 0
	global_load_dwordx4 v[0:3], v160, s[0:1] nt
	global_load_dwordx4 v[4:7], v160, s[0:1] offset:1024 nt
	global_load_dwordx4 v[8:11], v160, s[0:1] offset:2048 nt
	global_load_dwordx4 v[12:15], v160, s[0:1] offset:3072 nt
	s_mul_i32 s0, s4, 0x880
	s_add_u32 s0, s6, s0
	s_addc_u32 s1, s7, 0
	s_add_u32 s0, s0, 0x8c04100
	s_addc_u32 s1, s1, 0
	global_load_dwordx2 v[48:49], v236, s[0:1]
	global_load_dwordx2 v[50:51], v236, s[0:1] offset:512
	global_load_dwordx2 v[52:53], v236, s[0:1] offset:1024
	global_load_dwordx2 v[54:55], v236, s[0:1] offset:1536

; DI float bf2f(unsigned h) { return __uint_as_float(h << 16); }
; DI void ln_phase(const Params& p, int ls) {
;     ...
;     float v[16];
;     float sum = 0.f;
; #pragma unroll
;     for (int i = 0; i < 4; ++i) {
;       const int col = lane * 4 + 256 * i;
;       const f32x4 xv = xc[i];
;       const uint2 yv = yc[i];
;       const float4 g = *(const float4*)(gate + col);
;       v[4 * i + 0] = DN_ALPHA * xv.x + (1.f + g.x) * bf2f(yv.x & 0xffffu);
;       v[4 * i + 1] = DN_ALPHA * xv.y + (1.f + g.y) * bf2f(yv.x >> 16);
;       v[4 * i + 2] = DN_ALPHA * xv.z + (1.f + g.z) * bf2f(yv.y & 0xffffu);
;       v[4 * i + 3] = DN_ALPHA * xv.w + (1.f + g.w) * bf2f(yv.y >> 16);
;       sum += v[4 * i] + v[4 * i + 1] + v[4 * i + 2] + v[4 * i + 3];
;     }
; #pragma unroll
;     for (int m = 32; m >= 1; m >>= 1) sum += __shfl_xor(sum, m);
;     const float mean = sum * (1.f / 1024.f);
;     float vs = 0.f;
; #pragma unroll
;     for (int i = 0; i < 16; ++i) { const float d = v[i] - mean; vs += d * d; }
; #pragma unroll
;     for (int m = 32; m >= 1; m >>= 1) vs += __shfl_xor(vs, m);
;     const float rstd = rsqrtf(vs * (1.f / 1024.f) + 1e-5f);
; #pragma unroll
;     for (int i = 0; i < 4; ++i) {
;       const int col = lane * 4 + 256 * i;
;       const float4 g = *(const float4*)(lg + col); const float4 bb = *(const float4*)(lb + col);
;       float4 o;
;       o.x = (v[4 * i + 0] - mean) * rstd * g.x + bb.x; o.y = (v[4 * i + 1] - mean) * rstd * g.y + bb.y;
;       o.z = (v[4 * i + 2] - mean) * rstd * g.z + bb.z; o.w = (v[4 * i + 3] - mean) * rstd * g.w + bb.w;
;       { f32x4 ov = {o.x, o.y, o.z, o.w}; __builtin_nontemporal_store(ov, (f32x4*)(p.out + (size_t)row * 1024 + col)); }
.Lln_j1:
	v_lshlrev_b32_e32 v180, 16, v56
	v_and_b32_e32 v181, 0xffff0000, v56
	v_mul_f32_e32 v164, v100, v180
	v_mul_f32_e32 v165, v101, v181
	v_fmamk_f32 v164, v16, 0x3fd744fd, v164
	v_fmamk_f32 v165, v17, 0x3fd744fd, v165
	v_lshlrev_b32_e32 v180, 16, v57
	v_and_b32_e32 v181, 0xffff0000, v57
	v_mul_f32_e32 v166, v102, v180
	v_mul_f32_e32 v167, v103, v181
	v_fmamk_f32 v166, v18, 0x3fd744fd, v166
	v_fmamk_f32 v167, v19, 0x3fd744fd, v167
	v_lshlrev_b32_e32 v180, 16, v58
	v_and_b32_e32 v181, 0xffff0000, v58
	v_mul_f32_e32 v168, v104, v180
	v_mul_f32_e32 v169, v105, v181
	v_fmamk_f32 v168, v20, 0x3fd744fd, v168
	v_fmamk_f32 v169, v21, 0x3fd744fd, v169
	v_lshlrev_b32_e32 v180, 16, v59
	v_and_b32_e32 v181, 0xffff0000, v59
	v_mul_f32_e32 v170, v106, v180
	v_mul_f32_e32 v171, v107, v181
	v_fmamk_f32 v170, v22, 0x3fd744fd, v170
	v_fmamk_f32 v171, v23, 0x3fd744fd, v171
	v_lshlrev_b32_e32 v180, 16, v60
	v_and_b32_e32 v181, 0xffff0000, v60
	v_mul_f32_e32 v172, v108, v180
	v_mul_f32_e32 v173, v109, v181
	v_fmamk_f32 v172, v24, 0x3fd744fd, v172
	v_fmamk_f32 v173, v25, 0x3fd744fd, v173
	v_lshlrev_b32_e32 v180, 16, v61
	v_and_b32_e32 v181, 0xffff0000, v61
	v_mul_f32_e32 v174, v110, v180
	v_mul_f32_e32 v175, v111, v181
	v_fmamk_f32 v174, v26, 0x3fd744fd, v174
	v_fmamk_f32 v175, v27, 0x3fd744fd, v175
	v_lshlrev_b32_e32 v180, 16, v62
	v_and_b32_e32 v181, 0xffff0000, v62
	v_mul_f32_e32 v176, v112, v180
	v_mul_f32_e32 v177, v113, v181
	v_fmamk_f32 v176, v28, 0x3fd744fd, v176
	v_fmamk_f32 v177, v29, 0x3fd744fd, v177
	v_lshlrev_b32_e32 v180, 16, v63
	v_and_b32_e32 v181, 0xffff0000, v63
	v_mul_f32_e32 v178, v114, v180
	v_mul_f32_e32 v179, v115, v181
	v_fmamk_f32 v178, v30, 0x3fd744fd, v178
	v_fmamk_f32 v179, v31, 0x3fd744fd, v179
	v_add_f32_e32 v180, v164, v165
	v_add_f32_e32 v188, v166, v167
	v_add_f32_e32 v180, v180, v168
	v_add_f32_e32 v188, v188, v169
	v_add_f32_e32 v180, v180, v170
	v_add_f32_e32 v188, v188, v171
	v_add_f32_e32 v180, v180, v172
	v_add_f32_e32 v188, v188, v173
	v_add_f32_e32 v180, v180, v174
	v_add_f32_e32 v188, v188, v175
	v_add_f32_e32 v180, v180, v176
	v_add_f32_e32 v188, v188, v177
	v_add_f32_e32 v180, v180, v178
	v_add_f32_e32 v188, v188, v179
	v_add_f32_e32 v180, v180, v188
	s_nop 1
	v_add_f32_dpp v180, v180, v180 quad_perm:[1,0,3,2] row_mask:0xf bank_mask:0xf
	s_nop 1
	v_add_f32_dpp v180, v180, v180 quad_perm:[2,3,0,1] row_mask:0xf bank_mask:0xf
	s_nop 1
	v_add_f32_dpp v180, v180, v180 row_half_mirror row_mask:0xf bank_mask:0xf
	s_nop 1
	v_add_f32_dpp v180, v180, v180 row_mirror row_mask:0xf bank_mask:0xf
	s_nop 1
	v_add_f32_dpp v180, v180, v180 row_bcast:15 row_mask:0xa bank_mask:0xf
	s_nop 1
	v_add_f32_dpp v180, v180, v180 row_bcast:31 row_mask:0xc bank_mask:0xf
	s_nop 1
	v_readlane_b32 s0, v180, 63
	s_nop 3
	v_mov_b32_e32 v181, s0
	v_mul_f32_e32 v181, 0x3a800000, v181
	v_sub_f32_e32 v164, v164, v181
	v_sub_f32_e32 v165, v165, v181
	v_sub_f32_e32 v166, v166, v181
	v_sub_f32_e32 v167, v167, v181
	v_sub_f32_e32 v168, v168, v181
	v_sub_f32_e32 v169, v169, v181
	v_sub_f32_e32 v170, v170, v181
	v_sub_f32_e32 v171, v171, v181
	v_sub_f32_e32 v172, v172, v181
	v_sub_f32_e32 v173, v173, v181
	v_sub_f32_e32 v174, v174, v181
	v_sub_f32_e32 v175, v175, v181
	v_sub_f32_e32 v176, v176, v181
	v_sub_f32_e32 v177, v177, v181
	v_sub_f32_e32 v178, v178, v181
	v_sub_f32_e32 v179, v179, v181
	v_mul_f32_e32 v180, v164, v164
	v_mul_f32_e32 v188, v165, v165
	v_fmac_f32_e32 v180, v166, v166
	v_fmac_f32_e32 v188, v167, v167
	v_fmac_f32_e32 v180, v168, v168
	v_fmac_f32_e32 v188, v169, v169
	v_fmac_f32_e32 v180, v170, v170
	v_fmac_f32_e32 v188, v171, v171
	v_fmac_f32_e32 v180, v172, v172
	v_fmac_f32_e32 v188, v173, v173
	v_fmac_f32_e32 v180, v174, v174
	v_fmac_f32_e32 v188, v175, v175
	v_fmac_f32_e32 v180, v176, v176
	v_fmac_f32_e32 v188, v177, v177
	v_fmac_f32_e32 v180, v178, v178
	v_fmac_f32_e32 v188, v179, v179
	v_add_f32_e32 v180, v180, v188
	s_nop 1
	v_add_f32_dpp v180, v180, v180 quad_perm:[1,0,3,2] row_mask:0xf bank_mask:0xf
	s_nop 1
	v_add_f32_dpp v180, v180, v180 quad_perm:[2,3,0,1] row_mask:0xf bank_mask:0xf
	s_nop 1
	v_add_f32_dpp v180, v180, v180 row_half_mirror row_mask:0xf bank_mask:0xf
	s_nop 1
	v_add_f32_dpp v180, v180, v180 row_mirror row_mask:0xf bank_mask:0xf
	s_nop 1
	v_add_f32_dpp v180, v180, v180 row_bcast:15 row_mask:0xa bank_mask:0xf
	s_nop 1
	v_add_f32_dpp v180, v180, v180 row_bcast:31 row_mask:0xc bank_mask:0xf
	s_nop 1
	v_readlane_b32 s0, v180, 63
	s_nop 3
	v_mov_b32_e32 v181, s0
	v_fmamk_f32 v181, v181, 0x3a800000, v183
	v_rsq_f32_e32 v181, v181
	s_nop 0
	v_mul_f32_e32 v164, v164, v181
	v_mul_f32_e32 v165, v165, v181
	v_mul_f32_e32 v166, v166, v181
	v_mul_f32_e32 v167, v167, v181
	v_mul_f32_e32 v168, v168, v181
	v_mul_f32_e32 v169, v169, v181
	v_mul_f32_e32 v170, v170, v181
	v_mul_f32_e32 v171, v171, v181
	v_mul_f32_e32 v172, v172, v181
	v_mul_f32_e32 v173, v173, v181
	v_mul_f32_e32 v174, v174, v181
	v_mul_f32_e32 v175, v175, v181
	v_mul_f32_e32 v176, v176, v181
	v_mul_f32_e32 v177, v177, v181
	v_mul_f32_e32 v178, v178, v181
	v_mul_f32_e32 v179, v179, v181
	v_fma_f32 v164, v116, v164, v132
	v_fma_f32 v165, v117, v165, v133
	v_fma_f32 v166, v118, v166, v134
	v_fma_f32 v167, v119, v167, v135
	v_fma_f32 v168, v120, v168, v136
	v_fma_f32 v169, v121, v169, v137
	v_fma_f32 v170, v122, v170, v138
	v_fma_f32 v171, v123, v171, v139
	v_fma_f32 v172, v124, v172, v140
	v_fma_f32 v173, v125, v173, v141
	v_fma_f32 v174, v126, v174, v142
	v_fma_f32 v175, v127, v175, v143
	v_fma_f32 v176, v128, v176, v144
	v_fma_f32 v177, v129, v177, v145
	v_fma_f32 v178, v130, v178, v146
	v_fma_f32 v179, v131, v179, v147
	s_lshl_b32 s0, s100, 12
	s_add_u32 s0, s30, s0
	s_addc_u32 s1, s31, 0
	global_store_dwordx4 v160, v[164:167], s[0:1] nt
	global_store_dwordx4 v160, v[168:171], s[0:1] offset:1024 nt
	global_store_dwordx4 v160, v[172:175], s[0:1] offset:2048 nt
	global_store_dwordx4 v160, v[176:179], s[0:1] offset:3072 nt
	s_cmp_lt_i32 s22, 7
	s_cbranch_scc0 .Lln_noh1
; DI unsigned pack2(float a, float b) { f2_t v = {a, b}; bf2_t r = __builtin_convertvector(v, bf2_t); return __builtin_bit_cast(unsigned, r); }
; DI void ln_phase(const Params& p, int ls) {
;     ...
;       if (ls < 7) {
;         const float* m2 = mod + ((ls + 1) * 2 + b) * 3072;
;         const float4 sh = *(const float4*)(m2 + col); const float4 sc = *(const float4*)(m2 + 1024 + col);
;         uint2 h;
;         h.x = pack2(o.x * (1.f + sc.x) + sh.x, o.y * (1.f + sc.y) + sh.y);
;         h.y = pack2(o.z * (1.f + sc.z) + sh.z, o.w * (1.f + sc.w) + sh.w);
;         *(uint2*)(hy + (size_t)row * LDH + col) = h;
;       }
	v_fma_f32 v180, v164, v204, v220
	v_fma_f32 v181, v165, v205, v221
	v_cvt_pk_bf16_f32 v238, v180, v181
	v_fma_f32 v180, v166, v206, v222
	v_fma_f32 v181, v167, v207, v223
	v_cvt_pk_bf16_f32 v239, v180, v181
	v_fma_f32 v180, v168, v208, v224
	v_fma_f32 v181, v169, v209, v225
	v_cvt_pk_bf16_f32 v240, v180, v181
	v_fma_f32 v180, v170, v210, v226
	v_fma_f32 v181, v171, v211, v227
	v_cvt_pk_bf16_f32 v241, v180, v181
	v_fma_f32 v180, v172, v212, v228
	v_fma_f32 v181, v173, v213, v229
	v_cvt_pk_bf16_f32 v242, v180, v181
	v_fma_f32 v180, v174, v214, v230
	v_fma_f32 v181, v175, v215, v231
	v_cvt_pk_bf16_f32 v243, v180, v181
	v_fma_f32 v180, v176, v216, v232
	v_fma_f32 v181, v177, v217, v233
	v_cvt_pk_bf16_f32 v244, v180, v181
	v_fma_f32 v180, v178, v218, v234
	v_fma_f32 v181, v179, v219, v235
	v_cvt_pk_bf16_f32 v245, v180, v181
	s_mul_i32 s0, s100, 0x880
	s_add_u32 s0, s6, s0
	s_addc_u32 s1, s7, 0
	s_add_u32 s0, s0, 0x8c04100
	s_addc_u32 s1, s1, 0
	global_store_dwordx2 v236, v[238:239], s[0:1]
	global_store_dwordx2 v236, v[240:241], s[0:1] offset:512
	global_store_dwordx2 v236, v[242:243], s[0:1] offset:1024
	global_store_dwordx2 v236, v[244:245], s[0:1] offset:1536

; DI void ln_phase(const Params& p, int ls) {
;     ...
;     const int rn = row + stride;
;     if (rn < T_) {
; #pragma unroll
;       for (int i = 0; i < 4; ++i) {
;         const int col = lane * 4 + 256 * i;
;         xn[i] = __builtin_nontemporal_load((const f32x4*)(xin + (size_t)rn * 1024 + col));
;         yn[i] = *(const uint2*)(hy + (size_t)rn * LDH + col);
;       }
;     }
.Lln_it2:
	s_mul_i32 s4, s20, 2
	s_add_i32 s4, s100, s4
	s_cmp_lt_u32 s4, 0x8000
	s_cbranch_scc0 .Lln_nopf2
	s_lshl_b32 s0, s4, 12
	s_add_u32 s0, s12, s0
	s_addc_u32 s1, s13, 0
	global_load_dwordx4 v[16:19], v160, s[0:1] nt
	global_load_dwordx4 v[20:23], v160, s[0:1] offset:1024 nt
	global_load_dwordx4 v[24:27], v160, s[0:1] offset:2048 nt
	global_load_dwordx4 v[28:31], v160, s[0:1] offset:3072 nt
	s_mul_i32 s0, s4, 0x880
	s_add_u32 s0, s6, s0
	s_addc_u32 s1, s7, 0
	s_add_u32 s0, s0, 0x8c04100
	s_addc_u32 s1, s1, 0
	global_load_dwordx2 v[56:57], v236, s[0:1]
	global_load_dwordx2 v[58:59], v236, s[0:1] offset:512
	global_load_dwordx2 v[60:61], v236, s[0:1] offset:1024
	global_load_dwordx2 v[62:63], v236, s[0:1] offset:1536

; DI float bf2f(unsigned h) { return __uint_as_float(h << 16); }
; DI void ln_phase(const Params& p, int ls) {
;     ...
;     float v[16];
;     float sum = 0.f;
; #pragma unroll
;     for (int i = 0; i < 4; ++i) {
;       const int col = lane * 4 + 256 * i;
;       const f32x4 xv = xc[i];
;       const uint2 yv = yc[i];
;       const float4 g = *(const float4*)(gate + col);
;       v[4 * i + 0] = DN_ALPHA * xv.x + (1.f + g.x) * bf2f(yv.x & 0xffffu);
;       v[4 * i + 1] = DN_ALPHA * xv.y + (1.f + g.y) * bf2f(yv.x >> 16);
;       v[4 * i + 2] = DN_ALPHA * xv.z + (1.f + g.z) * bf2f(yv.y & 0xffffu);
;       v[4 * i + 3] = DN_ALPHA * xv.w + (1.f + g.w) * bf2f(yv.y >> 16);
;       sum += v[4 * i] + v[4 * i + 1] + v[4 * i + 2] + v[4 * i + 3];
;     }
; #pragma unroll
;     for (int m = 32; m >= 1; m >>= 1) sum += __shfl_xor(sum, m);
;     const float mean = sum * (1.f / 1024.f);
;     float vs = 0.f;
; #pragma unroll
;     for (int i = 0; i < 16; ++i) { const float d = v[i] - mean; vs += d * d; }
; #pragma unroll
;     for (int m = 32; m >= 1; m >>= 1) vs += __shfl_xor(vs, m);
;     const float rstd = rsqrtf(vs * (1.f / 1024.f) + 1e-5f);
; #pragma unroll
;     for (int i = 0; i < 4; ++i) {
;       const int col = lane * 4 + 256 * i;
;       const float4 g = *(const float4*)(lg + col); const float4 bb = *(const float4*)(lb + col);
;       float4 o;
;       o.x = (v[4 * i + 0] - mean) * rstd * g.x + bb.x; o.y = (v[4 * i + 1] - mean) * rstd * g.y + bb.y;
;       o.z = (v[4 * i + 2] - mean) * rstd * g.z + bb.z; o.w = (v[4 * i + 3] - mean) * rstd * g.w + bb.w;
;       { f32x4 ov = {o.x, o.y, o.z, o.w}; __builtin_nontemporal_store(ov, (f32x4*)(p.out + (size_t)row * 1024 + col)); }
.Lln_j2:
	v_lshlrev_b32_e32 v180, 16, v64
	v_and_b32_e32 v181, 0xffff0000, v64
	v_mul_f32_e32 v164, v100, v180
	v_mul_f32_e32 v165, v101, v181
	v_fmamk_f32 v164, v32, 0x3fd744fd, v164
	v_fmamk_f32 v165, v33, 0x3fd744fd, v165
	v_lshlrev_b32_e32 v180, 16, v65
	v_and_b32_e32 v181, 0xffff0000, v65
	v_mul_f32_e32 v166, v102, v180
	v_mul_f32_e32 v167, v103, v181
	v_fmamk_f32 v166, v34, 0x3fd744fd, v166
	v_fmamk_f32 v167, v35, 0x3fd744fd, v167
	v_lshlrev_b32_e32 v180, 16, v66
	v_and_b32_e32 v181, 0xffff0000, v66
	v_mul_f32_e32 v168, v104, v180
	v_mul_f32_e32 v169, v105, v181
	v_fmamk_f32 v168, v36, 0x3fd744fd, v168
	v_fmamk_f32 v169, v37, 0x3fd744fd, v169
	v_lshlrev_b32_e32 v180, 16, v67
	v_and_b32_e32 v181, 0xffff0000, v67
	v_mul_f32_e32 v170, v106, v180
	v_mul_f32_e32 v171, v107, v181
	v_fmamk_f32 v170, v38, 0x3fd744fd, v170
	v_fmamk_f32 v171, v39, 0x3fd744fd, v171
	v_lshlrev_b32_e32 v180, 16, v68
	v_and_b32_e32 v181, 0xffff0000, v68
	v_mul_f32_e32 v172, v108, v180
	v_mul_f32_e32 v173, v109, v181
	v_fmamk_f32 v172, v40, 0x3fd744fd, v172
	v_fmamk_f32 v173, v41, 0x3fd744fd, v173
	v_lshlrev_b32_e32 v180, 16, v69
	v_and_b32_e32 v181, 0xffff0000, v69
	v_mul_f32_e32 v174, v110, v180
	v_mul_f32_e32 v175, v111, v181
	v_fmamk_f32 v174, v42, 0x3fd744fd, v174
	v_fmamk_f32 v175, v43, 0x3fd744fd, v175
	v_lshlrev_b32_e32 v180, 16, v70
	v_and_b32_e32 v181, 0xffff0000, v70
	v_mul_f32_e32 v176, v112, v180
	v_mul_f32_e32 v177, v113, v181
	v_fmamk_f32 v176, v44, 0x3fd744fd, v176
	v_fmamk_f32 v177, v45, 0x3fd744fd, v177
	v_lshlrev_b32_e32 v180, 16, v71
	v_and_b32_e32 v181, 0xffff0000, v71
	v_mul_f32_e32 v178, v114, v180
	v_mul_f32_e32 v179, v115, v181
	v_fmamk_f32 v178, v46, 0x3fd744fd, v178
	v_fmamk_f32 v179, v47, 0x3fd744fd, v179
	v_add_f32_e32 v180, v164, v165
	v_add_f32_e32 v188, v166, v167
	v_add_f32_e32 v180, v180, v168
	v_add_f32_e32 v188, v188, v169
	v_add_f32_e32 v180, v180, v170
	v_add_f32_e32 v188, v188, v171
	v_add_f32_e32 v180, v180, v172
	v_add_f32_e32 v188, v188, v173
	v_add_f32_e32 v180, v180, v174
	v_add_f32_e32 v188, v188, v175
	v_add_f32_e32 v180, v180, v176
	v_add_f32_e32 v188, v188, v177
	v_add_f32_e32 v180, v180, v178
	v_add_f32_e32 v188, v188, v179
	v_add_f32_e32 v180, v180, v188
	s_nop 1
	v_add_f32_dpp v180, v180, v180 quad_perm:[1,0,3,2] row_mask:0xf bank_mask:0xf
	s_nop 1
	v_add_f32_dpp v180, v180, v180 quad_perm:[2,3,0,1] row_mask:0xf bank_mask:0xf
	s_nop 1
	v_add_f32_dpp v180, v180, v180 row_half_mirror row_mask:0xf bank_mask:0xf
	s_nop 1
	v_add_f32_dpp v180, v180, v180 row_mirror row_mask:0xf bank_mask:0xf
	s_nop 1
	v_add_f32_dpp v180, v180, v180 row_bcast:15 row_mask:0xa bank_mask:0xf
	s_nop 1
	v_add_f32_dpp v180, v180, v180 row_bcast:31 row_mask:0xc bank_mask:0xf
	s_nop 1
	v_readlane_b32 s0, v180, 63
	s_nop 3
	v_mov_b32_e32 v181, s0
	v_mul_f32_e32 v181, 0x3a800000, v181
	v_sub_f32_e32 v164, v164, v181
	v_sub_f32_e32 v165, v165, v181
	v_sub_f32_e32 v166, v166, v181
	v_sub_f32_e32 v167, v167, v181
	v_sub_f32_e32 v168, v168, v181
	v_sub_f32_e32 v169, v169, v181
	v_sub_f32_e32 v170, v170, v181
	v_sub_f32_e32 v171, v171, v181
	v_sub_f32_e32 v172, v172, v181
	v_sub_f32_e32 v173, v173, v181
	v_sub_f32_e32 v174, v174, v181
	v_sub_f32_e32 v175, v175, v181
	v_sub_f32_e32 v176, v176, v181
	v_sub_f32_e32 v177, v177, v181
	v_sub_f32_e32 v178, v178, v181
	v_sub_f32_e32 v179, v179, v181
	v_mul_f32_e32 v180, v164, v164
	v_mul_f32_e32 v188, v165, v165
	v_fmac_f32_e32 v180, v166, v166
	v_fmac_f32_e32 v188, v167, v167
	v_fmac_f32_e32 v180, v168, v168
	v_fmac_f32_e32 v188, v169, v169
	v_fmac_f32_e32 v180, v170, v170
	v_fmac_f32_e32 v188, v171, v171
	v_fmac_f32_e32 v180, v172, v172
	v_fmac_f32_e32 v188, v173, v173
	v_fmac_f32_e32 v180, v174, v174
	v_fmac_f32_e32 v188, v175, v175
	v_fmac_f32_e32 v180, v176, v176
	v_fmac_f32_e32 v188, v177, v177
	v_fmac_f32_e32 v180, v178, v178
	v_fmac_f32_e32 v188, v179, v179
	v_add_f32_e32 v180, v180, v188
	s_nop 1
	v_add_f32_dpp v180, v180, v180 quad_perm:[1,0,3,2] row_mask:0xf bank_mask:0xf
	s_nop 1
	v_add_f32_dpp v180, v180, v180 quad_perm:[2,3,0,1] row_mask:0xf bank_mask:0xf
	s_nop 1
	v_add_f32_dpp v180, v180, v180 row_half_mirror row_mask:0xf bank_mask:0xf
	s_nop 1
	v_add_f32_dpp v180, v180, v180 row_mirror row_mask:0xf bank_mask:0xf
	s_nop 1
	v_add_f32_dpp v180, v180, v180 row_bcast:15 row_mask:0xa bank_mask:0xf
	s_nop 1
	v_add_f32_dpp v180, v180, v180 row_bcast:31 row_mask:0xc bank_mask:0xf
	s_nop 1
	v_readlane_b32 s0, v180, 63
	s_nop 3
	v_mov_b32_e32 v181, s0
	v_fmamk_f32 v181, v181, 0x3a800000, v183
	v_rsq_f32_e32 v181, v181
	s_nop 0
	v_mul_f32_e32 v164, v164, v181
	v_mul_f32_e32 v165, v165, v181
	v_mul_f32_e32 v166, v166, v181
	v_mul_f32_e32 v167, v167, v181
	v_mul_f32_e32 v168, v168, v181
	v_mul_f32_e32 v169, v169, v181
	v_mul_f32_e32 v170, v170, v181
	v_mul_f32_e32 v171, v171, v181
	v_mul_f32_e32 v172, v172, v181
	v_mul_f32_e32 v173, v173, v181
	v_mul_f32_e32 v174, v174, v181
	v_mul_f32_e32 v175, v175, v181
	v_mul_f32_e32 v176, v176, v181
	v_mul_f32_e32 v177, v177, v181
	v_mul_f32_e32 v178, v178, v181
	v_mul_f32_e32 v179, v179, v181
	v_fma_f32 v164, v116, v164, v132
	v_fma_f32 v165, v117, v165, v133
	v_fma_f32 v166, v118, v166, v134
	v_fma_f32 v167, v119, v167, v135
	v_fma_f32 v168, v120, v168, v136
	v_fma_f32 v169, v121, v169, v137
	v_fma_f32 v170, v122, v170, v138
	v_fma_f32 v171, v123, v171, v139
	v_fma_f32 v172, v124, v172, v140
	v_fma_f32 v173, v125, v173, v141
	v_fma_f32 v174, v126, v174, v142
	v_fma_f32 v175, v127, v175, v143
	v_fma_f32 v176, v128, v176, v144
	v_fma_f32 v177, v129, v177, v145
	v_fma_f32 v178, v130, v178, v146
	v_fma_f32 v179, v131, v179, v147
	s_lshl_b32 s0, s100, 12
	s_add_u32 s0, s30, s0
	s_addc_u32 s1, s31, 0
	global_store_dwordx4 v160, v[164:167], s[0:1] nt
	global_store_dwordx4 v160, v[168:171], s[0:1] offset:1024 nt
	global_store_dwordx4 v160, v[172:175], s[0:1] offset:2048 nt
	global_store_dwordx4 v160, v[176:179], s[0:1] offset:3072 nt
	s_cmp_lt_i32 s22, 7
	s_cbranch_scc0 .Lln_noh2
; DI unsigned pack2(float a, float b) { f2_t v = {a, b}; bf2_t r = __builtin_convertvector(v, bf2_t); return __builtin_bit_cast(unsigned, r); }
; DI void ln_phase(const Params& p, int ls) {
;     ...
;       if (ls < 7) {
;         const float* m2 = mod + ((ls + 1) * 2 + b) * 3072;
;         const float4 sh = *(const float4*)(m2 + col); const float4 sc = *(const float4*)(m2 + 1024 + col);
;         uint2 h;
;         h.x = pack2(o.x * (1.f + sc.x) + sh.x, o.y * (1.f + sc.y) + sh.y);
;         h.y = pack2(o.z * (1.f + sc.z) + sh.z, o.w * (1.f + sc.w) + sh.w);
;         *(uint2*)(hy + (size_t)row * LDH + col) = h;
;       }
	v_fma_f32 v180, v164, v204, v220
	v_fma_f32 v181, v165, v205, v221
	v_cvt_pk_bf16_f32 v238, v180, v181
	v_fma_f32 v180, v166, v206, v222
	v_fma_f32 v181, v167, v207, v223
	v_cvt_pk_bf16_f32 v239, v180, v181
	v_fma_f32 v180, v168, v208, v224
	v_fma_f32 v181, v169, v209, v225
	v_cvt_pk_bf16_f32 v240, v180, v181
	v_fma_f32 v180, v170, v210, v226
	v_fma_f32 v181, v171, v211, v227
	v_cvt_pk_bf16_f32 v241, v180, v181
	v_fma_f32 v180, v172, v212, v228
	v_fma_f32 v181, v173, v213, v229
	v_cvt_pk_bf16_f32 v242, v180, v181
	v_fma_f32 v180, v174, v214, v230
	v_fma_f32 v181, v175, v215, v231
	v_cvt_pk_bf16_f32 v243, v180, v181
	v_fma_f32 v180, v176, v216, v232
	v_fma_f32 v181, v177, v217, v233
	v_cvt_pk_bf16_f32 v244, v180, v181
	v_fma_f32 v180, v178, v218, v234
	v_fma_f32 v181, v179, v219, v235
	v_cvt_pk_bf16_f32 v245, v180, v181
	s_mul_i32 s0, s100, 0x880
	s_add_u32 s0, s6, s0
	s_addc_u32 s1, s7, 0
	s_add_u32 s0, s0, 0x8c04100
	s_addc_u32 s1, s1, 0
	global_store_dwordx2 v236, v[238:239], s[0:1]
	global_store_dwordx2 v236, v[240:241], s[0:1] offset:512
	global_store_dwordx2 v236, v[242:243], s[0:1] offset:1024
	global_store_dwordx2 v236, v[244:245], s[0:1] offset:1536

; #define RAWBAR() { asm volatile("s_waitcnt vmcnt(0) lgkmcnt(0)" ::: "memory"); __builtin_amdgcn_s_barrier(); }
;     ...
;   if (V != 1) GLDS(0, 0);
;   RAWBAR();
;   for (int kt = 0; kt < nk; kt += 2) {
;     if (V != 1) GLDS(kt + 1, 1);
;     if (V != 2) COMPUTE(0);
;     RAWBAR();
;     if (V != 1) if (kt + 2 < nk) GLDS(kt + 2, 0);
;     if (V != 2) COMPUTE(1);
;     RAWBAR();
;   }
;     ...
;   for (int lt = blockIdx.x >> 3; lt < 16 * nN; lt += gridDim.x >> 3) {
;     int mt, nt; tile_map(lt, 16, nN, 8, 4, mt, nt);
;     const int m0 = mt * 256, n0 = nt * 256;
.Lgm_cadv_done7:
	s_waitcnt lgkmcnt(6)
	v_mfma_f32_32x32x16_bf16 v[0:15], v[162:165], v[128:131], v[0:15]
	v_mfma_f32_32x32x16_bf16 v[16:31], v[166:169], v[128:131], v[16:31]
	ds_read_b128 v[128:131], v210
	v_mfma_f32_32x32x16_bf16 v[32:47], v[162:165], v[132:135], v[32:47]
	v_mfma_f32_32x32x16_bf16 v[48:63], v[166:169], v[132:135], v[48:63]
	ds_read_b128 v[132:135], v210 offset:4096
	v_mfma_f32_32x32x16_bf16 v[64:79], v[162:165], v[136:139], v[64:79]
	v_mfma_f32_32x32x16_bf16 v[80:95], v[166:169], v[136:139], v[80:95]
	ds_read_b128 v[136:139], v210 offset:8192
	v_mfma_f32_32x32x16_bf16 v[96:111], v[162:165], v[140:143], v[96:111]
	v_mfma_f32_32x32x16_bf16 v[112:127], v[166:169], v[140:143], v[112:127]
	ds_read_b128 v[140:143], v210 offset:12288
	ds_read_b128 v[162:165], v218
	ds_read_b128 v[166:169], v218 offset:4096
	s_waitcnt lgkmcnt(6)
	v_mfma_f32_32x32x16_bf16 v[0:15], v[170:173], v[144:147], v[0:15]
	v_mfma_f32_32x32x16_bf16 v[16:31], v[174:177], v[144:147], v[16:31]
	ds_read_b128 v[144:147], v211
	v_mfma_f32_32x32x16_bf16 v[32:47], v[170:173], v[148:151], v[32:47]
	v_mfma_f32_32x32x16_bf16 v[48:63], v[174:177], v[148:151], v[48:63]
	ds_read_b128 v[148:151], v211 offset:4096
	v_mfma_f32_32x32x16_bf16 v[64:79], v[170:173], v[152:155], v[64:79]
	v_mfma_f32_32x32x16_bf16 v[80:95], v[174:177], v[152:155], v[80:95]
	ds_read_b128 v[152:155], v211 offset:8192
	v_mfma_f32_32x32x16_bf16 v[96:111], v[170:173], v[156:159], v[96:111]
	v_mfma_f32_32x32x16_bf16 v[112:127], v[174:177], v[156:159], v[112:127]
	ds_read_b128 v[156:159], v211 offset:12288
	ds_read_b128 v[170:173], v219
	ds_read_b128 v[174:177], v219 offset:4096
	s_waitcnt vmcnt(0) lgkmcnt(0)
	s_barrier
	s_add_u32 m0, s14, 0x10000
	v_mfma_f32_32x32x16_bf16 v[0:15], v[162:165], v[128:131], v[0:15]
	global_load_lds_dwordx4 v220, s[22:23]
	s_add_u32 m0, s14, 0x10400
	v_mfma_f32_32x32x16_bf16 v[16:31], v[166:169], v[128:131], v[16:31]
	global_load_lds_dwordx4 v221, s[22:23]
	ds_read_b128 v[128:131], v204
	s_add_u32 m0, s14, 0x10800
	v_mfma_f32_32x32x16_bf16 v[32:47], v[162:165], v[132:135], v[32:47]
	global_load_lds_dwordx4 v222, s[22:23]
	s_add_u32 m0, s14, 0x10c00
	v_mfma_f32_32x32x16_bf16 v[48:63], v[166:169], v[132:135], v[48:63]
	global_load_lds_dwordx4 v223, s[22:23]
	ds_read_b128 v[132:135], v204 offset:4096
	v_mfma_f32_32x32x16_bf16 v[64:79], v[162:165], v[136:139], v[64:79]
	v_mfma_f32_32x32x16_bf16 v[80:95], v[166:169], v[136:139], v[80:95]
	ds_read_b128 v[136:139], v204 offset:8192
	v_mfma_f32_32x32x16_bf16 v[96:111], v[162:165], v[140:143], v[96:111]
	v_mfma_f32_32x32x16_bf16 v[112:127], v[166:169], v[140:143], v[112:127]
	ds_read_b128 v[140:143], v204 offset:12288
	ds_read_b128 v[162:165], v212
	ds_read_b128 v[166:169], v212 offset:4096
	v_mfma_f32_32x32x16_bf16 v[0:15], v[170:173], v[144:147], v[0:15]
	v_mfma_f32_32x32x16_bf16 v[16:31], v[174:177], v[144:147], v[16:31]
	ds_read_b128 v[144:147], v205
	v_mfma_f32_32x32x16_bf16 v[32:47], v[170:173], v[148:151], v[32:47]
	v_mfma_f32_32x32x16_bf16 v[48:63], v[174:177], v[148:151], v[48:63]
	ds_read_b128 v[148:151], v205 offset:4096
	v_mfma_f32_32x32x16_bf16 v[64:79], v[170:173], v[152:155], v[64:79]
	v_mfma_f32_32x32x16_bf16 v[80:95], v[174:177], v[152:155], v[80:95]
	ds_read_b128 v[152:155], v205 offset:8192
	v_mfma_f32_32x32x16_bf16 v[96:111], v[170:173], v[156:159], v[96:111]
	v_mfma_f32_32x32x16_bf16 v[112:127], v[174:177], v[156:159], v[112:127]
	ds_read_b128 v[156:159], v205 offset:12288
	ds_read_b128 v[170:173], v213
	ds_read_b128 v[174:177], v213 offset:4096
	s_lshr_b32 s53, s28, 5
	s_and_b32 s54, s28, 31
	s_lshr_b32 s55, s53, s34
	s_lshl_b32 s56, s55, s34
	s_sub_u32 s56, s53, s56
	s_lshl_b32 s55, s55, 3
	s_add_u32 s55, s55, s31
	s_lshr_b32 s57, s54, 2
	s_add_u32 s55, s55, s57
	s_lshl_b32 s56, s56, 2
	s_and_b32 s57, s54, 3
	s_add_u32 s56, s56, s57
	s_lshl_b32 s57, s55, 8
	s_add_u32 s57, s57, s58
	s_mul_i32 s57, s57, s36
	s_add_u32 s38, s12, s57
	s_addc_u32 s39, s13, 0
	s_lshl_b32 s57, s56, 9
	s_add_u32 s57, s57, s59
	s_add_u32 s38, s38, s57
	s_addc_u32 s39, s39, 0
	s_cmp_eq_u64 s[4:5], 0
	s_cbranch_scc1 .Lgm_epi_relu
; DI int crow(int r, int hf) { return (r & 3) + 8 * (r >> 2) + 4 * hf; }
;     ...
;     gemm_tile<V>(A + (size_t)m0 * lda, lda, K / 64, nullptr, 0, 0, Wt + (size_t)n0 * ldb, ldb, smem, [&](f32x16(&acc)[2][2], int moff) {
;       const int m0_ = m0 + moff;
;       int l32_ = l32, hf_ = hf; asm volatile("" : "+v"(l32_), "+v"(hf_));
; #pragma unroll
;       for (int i = 0; i < 2; ++i)
; #pragma unroll
;         for (int j = 0; j < 2; ++j)
; #pragma unroll
;           for (int r = 0; r < 16; ++r) {
;             const int row = m0_ + wm * 64 + i * 32 + crow(r, hf_), col = n0 + wn * 64 + j * 32 + l32_;
;             float v = acc[i][j][r];
;             if (mode == 1) { v = fmaxf(v, 0.f); v = v * v; }
;             if (V == 0 || v == 123456.789f) C[(size_t)row * ldc + col] = f2bf(v);
;           }
	v_cvt_pk_bf16_f32 v238, v0, v1
	v_cvt_pk_bf16_f32 v239, v2, v3
	ds_write_b64 v178, v[238:239] offset:32768
	v_cvt_pk_bf16_f32 v240, v4, v5
	v_cvt_pk_bf16_f32 v241, v6, v7
	ds_write_b64 v179, v[240:241] offset:32768
	v_cvt_pk_bf16_f32 v242, v8, v9
	v_cvt_pk_bf16_f32 v243, v10, v11
	ds_write_b64 v180, v[242:243] offset:32768
	v_cvt_pk_bf16_f32 v244, v12, v13
	v_cvt_pk_bf16_f32 v245, v14, v15
	ds_write_b64 v181, v[244:245] offset:32768
	v_cvt_pk_bf16_f32 v238, v16, v17
	v_cvt_pk_bf16_f32 v239, v18, v19
	ds_write_b64 v188, v[238:239] offset:32768
	v_cvt_pk_bf16_f32 v240, v20, v21
	v_cvt_pk_bf16_f32 v241, v22, v23
	ds_write_b64 v189, v[240:241] offset:32768
	v_cvt_pk_bf16_f32 v242, v24, v25
	v_cvt_pk_bf16_f32 v243, v26, v27
	ds_write_b64 v190, v[242:243] offset:32768
	v_cvt_pk_bf16_f32 v244, v28, v29
	v_cvt_pk_bf16_f32 v245, v30, v31
	ds_write_b64 v191, v[244:245] offset:32768
	ds_read_b128 v[0:3], v194 offset:32768
	ds_read_b128 v[4:7], v194 offset:33792
	ds_read_b128 v[8:11], v194 offset:34816
	ds_read_b128 v[12:15], v194 offset:35840
	v_cvt_pk_bf16_f32 v238, v32, v33
	v_cvt_pk_bf16_f32 v239, v34, v35
	ds_write_b64 v178, v[238:239] offset:32768
	v_cvt_pk_bf16_f32 v240, v36, v37
	v_cvt_pk_bf16_f32 v241, v38, v39
	ds_write_b64 v179, v[240:241] offset:32768
	v_cvt_pk_bf16_f32 v242, v40, v41
	v_cvt_pk_bf16_f32 v243, v42, v43
	ds_write_b64 v180, v[242:243] offset:32768
	v_cvt_pk_bf16_f32 v244, v44, v45
	v_cvt_pk_bf16_f32 v245, v46, v47
	ds_write_b64 v181, v[244:245] offset:32768
	v_cvt_pk_bf16_f32 v238, v48, v49
	v_cvt_pk_bf16_f32 v239, v50, v51
	ds_write_b64 v188, v[238:239] offset:32768
	v_cvt_pk_bf16_f32 v240, v52, v53
	v_cvt_pk_bf16_f32 v241, v54, v55
	ds_write_b64 v189, v[240:241] offset:32768
	v_cvt_pk_bf16_f32 v242, v56, v57
	v_cvt_pk_bf16_f32 v243, v58, v59
	ds_write_b64 v190, v[242:243] offset:32768
	v_cvt_pk_bf16_f32 v244, v60, v61
	v_cvt_pk_bf16_f32 v245, v62, v63
	ds_write_b64 v191, v[244:245] offset:32768
	ds_read_b128 v[32:35], v194 offset:32768
	ds_read_b128 v[36:39], v194 offset:33792
	ds_read_b128 v[40:43], v194 offset:34816
	ds_read_b128 v[44:47], v194 offset:35840
	s_waitcnt lgkmcnt(12)
	global_store_dwordx4 v195, v[0:3], s[38:39]
	s_add_u32 s38, s38, s40
	s_addc_u32 s39, s39, 0
	global_store_dwordx4 v195, v[4:7], s[38:39]
	s_add_u32 s38, s38, s40
	s_addc_u32 s39, s39, 0
	global_store_dwordx4 v195, v[8:11], s[38:39]
	s_add_u32 s38, s38, s40
	s_addc_u32 s39, s39, 0
	global_store_dwordx4 v195, v[12:15], s[38:39]
	s_add_u32 s38, s38, s40
	s_addc_u32 s39, s39, 0
	v_cvt_pk_bf16_f32 v238, v64, v65
	v_cvt_pk_bf16_f32 v239, v66, v67
	ds_write_b64 v178, v[238:239] offset:32768
	v_cvt_pk_bf16_f32 v240, v68, v69
	v_cvt_pk_bf16_f32 v241, v70, v71
	ds_write_b64 v179, v[240:241] offset:32768
	v_cvt_pk_bf16_f32 v242, v72, v73
	v_cvt_pk_bf16_f32 v243, v74, v75
	ds_write_b64 v180, v[242:243] offset:32768
	v_cvt_pk_bf16_f32 v244, v76, v77
	v_cvt_pk_bf16_f32 v245, v78, v79
	ds_write_b64 v181, v[244:245] offset:32768
	v_cvt_pk_bf16_f32 v238, v80, v81
	v_cvt_pk_bf16_f32 v239, v82, v83
	ds_write_b64 v188, v[238:239] offset:32768
	v_cvt_pk_bf16_f32 v240, v84, v85
	v_cvt_pk_bf16_f32 v241, v86, v87
	ds_write_b64 v189, v[240:241] offset:32768
	v_cvt_pk_bf16_f32 v242, v88, v89
	v_cvt_pk_bf16_f32 v243, v90, v91
	ds_write_b64 v190, v[242:243] offset:32768
	v_cvt_pk_bf16_f32 v244, v92, v93
	v_cvt_pk_bf16_f32 v245, v94, v95
	ds_write_b64 v191, v[244:245] offset:32768
	ds_read_b128 v[64:67], v194 offset:32768
	ds_read_b128 v[68:71], v194 offset:33792
	ds_read_b128 v[72:75], v194 offset:34816
	ds_read_b128 v[76:79], v194 offset:35840
	s_waitcnt lgkmcnt(12)
	global_store_dwordx4 v195, v[32:35], s[38:39]
	s_add_u32 s38, s38, s40
	s_addc_u32 s39, s39, 0
	global_store_dwordx4 v195, v[36:39], s[38:39]
	s_add_u32 s38, s38, s40
	s_addc_u32 s39, s39, 0
	global_store_dwordx4 v195, v[40:43], s[38:39]
	s_add_u32 s38, s38, s40
	s_addc_u32 s39, s39, 0
	global_store_dwordx4 v195, v[44:47], s[38:39]
	s_add_u32 s38, s38, s40
	s_addc_u32 s39, s39, 0
	v_cvt_pk_bf16_f32 v238, v96, v97
	v_cvt_pk_bf16_f32 v239, v98, v99
	ds_write_b64 v178, v[238:239] offset:32768
	v_cvt_pk_bf16_f32 v240, v100, v101
	v_cvt_pk_bf16_f32 v241, v102, v103
	ds_write_b64 v179, v[240:241] offset:32768
	v_cvt_pk_bf16_f32 v242, v104, v105
	v_cvt_pk_bf16_f32 v243, v106, v107
	ds_write_b64 v180, v[242:243] offset:32768
	v_cvt_pk_bf16_f32 v244, v108, v109
	v_cvt_pk_bf16_f32 v245, v110, v111
	ds_write_b64 v181, v[244:245] offset:32768
	v_cvt_pk_bf16_f32 v238, v112, v113
	v_cvt_pk_bf16_f32 v239, v114, v115
	ds_write_b64 v188, v[238:239] offset:32768
	v_cvt_pk_bf16_f32 v240, v116, v117
	v_cvt_pk_bf16_f32 v241, v118, v119
	ds_write_b64 v189, v[240:241] offset:32768
	v_cvt_pk_bf16_f32 v242, v120, v121
	v_cvt_pk_bf16_f32 v243, v122, v123
	ds_write_b64 v190, v[242:243] offset:32768
	v_cvt_pk_bf16_f32 v244, v124, v125
	v_cvt_pk_bf16_f32 v245, v126, v127
	ds_write_b64 v191, v[244:245] offset:32768
	ds_read_b128 v[96:99], v194 offset:32768
	ds_read_b128 v[100:103], v194 offset:33792
	ds_read_b128 v[104:107], v194 offset:34816
	ds_read_b128 v[108:111], v194 offset:35840
	s_waitcnt lgkmcnt(12)
	global_store_dwordx4 v195, v[64:67], s[38:39]
	s_add_u32 s38, s38, s40
	s_addc_u32 s39, s39, 0
	global_store_dwordx4 v195, v[68:71], s[38:39]
	s_add_u32 s38, s38, s40
	s_addc_u32 s39, s39, 0
	global_store_dwordx4 v195, v[72:75], s[38:39]
	s_add_u32 s38, s38, s40
	s_addc_u32 s39, s39, 0
	global_store_dwordx4 v195, v[76:79], s[38:39]
	s_add_u32 s38, s38, s40
	s_addc_u32 s39, s39, 0
	s_waitcnt lgkmcnt(0)
	global_store_dwordx4 v195, v[96:99], s[38:39]
	s_add_u32 s38, s38, s40
	s_addc_u32 s39, s39, 0
	global_store_dwordx4 v195, v[100:103], s[38:39]
	s_add_u32 s38, s38, s40
	s_addc_u32 s39, s39, 0
	global_store_dwordx4 v195, v[104:107], s[38:39]
	s_add_u32 s38, s38, s40
	s_addc_u32 s39, s39, 0
	global_store_dwordx4 v195, v[108:111], s[38:39]
	s_branch .Lgm_epi_done
